# as v58 but diff_finish2 rows interleaved in groups of four instead of pairs
# speedup vs baseline: 1.0120x; 1.0001x over previous
.LBB0_1174:
	s_or_b64 exec, exec, s[4:5]
	s_waitcnt lgkmcnt(0)
	v_lshlrev_b32_e32 v2, 2, v158
	global_load_dword v249, v2, s[0:1]
	global_load_dword v250, v2, s[0:1] offset:128
	global_load_dword v251, v2, s[0:1] offset:256
	global_load_dword v253, v2, s[0:1] offset:384
	v_add_u32_e32 v10, s19, v148
	s_lshl_b64 s[4:5], s[10:11], 13
	s_add_u32 s4, s86, s4
	s_addc_u32 s5, s87, s5
	s_add_u32 s6, s4, s46
	s_addc_u32 s7, s5, 0
	s_waitcnt vmcnt(0)
	v_mul_f32_e32 v7, v164, v249
	v_mul_f32_e32 v9, v164, v250
	v_mul_f32_e32 v6, v164, v251
	v_mul_f32_e32 v8, v164, v253
	v_lshl_or_b32 v2, v159, 14, v158
	ds_read_b32 v11, v10
	ds_read2st64_b32 v[4:5], v1 offset1:16
	ds_read_b32 v23, v10 offset:4
	ds_read2st64_b32 v[16:17], v1 offset0:1 offset1:17
	ds_read_b32 v35, v10 offset:8
	ds_read2st64_b32 v[28:29], v1 offset0:2 offset1:18
	ds_read_b32 v47, v10 offset:12
	ds_read2st64_b32 v[40:41], v1 offset0:3 offset1:19
	s_waitcnt lgkmcnt(0)
	v_fma_f32 v12, v84, v11, -v4
	v_fma_f32 v13, v100, v11, -v5
	ds_read2st64_b32 v[4:5], v1 offset0:32 offset1:48
	v_mul_f32_e32 v14, v13, v13
	v_fmac_f32_e32 v14, v12, v12
	v_fma_f32 v24, v85, v23, -v16
	v_fma_f32 v25, v101, v23, -v17
	ds_read2st64_b32 v[16:17], v1 offset0:33 offset1:49
	v_mul_f32_e32 v26, v25, v25
	v_fmac_f32_e32 v26, v24, v24
	v_fma_f32 v36, v86, v35, -v28
	v_fma_f32 v37, v102, v35, -v29
	ds_read2st64_b32 v[28:29], v1 offset0:34 offset1:50
	v_mul_f32_e32 v38, v37, v37
	v_fmac_f32_e32 v38, v36, v36
	v_fma_f32 v48, v87, v47, -v40
	v_fma_f32 v49, v103, v47, -v41
	ds_read2st64_b32 v[40:41], v1 offset0:35 offset1:51
	v_mul_f32_e32 v50, v49, v49
	v_fmac_f32_e32 v50, v48, v48
	s_waitcnt lgkmcnt(0)
	v_fma_f32 v15, v116, v11, -v4
	v_fmac_f32_e32 v14, v15, v15
	v_fma_f32 v11, v132, v11, -v5
	v_fmac_f32_e32 v14, v11, v11
	s_nop 1
	v_add_f32_dpp v4, v14, v14 quad_perm:[1,0,3,2] row_mask:0xf bank_mask:0xf
	s_nop 1
	v_add_f32_dpp v4, v4, v4 quad_perm:[2,3,0,1] row_mask:0xf bank_mask:0xf
	s_nop 1
	v_add_f32_dpp v4, v4, v4 row_half_mirror row_mask:0xf bank_mask:0xf
	s_nop 1
	v_add_f32_dpp v4, v4, v4 row_mirror row_mask:0xf bank_mask:0xf
	ds_swizzle_b32 v5, v4 offset:swizzle(SWAP,16)
	v_fma_f32 v27, v117, v23, -v16
	v_fmac_f32_e32 v26, v27, v27
	v_fma_f32 v23, v133, v23, -v17
	v_fmac_f32_e32 v26, v23, v23
	s_nop 1
	v_add_f32_dpp v16, v26, v26 quad_perm:[1,0,3,2] row_mask:0xf bank_mask:0xf
	s_nop 1
	v_add_f32_dpp v16, v16, v16 quad_perm:[2,3,0,1] row_mask:0xf bank_mask:0xf
	s_nop 1
	v_add_f32_dpp v16, v16, v16 row_half_mirror row_mask:0xf bank_mask:0xf
	s_nop 1
	v_add_f32_dpp v16, v16, v16 row_mirror row_mask:0xf bank_mask:0xf
	ds_swizzle_b32 v17, v16 offset:swizzle(SWAP,16)
	v_fma_f32 v39, v118, v35, -v28
	v_fmac_f32_e32 v38, v39, v39
	v_fma_f32 v35, v134, v35, -v29
	v_fmac_f32_e32 v38, v35, v35
	s_nop 1
	v_add_f32_dpp v28, v38, v38 quad_perm:[1,0,3,2] row_mask:0xf bank_mask:0xf
	s_nop 1
	v_add_f32_dpp v28, v28, v28 quad_perm:[2,3,0,1] row_mask:0xf bank_mask:0xf
	s_nop 1
	v_add_f32_dpp v28, v28, v28 row_half_mirror row_mask:0xf bank_mask:0xf
	s_nop 1
	v_add_f32_dpp v28, v28, v28 row_mirror row_mask:0xf bank_mask:0xf
	ds_swizzle_b32 v29, v28 offset:swizzle(SWAP,16)
	v_fma_f32 v51, v119, v47, -v40
	v_fmac_f32_e32 v50, v51, v51
	v_fma_f32 v47, v135, v47, -v41
	v_fmac_f32_e32 v50, v47, v47
	s_nop 1
	v_add_f32_dpp v40, v50, v50 quad_perm:[1,0,3,2] row_mask:0xf bank_mask:0xf
	s_nop 1
	v_add_f32_dpp v40, v40, v40 quad_perm:[2,3,0,1] row_mask:0xf bank_mask:0xf
	s_nop 1
	v_add_f32_dpp v40, v40, v40 row_half_mirror row_mask:0xf bank_mask:0xf
	s_nop 1
	v_add_f32_dpp v40, v40, v40 row_mirror row_mask:0xf bank_mask:0xf
	ds_swizzle_b32 v41, v40 offset:swizzle(SWAP,16)
	s_waitcnt lgkmcnt(0)
	v_add_f32_e32 v4, v4, v5
	v_fmamk_f32 v4, v4, 0x3c000000, v254
	s_nop 0
	s_nop 0
	s_nop 0
	s_nop 1
	s_nop 1
	s_nop 0
	v_rsq_f32_e32 v14, v4
	s_nop 0
	v_mul_f32_e32 v4, v12, v14
	v_mul_f32_e32 v5, v13, v14
	v_mul_f32_e32 v4, v7, v4
	v_mul_f32_e32 v5, v9, v5
	v_cvt_pk_bf16_f32 v12, v4, v5
	v_lshl_add_u64 v[4:5], v[2:3], 1, s[6:7]
	global_store_short v[4:5], v12, off
	v_add_u32_e32 v4, 32, v2
	v_mov_b32_e32 v5, v3
	v_lshl_add_u64 v[4:5], v[4:5], 1, s[6:7]
	global_store_short_d16_hi v[4:5], v12, off
	v_mul_f32_e32 v4, v15, v14
	v_mul_f32_e32 v5, v11, v14
	v_mul_f32_e32 v4, v6, v4
	v_mul_f32_e32 v5, v8, v5
	v_cvt_pk_bf16_f32 v11, v4, v5
	v_add_u32_e32 v4, 64, v2
	v_mov_b32_e32 v5, v3
	v_lshl_add_u64 v[4:5], v[4:5], 1, s[6:7]
	global_store_short v[4:5], v11, off
	v_add_u32_e32 v4, 0x60, v2
	v_mov_b32_e32 v5, v3
	v_lshl_add_u64 v[4:5], v[4:5], 1, s[6:7]
	global_store_short_d16_hi v[4:5], v11, off
	v_add_f32_e32 v16, v16, v17
	v_fmamk_f32 v16, v16, 0x3c000000, v254
	s_nop 0
	s_nop 0
	s_nop 0
	s_nop 1
	s_nop 1
	s_nop 0
	v_rsq_f32_e32 v26, v16
	s_nop 0
	v_mul_f32_e32 v17, v24, v26
	v_mul_f32_e32 v24, v25, v26
	v_mul_f32_e32 v17, v7, v17
	v_mul_f32_e32 v24, v9, v24
	v_add_u32_e32 v16, 0x1000, v2
	v_cvt_pk_bf16_f32 v24, v17, v24
	v_mov_b32_e32 v17, v3
	v_lshl_add_u64 v[16:17], v[16:17], 1, s[6:7]
	global_store_short v[16:17], v24, off
	v_add_u32_e32 v16, 0x1020, v2
	v_mov_b32_e32 v17, v3
	v_lshl_add_u64 v[16:17], v[16:17], 1, s[6:7]
	global_store_short_d16_hi v[16:17], v24, off
	v_mul_f32_e32 v16, v27, v26
	v_mul_f32_e32 v17, v23, v26
	v_mul_f32_e32 v16, v6, v16
	v_mul_f32_e32 v17, v8, v17
	v_cvt_pk_bf16_f32 v23, v16, v17
	v_add_u32_e32 v16, 0x1040, v2
	v_mov_b32_e32 v17, v3
	v_lshl_add_u64 v[16:17], v[16:17], 1, s[6:7]
	global_store_short v[16:17], v23, off
	v_add_u32_e32 v16, 0x1060, v2
	v_mov_b32_e32 v17, v3
	v_lshl_add_u64 v[16:17], v[16:17], 1, s[6:7]
	global_store_short_d16_hi v[16:17], v23, off
	v_add_f32_e32 v28, v28, v29
	v_fmamk_f32 v28, v28, 0x3c000000, v254
	s_nop 0
	s_nop 0
	s_nop 0
	s_nop 1
	s_nop 1
	s_nop 0
	v_rsq_f32_e32 v38, v28
	s_nop 0
	v_mul_f32_e32 v29, v36, v38
	v_mul_f32_e32 v36, v37, v38
	v_mul_f32_e32 v29, v7, v29
	v_mul_f32_e32 v36, v9, v36
	v_add_u32_e32 v28, 0x2000, v2
	v_cvt_pk_bf16_f32 v36, v29, v36
	v_mov_b32_e32 v29, v3
	v_lshl_add_u64 v[28:29], v[28:29], 1, s[6:7]
	global_store_short v[28:29], v36, off
	v_add_u32_e32 v28, 0x2020, v2
	v_mov_b32_e32 v29, v3
	v_lshl_add_u64 v[28:29], v[28:29], 1, s[6:7]
	global_store_short_d16_hi v[28:29], v36, off
	v_mul_f32_e32 v28, v39, v38
	v_mul_f32_e32 v29, v35, v38
	v_mul_f32_e32 v28, v6, v28
	v_mul_f32_e32 v29, v8, v29
	v_cvt_pk_bf16_f32 v35, v28, v29
	v_add_u32_e32 v28, 0x2040, v2
	v_mov_b32_e32 v29, v3
	v_lshl_add_u64 v[28:29], v[28:29], 1, s[6:7]
	global_store_short v[28:29], v35, off
	v_add_u32_e32 v28, 0x2060, v2
	v_mov_b32_e32 v29, v3
	v_lshl_add_u64 v[28:29], v[28:29], 1, s[6:7]
	global_store_short_d16_hi v[28:29], v35, off
	v_add_f32_e32 v40, v40, v41
	v_fmamk_f32 v40, v40, 0x3c000000, v254
	s_nop 0
	s_nop 0
	s_nop 0
	s_nop 1
	s_nop 1
	s_nop 0
	v_rsq_f32_e32 v50, v40
	s_nop 0
	v_mul_f32_e32 v41, v48, v50
	v_mul_f32_e32 v48, v49, v50
	v_mul_f32_e32 v41, v7, v41
	v_mul_f32_e32 v48, v9, v48
	v_add_u32_e32 v40, 0x3000, v2
	v_cvt_pk_bf16_f32 v48, v41, v48
	v_mov_b32_e32 v41, v3
	v_lshl_add_u64 v[40:41], v[40:41], 1, s[6:7]
	global_store_short v[40:41], v48, off
	v_add_u32_e32 v40, 0x3020, v2
	v_mov_b32_e32 v41, v3
	v_lshl_add_u64 v[40:41], v[40:41], 1, s[6:7]
	global_store_short_d16_hi v[40:41], v48, off
	v_mul_f32_e32 v40, v51, v50
	v_mul_f32_e32 v41, v47, v50
	v_mul_f32_e32 v40, v6, v40
	v_mul_f32_e32 v41, v8, v41
	v_cvt_pk_bf16_f32 v47, v40, v41
	v_add_u32_e32 v40, 0x3040, v2
	v_mov_b32_e32 v41, v3
	v_lshl_add_u64 v[40:41], v[40:41], 1, s[6:7]
	global_store_short v[40:41], v47, off
	v_add_u32_e32 v40, 0x3060, v2
	v_mov_b32_e32 v41, v3
	v_lshl_add_u64 v[40:41], v[40:41], 1, s[6:7]
	global_store_short_d16_hi v[40:41], v47, off
	ds_read_b32 v11, v10 offset:32
	ds_read2st64_b32 v[4:5], v1 offset0:4 offset1:20
	ds_read_b32 v23, v10 offset:36
	ds_read2st64_b32 v[16:17], v1 offset0:5 offset1:21
	ds_read_b32 v35, v10 offset:40
	ds_read2st64_b32 v[28:29], v1 offset0:6 offset1:22
	ds_read_b32 v47, v10 offset:44
	ds_read2st64_b32 v[40:41], v1 offset0:7 offset1:23
	s_waitcnt lgkmcnt(0)
	v_fma_f32 v12, v88, v11, -v4
	v_fma_f32 v13, v104, v11, -v5
	ds_read2st64_b32 v[4:5], v1 offset0:36 offset1:52
	v_mul_f32_e32 v14, v13, v13
	v_fmac_f32_e32 v14, v12, v12
	v_fma_f32 v24, v89, v23, -v16
	v_fma_f32 v25, v105, v23, -v17
	ds_read2st64_b32 v[16:17], v1 offset0:37 offset1:53
	v_mul_f32_e32 v26, v25, v25
	v_fmac_f32_e32 v26, v24, v24
	v_fma_f32 v36, v90, v35, -v28
	v_fma_f32 v37, v106, v35, -v29
	ds_read2st64_b32 v[28:29], v1 offset0:38 offset1:54
	v_mul_f32_e32 v38, v37, v37
	v_fmac_f32_e32 v38, v36, v36
	v_fma_f32 v48, v91, v47, -v40
	v_fma_f32 v49, v107, v47, -v41
	ds_read2st64_b32 v[40:41], v1 offset0:39 offset1:55
	v_mul_f32_e32 v50, v49, v49
	v_fmac_f32_e32 v50, v48, v48
	s_waitcnt lgkmcnt(0)
	v_fma_f32 v15, v120, v11, -v4
	v_fmac_f32_e32 v14, v15, v15
	v_fma_f32 v11, v136, v11, -v5
	v_fmac_f32_e32 v14, v11, v11
	s_nop 1
	v_add_f32_dpp v4, v14, v14 quad_perm:[1,0,3,2] row_mask:0xf bank_mask:0xf
	s_nop 1
	v_add_f32_dpp v4, v4, v4 quad_perm:[2,3,0,1] row_mask:0xf bank_mask:0xf
	s_nop 1
	v_add_f32_dpp v4, v4, v4 row_half_mirror row_mask:0xf bank_mask:0xf
	s_nop 1
	v_add_f32_dpp v4, v4, v4 row_mirror row_mask:0xf bank_mask:0xf
	ds_swizzle_b32 v5, v4 offset:swizzle(SWAP,16)
	v_fma_f32 v27, v121, v23, -v16
	v_fmac_f32_e32 v26, v27, v27
	v_fma_f32 v23, v137, v23, -v17
	v_fmac_f32_e32 v26, v23, v23
	s_nop 1
	v_add_f32_dpp v16, v26, v26 quad_perm:[1,0,3,2] row_mask:0xf bank_mask:0xf
	s_nop 1
	v_add_f32_dpp v16, v16, v16 quad_perm:[2,3,0,1] row_mask:0xf bank_mask:0xf
	s_nop 1
	v_add_f32_dpp v16, v16, v16 row_half_mirror row_mask:0xf bank_mask:0xf
	s_nop 1
	v_add_f32_dpp v16, v16, v16 row_mirror row_mask:0xf bank_mask:0xf
	ds_swizzle_b32 v17, v16 offset:swizzle(SWAP,16)
	v_fma_f32 v39, v122, v35, -v28
	v_fmac_f32_e32 v38, v39, v39
	v_fma_f32 v35, v138, v35, -v29
	v_fmac_f32_e32 v38, v35, v35
	s_nop 1
	v_add_f32_dpp v28, v38, v38 quad_perm:[1,0,3,2] row_mask:0xf bank_mask:0xf
	s_nop 1
	v_add_f32_dpp v28, v28, v28 quad_perm:[2,3,0,1] row_mask:0xf bank_mask:0xf
	s_nop 1
	v_add_f32_dpp v28, v28, v28 row_half_mirror row_mask:0xf bank_mask:0xf
	s_nop 1
	v_add_f32_dpp v28, v28, v28 row_mirror row_mask:0xf bank_mask:0xf
	ds_swizzle_b32 v29, v28 offset:swizzle(SWAP,16)
	v_fma_f32 v51, v123, v47, -v40
	v_fmac_f32_e32 v50, v51, v51
	v_fma_f32 v47, v139, v47, -v41
	v_fmac_f32_e32 v50, v47, v47
	s_nop 1
	v_add_f32_dpp v40, v50, v50 quad_perm:[1,0,3,2] row_mask:0xf bank_mask:0xf
	s_nop 1
	v_add_f32_dpp v40, v40, v40 quad_perm:[2,3,0,1] row_mask:0xf bank_mask:0xf
	s_nop 1
	v_add_f32_dpp v40, v40, v40 row_half_mirror row_mask:0xf bank_mask:0xf
	s_nop 1
	v_add_f32_dpp v40, v40, v40 row_mirror row_mask:0xf bank_mask:0xf
	ds_swizzle_b32 v41, v40 offset:swizzle(SWAP,16)
	s_waitcnt lgkmcnt(0)
	v_add_f32_e32 v4, v4, v5
	v_fmamk_f32 v4, v4, 0x3c000000, v254
	s_nop 0
	s_nop 0
	s_nop 0
	s_nop 1
	s_nop 1
	s_nop 0
	v_rsq_f32_e32 v14, v4
	s_nop 0
	v_mul_f32_e32 v5, v12, v14
	v_mul_f32_e32 v12, v13, v14
	v_mul_f32_e32 v5, v7, v5
	v_mul_f32_e32 v12, v9, v12
	v_add_u32_e32 v4, 0x8000, v2
	v_cvt_pk_bf16_f32 v12, v5, v12
	v_mov_b32_e32 v5, v3
	v_lshl_add_u64 v[4:5], v[4:5], 1, s[6:7]
	global_store_short v[4:5], v12, off
	v_add_u32_e32 v4, 0x8020, v2
	v_mov_b32_e32 v5, v3
	v_lshl_add_u64 v[4:5], v[4:5], 1, s[6:7]
	global_store_short_d16_hi v[4:5], v12, off
	v_mul_f32_e32 v4, v15, v14
	v_mul_f32_e32 v5, v11, v14
	v_mul_f32_e32 v4, v6, v4
	v_mul_f32_e32 v5, v8, v5
	v_cvt_pk_bf16_f32 v11, v4, v5
	v_add_u32_e32 v4, 0x8040, v2
	v_mov_b32_e32 v5, v3
	v_lshl_add_u64 v[4:5], v[4:5], 1, s[6:7]
	global_store_short v[4:5], v11, off
	v_add_u32_e32 v4, 0x8060, v2
	v_mov_b32_e32 v5, v3
	v_lshl_add_u64 v[4:5], v[4:5], 1, s[6:7]
	global_store_short_d16_hi v[4:5], v11, off
	v_add_f32_e32 v16, v16, v17
	v_fmamk_f32 v16, v16, 0x3c000000, v254
	s_nop 0
	s_nop 0
	s_nop 0
	s_nop 1
	s_nop 1
	s_nop 0
	v_rsq_f32_e32 v26, v16
	s_nop 0
	v_mul_f32_e32 v17, v24, v26
	v_mul_f32_e32 v24, v25, v26
	v_mul_f32_e32 v17, v7, v17
	v_mul_f32_e32 v24, v9, v24
	v_add_u32_e32 v16, 0x9000, v2
	v_cvt_pk_bf16_f32 v24, v17, v24
	v_mov_b32_e32 v17, v3
	v_lshl_add_u64 v[16:17], v[16:17], 1, s[6:7]
	global_store_short v[16:17], v24, off
	v_add_u32_e32 v16, 0x9020, v2
	v_mov_b32_e32 v17, v3
	v_lshl_add_u64 v[16:17], v[16:17], 1, s[6:7]
	global_store_short_d16_hi v[16:17], v24, off
	v_mul_f32_e32 v16, v27, v26
	v_mul_f32_e32 v17, v23, v26
	v_mul_f32_e32 v16, v6, v16
	v_mul_f32_e32 v17, v8, v17
	v_cvt_pk_bf16_f32 v23, v16, v17
	v_add_u32_e32 v16, 0x9040, v2
	v_mov_b32_e32 v17, v3
	v_lshl_add_u64 v[16:17], v[16:17], 1, s[6:7]
	global_store_short v[16:17], v23, off
	v_add_u32_e32 v16, 0x9060, v2
	v_mov_b32_e32 v17, v3
	v_lshl_add_u64 v[16:17], v[16:17], 1, s[6:7]
	global_store_short_d16_hi v[16:17], v23, off
	v_add_f32_e32 v28, v28, v29
	v_fmamk_f32 v28, v28, 0x3c000000, v254
	s_nop 0
	s_nop 0
	s_nop 0
	s_nop 1
	s_nop 1
	s_nop 0
	v_rsq_f32_e32 v38, v28
	s_nop 0
	v_mul_f32_e32 v29, v36, v38
	v_mul_f32_e32 v36, v37, v38
	v_mul_f32_e32 v29, v7, v29
	v_mul_f32_e32 v36, v9, v36
	v_add_u32_e32 v28, 0xa000, v2
	v_cvt_pk_bf16_f32 v36, v29, v36
	v_mov_b32_e32 v29, v3
	v_lshl_add_u64 v[28:29], v[28:29], 1, s[6:7]
	global_store_short v[28:29], v36, off
	v_add_u32_e32 v28, 0xa020, v2
	v_mov_b32_e32 v29, v3
	v_lshl_add_u64 v[28:29], v[28:29], 1, s[6:7]
	global_store_short_d16_hi v[28:29], v36, off
	v_mul_f32_e32 v28, v39, v38
	v_mul_f32_e32 v29, v35, v38
	v_mul_f32_e32 v28, v6, v28
	v_mul_f32_e32 v29, v8, v29
	v_cvt_pk_bf16_f32 v35, v28, v29
	v_add_u32_e32 v28, 0xa040, v2
	v_mov_b32_e32 v29, v3
	v_lshl_add_u64 v[28:29], v[28:29], 1, s[6:7]
	global_store_short v[28:29], v35, off
	v_add_u32_e32 v28, 0xa060, v2
	v_mov_b32_e32 v29, v3
	v_lshl_add_u64 v[28:29], v[28:29], 1, s[6:7]
	global_store_short_d16_hi v[28:29], v35, off
	v_add_f32_e32 v40, v40, v41
	v_fmamk_f32 v40, v40, 0x3c000000, v254
	s_nop 0
	s_nop 0
	s_nop 0
	s_nop 1
	s_nop 1
	s_nop 0
	v_rsq_f32_e32 v50, v40
	s_nop 0
	v_mul_f32_e32 v41, v48, v50
	v_mul_f32_e32 v48, v49, v50
	v_mul_f32_e32 v41, v7, v41
	v_mul_f32_e32 v48, v9, v48
	v_add_u32_e32 v40, 0xb000, v2
	v_cvt_pk_bf16_f32 v48, v41, v48
	v_mov_b32_e32 v41, v3
	v_lshl_add_u64 v[40:41], v[40:41], 1, s[6:7]
	global_store_short v[40:41], v48, off
	v_add_u32_e32 v40, 0xb020, v2
	v_mov_b32_e32 v41, v3
	v_lshl_add_u64 v[40:41], v[40:41], 1, s[6:7]
	global_store_short_d16_hi v[40:41], v48, off
	v_mul_f32_e32 v40, v51, v50
	v_mul_f32_e32 v41, v47, v50
	v_mul_f32_e32 v40, v6, v40
	v_mul_f32_e32 v41, v8, v41
	v_cvt_pk_bf16_f32 v47, v40, v41
	v_add_u32_e32 v40, 0xb040, v2
	v_mov_b32_e32 v41, v3
	v_lshl_add_u64 v[40:41], v[40:41], 1, s[6:7]
	global_store_short v[40:41], v47, off
	v_add_u32_e32 v40, 0xb060, v2
	v_mov_b32_e32 v41, v3
	v_lshl_add_u64 v[40:41], v[40:41], 1, s[6:7]
	global_store_short_d16_hi v[40:41], v47, off
	ds_read_b32 v11, v10 offset:64
	ds_read2st64_b32 v[4:5], v1 offset0:8 offset1:24
	ds_read_b32 v23, v10 offset:68
	ds_read2st64_b32 v[16:17], v1 offset0:9 offset1:25
	ds_read_b32 v35, v10 offset:72
	ds_read2st64_b32 v[28:29], v1 offset0:10 offset1:26
	ds_read_b32 v47, v10 offset:76
	ds_read2st64_b32 v[40:41], v1 offset0:11 offset1:27
	s_waitcnt lgkmcnt(0)
	v_fma_f32 v12, v92, v11, -v4
	v_fma_f32 v13, v108, v11, -v5
	ds_read2st64_b32 v[4:5], v1 offset0:40 offset1:56
	v_mul_f32_e32 v14, v13, v13
	v_fmac_f32_e32 v14, v12, v12
	v_fma_f32 v24, v93, v23, -v16
	v_fma_f32 v25, v109, v23, -v17
	ds_read2st64_b32 v[16:17], v1 offset0:41 offset1:57
	v_mul_f32_e32 v26, v25, v25
	v_fmac_f32_e32 v26, v24, v24
	v_fma_f32 v36, v94, v35, -v28
	v_fma_f32 v37, v110, v35, -v29
	ds_read2st64_b32 v[28:29], v1 offset0:42 offset1:58
	v_mul_f32_e32 v38, v37, v37
	v_fmac_f32_e32 v38, v36, v36
	v_fma_f32 v48, v95, v47, -v40
	v_fma_f32 v49, v111, v47, -v41
	ds_read2st64_b32 v[40:41], v1 offset0:43 offset1:59
	v_mul_f32_e32 v50, v49, v49
	v_fmac_f32_e32 v50, v48, v48
	s_waitcnt lgkmcnt(0)
	v_fma_f32 v15, v124, v11, -v4
	v_fmac_f32_e32 v14, v15, v15
	v_fma_f32 v11, v140, v11, -v5
	v_fmac_f32_e32 v14, v11, v11
	s_nop 1
	v_add_f32_dpp v4, v14, v14 quad_perm:[1,0,3,2] row_mask:0xf bank_mask:0xf
	s_nop 1
	v_add_f32_dpp v4, v4, v4 quad_perm:[2,3,0,1] row_mask:0xf bank_mask:0xf
	s_nop 1
	v_add_f32_dpp v4, v4, v4 row_half_mirror row_mask:0xf bank_mask:0xf
	s_nop 1
	v_add_f32_dpp v4, v4, v4 row_mirror row_mask:0xf bank_mask:0xf
	ds_swizzle_b32 v5, v4 offset:swizzle(SWAP,16)
	v_fma_f32 v27, v125, v23, -v16
	v_fmac_f32_e32 v26, v27, v27
	v_fma_f32 v23, v141, v23, -v17
	v_fmac_f32_e32 v26, v23, v23
	s_nop 1
	v_add_f32_dpp v16, v26, v26 quad_perm:[1,0,3,2] row_mask:0xf bank_mask:0xf
	s_nop 1
	v_add_f32_dpp v16, v16, v16 quad_perm:[2,3,0,1] row_mask:0xf bank_mask:0xf
	s_nop 1
	v_add_f32_dpp v16, v16, v16 row_half_mirror row_mask:0xf bank_mask:0xf
	s_nop 1
	v_add_f32_dpp v16, v16, v16 row_mirror row_mask:0xf bank_mask:0xf
	ds_swizzle_b32 v17, v16 offset:swizzle(SWAP,16)
	v_fma_f32 v39, v126, v35, -v28
	v_fmac_f32_e32 v38, v39, v39
	v_fma_f32 v35, v142, v35, -v29
	v_fmac_f32_e32 v38, v35, v35
	s_nop 1
	v_add_f32_dpp v28, v38, v38 quad_perm:[1,0,3,2] row_mask:0xf bank_mask:0xf
	s_nop 1
	v_add_f32_dpp v28, v28, v28 quad_perm:[2,3,0,1] row_mask:0xf bank_mask:0xf
	s_nop 1
	v_add_f32_dpp v28, v28, v28 row_half_mirror row_mask:0xf bank_mask:0xf
	s_nop 1
	v_add_f32_dpp v28, v28, v28 row_mirror row_mask:0xf bank_mask:0xf
	ds_swizzle_b32 v29, v28 offset:swizzle(SWAP,16)
	v_fma_f32 v51, v127, v47, -v40
	v_fmac_f32_e32 v50, v51, v51
	v_fma_f32 v47, v143, v47, -v41
	v_fmac_f32_e32 v50, v47, v47
	s_nop 1
	v_add_f32_dpp v40, v50, v50 quad_perm:[1,0,3,2] row_mask:0xf bank_mask:0xf
	s_nop 1
	v_add_f32_dpp v40, v40, v40 quad_perm:[2,3,0,1] row_mask:0xf bank_mask:0xf
	s_nop 1
	v_add_f32_dpp v40, v40, v40 row_half_mirror row_mask:0xf bank_mask:0xf
	s_nop 1
	v_add_f32_dpp v40, v40, v40 row_mirror row_mask:0xf bank_mask:0xf
	ds_swizzle_b32 v41, v40 offset:swizzle(SWAP,16)
	s_waitcnt lgkmcnt(0)
	v_add_f32_e32 v4, v4, v5
	v_fmamk_f32 v4, v4, 0x3c000000, v254
	s_nop 0
	s_nop 0
	s_nop 0
	s_nop 1
	s_nop 1
	s_nop 0
	v_rsq_f32_e32 v14, v4
	s_nop 0
	v_mul_f32_e32 v5, v12, v14
	v_mul_f32_e32 v12, v13, v14
	v_mul_f32_e32 v5, v7, v5
	v_mul_f32_e32 v12, v9, v12
	v_add_u32_e32 v4, 0x10000, v2
	v_cvt_pk_bf16_f32 v12, v5, v12
	v_mov_b32_e32 v5, v3
	v_lshl_add_u64 v[4:5], v[4:5], 1, s[6:7]
	global_store_short v[4:5], v12, off
	v_add_u32_e32 v4, 0x10020, v2
	v_mov_b32_e32 v5, v3
	v_lshl_add_u64 v[4:5], v[4:5], 1, s[6:7]
	global_store_short_d16_hi v[4:5], v12, off
	v_mul_f32_e32 v4, v15, v14
	v_mul_f32_e32 v5, v11, v14
	v_mul_f32_e32 v4, v6, v4
	v_mul_f32_e32 v5, v8, v5
	v_cvt_pk_bf16_f32 v11, v4, v5
	v_add_u32_e32 v4, 0x10040, v2
	v_mov_b32_e32 v5, v3
	v_lshl_add_u64 v[4:5], v[4:5], 1, s[6:7]
	global_store_short v[4:5], v11, off
	v_add_u32_e32 v4, 0x10060, v2
	v_mov_b32_e32 v5, v3
	v_lshl_add_u64 v[4:5], v[4:5], 1, s[6:7]
	global_store_short_d16_hi v[4:5], v11, off
	v_add_f32_e32 v16, v16, v17
	v_fmamk_f32 v16, v16, 0x3c000000, v254
	s_nop 0
	s_nop 0
	s_nop 0
	s_nop 1
	s_nop 1
	s_nop 0
	v_rsq_f32_e32 v26, v16
	s_nop 0
	v_mul_f32_e32 v17, v24, v26
	v_mul_f32_e32 v24, v25, v26
	v_mul_f32_e32 v17, v7, v17
	v_mul_f32_e32 v24, v9, v24
	v_add_u32_e32 v16, 0x11000, v2
	v_cvt_pk_bf16_f32 v24, v17, v24
	v_mov_b32_e32 v17, v3
	v_lshl_add_u64 v[16:17], v[16:17], 1, s[6:7]
	global_store_short v[16:17], v24, off
	v_add_u32_e32 v16, 0x11020, v2
	v_mov_b32_e32 v17, v3
	v_lshl_add_u64 v[16:17], v[16:17], 1, s[6:7]
	global_store_short_d16_hi v[16:17], v24, off
	v_mul_f32_e32 v16, v27, v26
	v_mul_f32_e32 v17, v23, v26
	v_mul_f32_e32 v16, v6, v16
	v_mul_f32_e32 v17, v8, v17
	v_cvt_pk_bf16_f32 v23, v16, v17
	v_add_u32_e32 v16, 0x11040, v2
	v_mov_b32_e32 v17, v3
	v_lshl_add_u64 v[16:17], v[16:17], 1, s[6:7]
	global_store_short v[16:17], v23, off
	v_add_u32_e32 v16, 0x11060, v2
	v_mov_b32_e32 v17, v3
	v_lshl_add_u64 v[16:17], v[16:17], 1, s[6:7]
	global_store_short_d16_hi v[16:17], v23, off
	v_add_f32_e32 v28, v28, v29
	v_fmamk_f32 v28, v28, 0x3c000000, v254
	s_nop 0
	s_nop 0
	s_nop 0
	s_nop 1
	s_nop 1
	s_nop 0
	v_rsq_f32_e32 v38, v28
	s_nop 0
	v_mul_f32_e32 v29, v36, v38
	v_mul_f32_e32 v36, v37, v38
	v_mul_f32_e32 v29, v7, v29
	v_mul_f32_e32 v36, v9, v36
	v_add_u32_e32 v28, 0x12000, v2
	v_cvt_pk_bf16_f32 v36, v29, v36
	v_mov_b32_e32 v29, v3
	v_lshl_add_u64 v[28:29], v[28:29], 1, s[6:7]
	global_store_short v[28:29], v36, off
	v_add_u32_e32 v28, 0x12020, v2
	v_mov_b32_e32 v29, v3
	v_lshl_add_u64 v[28:29], v[28:29], 1, s[6:7]
	global_store_short_d16_hi v[28:29], v36, off
	v_mul_f32_e32 v28, v39, v38
	v_mul_f32_e32 v29, v35, v38
	v_mul_f32_e32 v28, v6, v28
	v_mul_f32_e32 v29, v8, v29
	v_cvt_pk_bf16_f32 v35, v28, v29
	v_add_u32_e32 v28, 0x12040, v2
	v_mov_b32_e32 v29, v3
	v_lshl_add_u64 v[28:29], v[28:29], 1, s[6:7]
	global_store_short v[28:29], v35, off
	v_add_u32_e32 v28, 0x12060, v2
	v_mov_b32_e32 v29, v3
	v_lshl_add_u64 v[28:29], v[28:29], 1, s[6:7]
	global_store_short_d16_hi v[28:29], v35, off
	v_add_f32_e32 v40, v40, v41
	v_fmamk_f32 v40, v40, 0x3c000000, v254
	s_nop 0
	s_nop 0
	s_nop 0
	s_nop 1
	s_nop 1
	s_nop 0
	v_rsq_f32_e32 v50, v40
	s_nop 0
	v_mul_f32_e32 v41, v48, v50
	v_mul_f32_e32 v48, v49, v50
	v_mul_f32_e32 v41, v7, v41
	v_mul_f32_e32 v48, v9, v48
	v_add_u32_e32 v40, 0x13000, v2
	v_cvt_pk_bf16_f32 v48, v41, v48
	v_mov_b32_e32 v41, v3
	v_lshl_add_u64 v[40:41], v[40:41], 1, s[6:7]
	global_store_short v[40:41], v48, off
	v_add_u32_e32 v40, 0x13020, v2
	v_mov_b32_e32 v41, v3
	v_lshl_add_u64 v[40:41], v[40:41], 1, s[6:7]
	global_store_short_d16_hi v[40:41], v48, off
	v_mul_f32_e32 v40, v51, v50
	v_mul_f32_e32 v41, v47, v50
	v_mul_f32_e32 v40, v6, v40
	v_mul_f32_e32 v41, v8, v41
	v_cvt_pk_bf16_f32 v47, v40, v41
	v_add_u32_e32 v40, 0x13040, v2
	v_mov_b32_e32 v41, v3
	v_lshl_add_u64 v[40:41], v[40:41], 1, s[6:7]
	global_store_short v[40:41], v47, off
	v_add_u32_e32 v40, 0x13060, v2
	v_mov_b32_e32 v41, v3
	v_lshl_add_u64 v[40:41], v[40:41], 1, s[6:7]
	global_store_short_d16_hi v[40:41], v47, off
	ds_read_b32 v11, v10 offset:96
	ds_read2st64_b32 v[4:5], v1 offset0:12 offset1:28
	ds_read_b32 v23, v10 offset:100
	ds_read2st64_b32 v[16:17], v1 offset0:13 offset1:29
	ds_read_b32 v35, v10 offset:104
	ds_read2st64_b32 v[28:29], v1 offset0:14 offset1:30
	s_waitcnt lgkmcnt(0)
	v_fma_f32 v12, v96, v11, -v4
	v_fma_f32 v13, v112, v11, -v5
	ds_read2st64_b32 v[4:5], v1 offset0:44 offset1:60
	v_mul_f32_e32 v14, v13, v13
	v_fmac_f32_e32 v14, v12, v12
	v_fma_f32 v24, v97, v23, -v16
	v_fma_f32 v25, v113, v23, -v17
	ds_read2st64_b32 v[16:17], v1 offset0:45 offset1:61
	v_mul_f32_e32 v26, v25, v25
	v_fmac_f32_e32 v26, v24, v24
	v_fma_f32 v36, v98, v35, -v28
	v_fma_f32 v37, v114, v35, -v29
	ds_read2st64_b32 v[28:29], v1 offset0:46 offset1:62
	v_mul_f32_e32 v38, v37, v37
	v_fmac_f32_e32 v38, v36, v36
	s_waitcnt lgkmcnt(0)
	v_fma_f32 v15, v128, v11, -v4
	v_fmac_f32_e32 v14, v15, v15
	v_fma_f32 v11, v144, v11, -v5
	v_fmac_f32_e32 v14, v11, v11
	s_nop 1
	v_add_f32_dpp v4, v14, v14 quad_perm:[1,0,3,2] row_mask:0xf bank_mask:0xf
	s_nop 1
	v_add_f32_dpp v4, v4, v4 quad_perm:[2,3,0,1] row_mask:0xf bank_mask:0xf
	s_nop 1
	v_add_f32_dpp v4, v4, v4 row_half_mirror row_mask:0xf bank_mask:0xf
	s_nop 1
	v_add_f32_dpp v4, v4, v4 row_mirror row_mask:0xf bank_mask:0xf
	ds_swizzle_b32 v5, v4 offset:swizzle(SWAP,16)
	v_fma_f32 v27, v129, v23, -v16
	v_fmac_f32_e32 v26, v27, v27
	v_fma_f32 v23, v145, v23, -v17
	v_fmac_f32_e32 v26, v23, v23
	s_nop 1
	v_add_f32_dpp v16, v26, v26 quad_perm:[1,0,3,2] row_mask:0xf bank_mask:0xf
	s_nop 1
	v_add_f32_dpp v16, v16, v16 quad_perm:[2,3,0,1] row_mask:0xf bank_mask:0xf
	s_nop 1
	v_add_f32_dpp v16, v16, v16 row_half_mirror row_mask:0xf bank_mask:0xf
	s_nop 1
	v_add_f32_dpp v16, v16, v16 row_mirror row_mask:0xf bank_mask:0xf
	ds_swizzle_b32 v17, v16 offset:swizzle(SWAP,16)
	v_fma_f32 v39, v130, v35, -v28
	v_fmac_f32_e32 v38, v39, v39
	v_fma_f32 v35, v146, v35, -v29
	v_fmac_f32_e32 v38, v35, v35
	s_nop 1
	v_add_f32_dpp v28, v38, v38 quad_perm:[1,0,3,2] row_mask:0xf bank_mask:0xf
	s_nop 1
	v_add_f32_dpp v28, v28, v28 quad_perm:[2,3,0,1] row_mask:0xf bank_mask:0xf
	s_nop 1
	v_add_f32_dpp v28, v28, v28 row_half_mirror row_mask:0xf bank_mask:0xf
	s_nop 1
	v_add_f32_dpp v28, v28, v28 row_mirror row_mask:0xf bank_mask:0xf
	ds_swizzle_b32 v29, v28 offset:swizzle(SWAP,16)
	s_waitcnt lgkmcnt(0)
	v_add_f32_e32 v4, v4, v5
	v_fmamk_f32 v4, v4, 0x3c000000, v254
	s_nop 0
	s_nop 0
	s_nop 0
	s_nop 1
	s_nop 1
	s_nop 0
	v_rsq_f32_e32 v14, v4
	s_nop 0
	v_mul_f32_e32 v5, v12, v14
	v_mul_f32_e32 v12, v13, v14
	v_mul_f32_e32 v5, v7, v5
	v_mul_f32_e32 v12, v9, v12
	v_add_u32_e32 v4, 0x18000, v2
	v_cvt_pk_bf16_f32 v12, v5, v12
	v_mov_b32_e32 v5, v3
	v_lshl_add_u64 v[4:5], v[4:5], 1, s[6:7]
	global_store_short v[4:5], v12, off
	v_add_u32_e32 v4, 0x18020, v2
	v_mov_b32_e32 v5, v3
	v_lshl_add_u64 v[4:5], v[4:5], 1, s[6:7]
	global_store_short_d16_hi v[4:5], v12, off
	v_mul_f32_e32 v4, v15, v14
	v_mul_f32_e32 v5, v11, v14
	v_mul_f32_e32 v4, v6, v4
	v_mul_f32_e32 v5, v8, v5
	v_cvt_pk_bf16_f32 v11, v4, v5
	v_add_u32_e32 v4, 0x18040, v2
	v_mov_b32_e32 v5, v3
	v_lshl_add_u64 v[4:5], v[4:5], 1, s[6:7]
	global_store_short v[4:5], v11, off
	v_add_u32_e32 v4, 0x18060, v2
	v_mov_b32_e32 v5, v3
	v_lshl_add_u64 v[4:5], v[4:5], 1, s[6:7]
	global_store_short_d16_hi v[4:5], v11, off
	v_add_f32_e32 v16, v16, v17
	v_fmamk_f32 v16, v16, 0x3c000000, v254
	s_nop 0
	s_nop 0
	s_nop 0
	s_nop 1
	s_nop 1
	s_nop 0
	v_rsq_f32_e32 v26, v16
	s_nop 0
	v_mul_f32_e32 v17, v24, v26
	v_mul_f32_e32 v24, v25, v26
	v_mul_f32_e32 v17, v7, v17
	v_mul_f32_e32 v24, v9, v24
	v_add_u32_e32 v16, 0x19000, v2
	v_cvt_pk_bf16_f32 v24, v17, v24
	v_mov_b32_e32 v17, v3
	v_lshl_add_u64 v[16:17], v[16:17], 1, s[6:7]
	global_store_short v[16:17], v24, off
	v_add_u32_e32 v16, 0x19020, v2
	v_mov_b32_e32 v17, v3
	v_lshl_add_u64 v[16:17], v[16:17], 1, s[6:7]
	global_store_short_d16_hi v[16:17], v24, off
	v_mul_f32_e32 v16, v27, v26
	v_mul_f32_e32 v17, v23, v26
	v_mul_f32_e32 v16, v6, v16
	v_mul_f32_e32 v17, v8, v17
	v_cvt_pk_bf16_f32 v23, v16, v17
	v_add_u32_e32 v16, 0x19040, v2
	v_mov_b32_e32 v17, v3
	v_lshl_add_u64 v[16:17], v[16:17], 1, s[6:7]
	global_store_short v[16:17], v23, off
	v_add_u32_e32 v16, 0x19060, v2
	v_mov_b32_e32 v17, v3
	v_lshl_add_u64 v[16:17], v[16:17], 1, s[6:7]
	global_store_short_d16_hi v[16:17], v23, off
	v_add_f32_e32 v28, v28, v29
	v_fmamk_f32 v28, v28, 0x3c000000, v254
	s_nop 0
	s_nop 0
	s_nop 0
	s_nop 1
	s_nop 1
	s_nop 0
	v_rsq_f32_e32 v38, v28
	s_nop 0
	v_mul_f32_e32 v29, v36, v38
	v_mul_f32_e32 v36, v37, v38
	v_mul_f32_e32 v29, v7, v29
	v_mul_f32_e32 v36, v9, v36
	v_add_u32_e32 v28, 0x1a000, v2
	v_cvt_pk_bf16_f32 v36, v29, v36
	v_mov_b32_e32 v29, v3
	v_lshl_add_u64 v[28:29], v[28:29], 1, s[6:7]
	global_store_short v[28:29], v36, off
	v_add_u32_e32 v28, 0x1a020, v2
	v_mov_b32_e32 v29, v3
	v_lshl_add_u64 v[28:29], v[28:29], 1, s[6:7]
	global_store_short_d16_hi v[28:29], v36, off
	v_mul_f32_e32 v28, v39, v38
	v_mul_f32_e32 v29, v35, v38
	v_mul_f32_e32 v28, v6, v28
	v_mul_f32_e32 v29, v8, v29
	v_cvt_pk_bf16_f32 v35, v28, v29
	v_add_u32_e32 v28, 0x1a040, v2
	v_mov_b32_e32 v29, v3
	v_lshl_add_u64 v[28:29], v[28:29], 1, s[6:7]
	global_store_short v[28:29], v35, off
	v_add_u32_e32 v28, 0x1a060, v2
	v_mov_b32_e32 v29, v3
	v_lshl_add_u64 v[28:29], v[28:29], 1, s[6:7]
	global_store_short_d16_hi v[28:29], v35, off
	ds_read_b32 v10, v10 offset:108
	ds_read2st64_b32 v[4:5], v1 offset0:15 offset1:31
	s_waitcnt lgkmcnt(0)
	v_fma_f32 v11, v99, v10, -v4
	v_fma_f32 v12, v115, v10, -v5
	ds_read2st64_b32 v[4:5], v1 offset0:47 offset1:63
	v_mul_f32_e32 v13, v12, v12
	v_fmac_f32_e32 v13, v11, v11
	s_waitcnt lgkmcnt(0)
	v_fma_f32 v1, v131, v10, -v4
	v_fmac_f32_e32 v13, v1, v1
	v_fma_f32 v10, v147, v10, -v5
	v_fmac_f32_e32 v13, v10, v10
	s_nop 1
	v_add_f32_dpp v4, v13, v13 quad_perm:[1,0,3,2] row_mask:0xf bank_mask:0xf
	s_nop 1
	v_add_f32_dpp v4, v4, v4 quad_perm:[2,3,0,1] row_mask:0xf bank_mask:0xf
	s_nop 1
	v_add_f32_dpp v4, v4, v4 row_half_mirror row_mask:0xf bank_mask:0xf
	s_nop 1
	v_add_f32_dpp v4, v4, v4 row_mirror row_mask:0xf bank_mask:0xf
	ds_swizzle_b32 v5, v4 offset:swizzle(SWAP,16)
	s_waitcnt lgkmcnt(0)
	v_add_f32_e32 v4, v4, v5
	v_fmamk_f32 v4, v4, 0x3c000000, v254
	s_nop 0
	s_nop 0
	s_nop 0
	s_nop 1
	s_nop 1
	s_nop 0
	v_rsq_f32_e32 v13, v4
	s_nop 0
	v_mul_f32_e32 v5, v11, v13
	v_mul_f32_e32 v5, v7, v5
	v_mul_f32_e32 v7, v12, v13
	v_mul_f32_e32 v7, v9, v7
	v_add_u32_e32 v4, 0x1b000, v2
	v_cvt_pk_bf16_f32 v7, v5, v7
	v_mov_b32_e32 v5, v3
	v_lshl_add_u64 v[4:5], v[4:5], 1, s[6:7]
	global_store_short v[4:5], v7, off
	v_add_u32_e32 v4, 0x1b020, v2
	v_mov_b32_e32 v5, v3
	v_lshl_add_u64 v[4:5], v[4:5], 1, s[6:7]
	global_store_short_d16_hi v[4:5], v7, off
	v_mul_f32_e32 v1, v1, v13
	v_mul_f32_e32 v4, v10, v13
	v_mul_f32_e32 v1, v6, v1
	v_mul_f32_e32 v4, v8, v4
	v_cvt_pk_bf16_f32 v1, v1, v4
	v_add_u32_e32 v4, 0x1b040, v2
	v_mov_b32_e32 v5, v3
	v_lshl_add_u64 v[4:5], v[4:5], 1, s[6:7]
	v_add_u32_e32 v2, 0x1b060, v2
	global_store_short v[4:5], v1, off
	v_lshl_add_u64 v[4:5], v[2:3], 1, s[6:7]
	global_store_short_d16_hi v[4:5], v1, off

.LBB0_1239:
	s_or_b64 exec, exec, s[4:5]
	s_waitcnt lgkmcnt(0)
	v_lshlrev_b32_e32 v2, 2, v158
	global_load_dword v249, v2, s[0:1]
	global_load_dword v250, v2, s[0:1] offset:128
	global_load_dword v251, v2, s[0:1] offset:256
	global_load_dword v253, v2, s[0:1] offset:384
	v_add_u32_e32 v10, s43, v148
	s_lshl_b64 s[4:5], s[24:25], 13
	s_add_u32 s4, s86, s4
	s_addc_u32 s5, s87, s5
	s_lshl_b32 s6, s8, 1
	s_add_u32 s6, s4, s6
	s_addc_u32 s7, s5, 0
	s_waitcnt vmcnt(0)
	v_mul_f32_e32 v7, v164, v249
	v_mul_f32_e32 v9, v164, v250
	v_mul_f32_e32 v6, v164, v251
	v_mul_f32_e32 v8, v164, v253
	v_lshl_or_b32 v2, v159, 14, v158
	ds_read_b32 v11, v10
	ds_read2st64_b32 v[4:5], v1 offset1:16
	ds_read_b32 v23, v10 offset:4
	ds_read2st64_b32 v[16:17], v1 offset0:1 offset1:17
	ds_read_b32 v35, v10 offset:8
	ds_read2st64_b32 v[28:29], v1 offset0:2 offset1:18
	ds_read_b32 v47, v10 offset:12
	ds_read2st64_b32 v[40:41], v1 offset0:3 offset1:19
	s_waitcnt lgkmcnt(0)
	v_fma_f32 v12, v68, v11, -v4
	v_fma_f32 v13, v84, v11, -v5
	ds_read2st64_b32 v[4:5], v1 offset0:32 offset1:48
	v_mul_f32_e32 v14, v13, v13
	v_fmac_f32_e32 v14, v12, v12
	v_fma_f32 v24, v69, v23, -v16
	v_fma_f32 v25, v85, v23, -v17
	ds_read2st64_b32 v[16:17], v1 offset0:33 offset1:49
	v_mul_f32_e32 v26, v25, v25
	v_fmac_f32_e32 v26, v24, v24
	v_fma_f32 v36, v70, v35, -v28
	v_fma_f32 v37, v86, v35, -v29
	ds_read2st64_b32 v[28:29], v1 offset0:34 offset1:50
	v_mul_f32_e32 v38, v37, v37
	v_fmac_f32_e32 v38, v36, v36
	v_fma_f32 v48, v71, v47, -v40
	v_fma_f32 v49, v87, v47, -v41
	ds_read2st64_b32 v[40:41], v1 offset0:35 offset1:51
	v_mul_f32_e32 v50, v49, v49
	v_fmac_f32_e32 v50, v48, v48
	s_waitcnt lgkmcnt(0)
	v_fma_f32 v15, v100, v11, -v4
	v_fmac_f32_e32 v14, v15, v15
	v_fma_f32 v11, v116, v11, -v5
	v_fmac_f32_e32 v14, v11, v11
	s_nop 1
	v_add_f32_dpp v4, v14, v14 quad_perm:[1,0,3,2] row_mask:0xf bank_mask:0xf
	s_nop 1
	v_add_f32_dpp v4, v4, v4 quad_perm:[2,3,0,1] row_mask:0xf bank_mask:0xf
	s_nop 1
	v_add_f32_dpp v4, v4, v4 row_half_mirror row_mask:0xf bank_mask:0xf
	s_nop 1
	v_add_f32_dpp v4, v4, v4 row_mirror row_mask:0xf bank_mask:0xf
	ds_swizzle_b32 v5, v4 offset:swizzle(SWAP,16)
	v_fma_f32 v27, v101, v23, -v16
	v_fmac_f32_e32 v26, v27, v27
	v_fma_f32 v23, v117, v23, -v17
	v_fmac_f32_e32 v26, v23, v23
	s_nop 1
	v_add_f32_dpp v16, v26, v26 quad_perm:[1,0,3,2] row_mask:0xf bank_mask:0xf
	s_nop 1
	v_add_f32_dpp v16, v16, v16 quad_perm:[2,3,0,1] row_mask:0xf bank_mask:0xf
	s_nop 1
	v_add_f32_dpp v16, v16, v16 row_half_mirror row_mask:0xf bank_mask:0xf
	s_nop 1
	v_add_f32_dpp v16, v16, v16 row_mirror row_mask:0xf bank_mask:0xf
	ds_swizzle_b32 v17, v16 offset:swizzle(SWAP,16)
	v_fma_f32 v39, v102, v35, -v28
	v_fmac_f32_e32 v38, v39, v39
	v_fma_f32 v35, v118, v35, -v29
	v_fmac_f32_e32 v38, v35, v35
	s_nop 1
	v_add_f32_dpp v28, v38, v38 quad_perm:[1,0,3,2] row_mask:0xf bank_mask:0xf
	s_nop 1
	v_add_f32_dpp v28, v28, v28 quad_perm:[2,3,0,1] row_mask:0xf bank_mask:0xf
	s_nop 1
	v_add_f32_dpp v28, v28, v28 row_half_mirror row_mask:0xf bank_mask:0xf
	s_nop 1
	v_add_f32_dpp v28, v28, v28 row_mirror row_mask:0xf bank_mask:0xf
	ds_swizzle_b32 v29, v28 offset:swizzle(SWAP,16)
	v_fma_f32 v51, v103, v47, -v40
	v_fmac_f32_e32 v50, v51, v51
	v_fma_f32 v47, v119, v47, -v41
	v_fmac_f32_e32 v50, v47, v47
	s_nop 1
	v_add_f32_dpp v40, v50, v50 quad_perm:[1,0,3,2] row_mask:0xf bank_mask:0xf
	s_nop 1
	v_add_f32_dpp v40, v40, v40 quad_perm:[2,3,0,1] row_mask:0xf bank_mask:0xf
	s_nop 1
	v_add_f32_dpp v40, v40, v40 row_half_mirror row_mask:0xf bank_mask:0xf
	s_nop 1
	v_add_f32_dpp v40, v40, v40 row_mirror row_mask:0xf bank_mask:0xf
	ds_swizzle_b32 v41, v40 offset:swizzle(SWAP,16)
	s_waitcnt lgkmcnt(0)
	v_add_f32_e32 v4, v4, v5
	v_fmamk_f32 v4, v4, 0x3c000000, v254
	s_nop 0
	s_nop 0
	s_nop 0
	s_nop 1
	s_nop 1
	s_nop 0
	v_rsq_f32_e32 v14, v4
	s_nop 0
	v_mul_f32_e32 v4, v12, v14
	v_mul_f32_e32 v5, v13, v14
	v_mul_f32_e32 v4, v7, v4
	v_mul_f32_e32 v5, v9, v5
	v_cvt_pk_bf16_f32 v12, v4, v5
	v_lshl_add_u64 v[4:5], v[2:3], 1, s[6:7]
	global_store_short v[4:5], v12, off
	v_add_u32_e32 v4, 32, v2
	v_mov_b32_e32 v5, v3
	v_lshl_add_u64 v[4:5], v[4:5], 1, s[6:7]
	global_store_short_d16_hi v[4:5], v12, off
	v_mul_f32_e32 v4, v15, v14
	v_mul_f32_e32 v5, v11, v14
	v_mul_f32_e32 v4, v6, v4
	v_mul_f32_e32 v5, v8, v5
	v_cvt_pk_bf16_f32 v11, v4, v5
	v_add_u32_e32 v4, 64, v2
	v_mov_b32_e32 v5, v3
	v_lshl_add_u64 v[4:5], v[4:5], 1, s[6:7]
	global_store_short v[4:5], v11, off
	v_add_u32_e32 v4, 0x60, v2
	v_mov_b32_e32 v5, v3
	v_lshl_add_u64 v[4:5], v[4:5], 1, s[6:7]
	global_store_short_d16_hi v[4:5], v11, off
	v_add_f32_e32 v16, v16, v17
	v_fmamk_f32 v16, v16, 0x3c000000, v254
	s_nop 0
	s_nop 0
	s_nop 0
	s_nop 1
	s_nop 1
	s_nop 0
	v_rsq_f32_e32 v26, v16
	s_nop 0
	v_mul_f32_e32 v17, v24, v26
	v_mul_f32_e32 v24, v25, v26
	v_mul_f32_e32 v17, v7, v17
	v_mul_f32_e32 v24, v9, v24
	v_add_u32_e32 v16, 0x1000, v2
	v_cvt_pk_bf16_f32 v24, v17, v24
	v_mov_b32_e32 v17, v3
	v_lshl_add_u64 v[16:17], v[16:17], 1, s[6:7]
	global_store_short v[16:17], v24, off
	v_add_u32_e32 v16, 0x1020, v2
	v_mov_b32_e32 v17, v3
	v_lshl_add_u64 v[16:17], v[16:17], 1, s[6:7]
	global_store_short_d16_hi v[16:17], v24, off
	v_mul_f32_e32 v16, v27, v26
	v_mul_f32_e32 v17, v23, v26
	v_mul_f32_e32 v16, v6, v16
	v_mul_f32_e32 v17, v8, v17
	v_cvt_pk_bf16_f32 v23, v16, v17
	v_add_u32_e32 v16, 0x1040, v2
	v_mov_b32_e32 v17, v3
	v_lshl_add_u64 v[16:17], v[16:17], 1, s[6:7]
	global_store_short v[16:17], v23, off
	v_add_u32_e32 v16, 0x1060, v2
	v_mov_b32_e32 v17, v3
	v_lshl_add_u64 v[16:17], v[16:17], 1, s[6:7]
	global_store_short_d16_hi v[16:17], v23, off
	v_add_f32_e32 v28, v28, v29
	v_fmamk_f32 v28, v28, 0x3c000000, v254
	s_nop 0
	s_nop 0
	s_nop 0
	s_nop 1
	s_nop 1
	s_nop 0
	v_rsq_f32_e32 v38, v28
	s_nop 0
	v_mul_f32_e32 v29, v36, v38
	v_mul_f32_e32 v36, v37, v38
	v_mul_f32_e32 v29, v7, v29
	v_mul_f32_e32 v36, v9, v36
	v_add_u32_e32 v28, 0x2000, v2
	v_cvt_pk_bf16_f32 v36, v29, v36
	v_mov_b32_e32 v29, v3
	v_lshl_add_u64 v[28:29], v[28:29], 1, s[6:7]
	global_store_short v[28:29], v36, off
	v_add_u32_e32 v28, 0x2020, v2
	v_mov_b32_e32 v29, v3
	v_lshl_add_u64 v[28:29], v[28:29], 1, s[6:7]
	global_store_short_d16_hi v[28:29], v36, off
	v_mul_f32_e32 v28, v39, v38
	v_mul_f32_e32 v29, v35, v38
	v_mul_f32_e32 v28, v6, v28
	v_mul_f32_e32 v29, v8, v29
	v_cvt_pk_bf16_f32 v35, v28, v29
	v_add_u32_e32 v28, 0x2040, v2
	v_mov_b32_e32 v29, v3
	v_lshl_add_u64 v[28:29], v[28:29], 1, s[6:7]
	global_store_short v[28:29], v35, off
	v_add_u32_e32 v28, 0x2060, v2
	v_mov_b32_e32 v29, v3
	v_lshl_add_u64 v[28:29], v[28:29], 1, s[6:7]
	global_store_short_d16_hi v[28:29], v35, off
	v_add_f32_e32 v40, v40, v41
	v_fmamk_f32 v40, v40, 0x3c000000, v254
	s_nop 0
	s_nop 0
	s_nop 0
	s_nop 1
	s_nop 1
	s_nop 0
	v_rsq_f32_e32 v50, v40
	s_nop 0
	v_mul_f32_e32 v41, v48, v50
	v_mul_f32_e32 v48, v49, v50
	v_mul_f32_e32 v41, v7, v41
	v_mul_f32_e32 v48, v9, v48
	v_add_u32_e32 v40, 0x3000, v2
	v_cvt_pk_bf16_f32 v48, v41, v48
	v_mov_b32_e32 v41, v3
	v_lshl_add_u64 v[40:41], v[40:41], 1, s[6:7]
	global_store_short v[40:41], v48, off
	v_add_u32_e32 v40, 0x3020, v2
	v_mov_b32_e32 v41, v3
	v_lshl_add_u64 v[40:41], v[40:41], 1, s[6:7]
	global_store_short_d16_hi v[40:41], v48, off
	v_mul_f32_e32 v40, v51, v50
	v_mul_f32_e32 v41, v47, v50
	v_mul_f32_e32 v40, v6, v40
	v_mul_f32_e32 v41, v8, v41
	v_cvt_pk_bf16_f32 v47, v40, v41
	v_add_u32_e32 v40, 0x3040, v2
	v_mov_b32_e32 v41, v3
	v_lshl_add_u64 v[40:41], v[40:41], 1, s[6:7]
	global_store_short v[40:41], v47, off
	v_add_u32_e32 v40, 0x3060, v2
	v_mov_b32_e32 v41, v3
	v_lshl_add_u64 v[40:41], v[40:41], 1, s[6:7]
	global_store_short_d16_hi v[40:41], v47, off
	ds_read_b32 v11, v10 offset:32
	ds_read2st64_b32 v[4:5], v1 offset0:4 offset1:20
	ds_read_b32 v23, v10 offset:36
	ds_read2st64_b32 v[16:17], v1 offset0:5 offset1:21
	ds_read_b32 v35, v10 offset:40
	ds_read2st64_b32 v[28:29], v1 offset0:6 offset1:22
	ds_read_b32 v47, v10 offset:44
	ds_read2st64_b32 v[40:41], v1 offset0:7 offset1:23
	s_waitcnt lgkmcnt(0)
	v_fma_f32 v12, v72, v11, -v4
	v_fma_f32 v13, v88, v11, -v5
	ds_read2st64_b32 v[4:5], v1 offset0:36 offset1:52
	v_mul_f32_e32 v14, v13, v13
	v_fmac_f32_e32 v14, v12, v12
	v_fma_f32 v24, v73, v23, -v16
	v_fma_f32 v25, v89, v23, -v17
	ds_read2st64_b32 v[16:17], v1 offset0:37 offset1:53
	v_mul_f32_e32 v26, v25, v25
	v_fmac_f32_e32 v26, v24, v24
	v_fma_f32 v36, v74, v35, -v28
	v_fma_f32 v37, v90, v35, -v29
	ds_read2st64_b32 v[28:29], v1 offset0:38 offset1:54
	v_mul_f32_e32 v38, v37, v37
	v_fmac_f32_e32 v38, v36, v36
	v_fma_f32 v48, v75, v47, -v40
	v_fma_f32 v49, v91, v47, -v41
	ds_read2st64_b32 v[40:41], v1 offset0:39 offset1:55
	v_mul_f32_e32 v50, v49, v49
	v_fmac_f32_e32 v50, v48, v48
	s_waitcnt lgkmcnt(0)
	v_fma_f32 v15, v104, v11, -v4
	v_fmac_f32_e32 v14, v15, v15
	v_fma_f32 v11, v120, v11, -v5
	v_fmac_f32_e32 v14, v11, v11
	s_nop 1
	v_add_f32_dpp v4, v14, v14 quad_perm:[1,0,3,2] row_mask:0xf bank_mask:0xf
	s_nop 1
	v_add_f32_dpp v4, v4, v4 quad_perm:[2,3,0,1] row_mask:0xf bank_mask:0xf
	s_nop 1
	v_add_f32_dpp v4, v4, v4 row_half_mirror row_mask:0xf bank_mask:0xf
	s_nop 1
	v_add_f32_dpp v4, v4, v4 row_mirror row_mask:0xf bank_mask:0xf
	ds_swizzle_b32 v5, v4 offset:swizzle(SWAP,16)
	v_fma_f32 v27, v105, v23, -v16
	v_fmac_f32_e32 v26, v27, v27
	v_fma_f32 v23, v121, v23, -v17
	v_fmac_f32_e32 v26, v23, v23
	s_nop 1
	v_add_f32_dpp v16, v26, v26 quad_perm:[1,0,3,2] row_mask:0xf bank_mask:0xf
	s_nop 1
	v_add_f32_dpp v16, v16, v16 quad_perm:[2,3,0,1] row_mask:0xf bank_mask:0xf
	s_nop 1
	v_add_f32_dpp v16, v16, v16 row_half_mirror row_mask:0xf bank_mask:0xf
	s_nop 1
	v_add_f32_dpp v16, v16, v16 row_mirror row_mask:0xf bank_mask:0xf
	ds_swizzle_b32 v17, v16 offset:swizzle(SWAP,16)
	v_fma_f32 v39, v106, v35, -v28
	v_fmac_f32_e32 v38, v39, v39
	v_fma_f32 v35, v122, v35, -v29
	v_fmac_f32_e32 v38, v35, v35
	s_nop 1
	v_add_f32_dpp v28, v38, v38 quad_perm:[1,0,3,2] row_mask:0xf bank_mask:0xf
	s_nop 1
	v_add_f32_dpp v28, v28, v28 quad_perm:[2,3,0,1] row_mask:0xf bank_mask:0xf
	s_nop 1
	v_add_f32_dpp v28, v28, v28 row_half_mirror row_mask:0xf bank_mask:0xf
	s_nop 1
	v_add_f32_dpp v28, v28, v28 row_mirror row_mask:0xf bank_mask:0xf
	ds_swizzle_b32 v29, v28 offset:swizzle(SWAP,16)
	v_fma_f32 v51, v107, v47, -v40
	v_fmac_f32_e32 v50, v51, v51
	v_fma_f32 v47, v123, v47, -v41
	v_fmac_f32_e32 v50, v47, v47
	s_nop 1
	v_add_f32_dpp v40, v50, v50 quad_perm:[1,0,3,2] row_mask:0xf bank_mask:0xf
	s_nop 1
	v_add_f32_dpp v40, v40, v40 quad_perm:[2,3,0,1] row_mask:0xf bank_mask:0xf
	s_nop 1
	v_add_f32_dpp v40, v40, v40 row_half_mirror row_mask:0xf bank_mask:0xf
	s_nop 1
	v_add_f32_dpp v40, v40, v40 row_mirror row_mask:0xf bank_mask:0xf
	ds_swizzle_b32 v41, v40 offset:swizzle(SWAP,16)
	s_waitcnt lgkmcnt(0)
	v_add_f32_e32 v4, v4, v5
	v_fmamk_f32 v4, v4, 0x3c000000, v254
	s_nop 0
	s_nop 0
	s_nop 0
	s_nop 1
	s_nop 1
	s_nop 0
	v_rsq_f32_e32 v14, v4
	s_nop 0
	v_mul_f32_e32 v5, v12, v14
	v_mul_f32_e32 v12, v13, v14
	v_mul_f32_e32 v5, v7, v5
	v_mul_f32_e32 v12, v9, v12
	v_add_u32_e32 v4, 0x8000, v2
	v_cvt_pk_bf16_f32 v12, v5, v12
	v_mov_b32_e32 v5, v3
	v_lshl_add_u64 v[4:5], v[4:5], 1, s[6:7]
	global_store_short v[4:5], v12, off
	v_add_u32_e32 v4, 0x8020, v2
	v_mov_b32_e32 v5, v3
	v_lshl_add_u64 v[4:5], v[4:5], 1, s[6:7]
	global_store_short_d16_hi v[4:5], v12, off
	v_mul_f32_e32 v4, v15, v14
	v_mul_f32_e32 v5, v11, v14
	v_mul_f32_e32 v4, v6, v4
	v_mul_f32_e32 v5, v8, v5
	v_cvt_pk_bf16_f32 v11, v4, v5
	v_add_u32_e32 v4, 0x8040, v2
	v_mov_b32_e32 v5, v3
	v_lshl_add_u64 v[4:5], v[4:5], 1, s[6:7]
	global_store_short v[4:5], v11, off
	v_add_u32_e32 v4, 0x8060, v2
	v_mov_b32_e32 v5, v3
	v_lshl_add_u64 v[4:5], v[4:5], 1, s[6:7]
	global_store_short_d16_hi v[4:5], v11, off
	v_add_f32_e32 v16, v16, v17
	v_fmamk_f32 v16, v16, 0x3c000000, v254
	s_nop 0
	s_nop 0
	s_nop 0
	s_nop 1
	s_nop 1
	s_nop 0
	v_rsq_f32_e32 v26, v16
	s_nop 0
	v_mul_f32_e32 v17, v24, v26
	v_mul_f32_e32 v24, v25, v26
	v_mul_f32_e32 v17, v7, v17
	v_mul_f32_e32 v24, v9, v24
	v_add_u32_e32 v16, 0x9000, v2
	v_cvt_pk_bf16_f32 v24, v17, v24
	v_mov_b32_e32 v17, v3
	v_lshl_add_u64 v[16:17], v[16:17], 1, s[6:7]
	global_store_short v[16:17], v24, off
	v_add_u32_e32 v16, 0x9020, v2
	v_mov_b32_e32 v17, v3
	v_lshl_add_u64 v[16:17], v[16:17], 1, s[6:7]
	global_store_short_d16_hi v[16:17], v24, off
	v_mul_f32_e32 v16, v27, v26
	v_mul_f32_e32 v17, v23, v26
	v_mul_f32_e32 v16, v6, v16
	v_mul_f32_e32 v17, v8, v17
	v_cvt_pk_bf16_f32 v23, v16, v17
	v_add_u32_e32 v16, 0x9040, v2
	v_mov_b32_e32 v17, v3
	v_lshl_add_u64 v[16:17], v[16:17], 1, s[6:7]
	global_store_short v[16:17], v23, off
	v_add_u32_e32 v16, 0x9060, v2
	v_mov_b32_e32 v17, v3
	v_lshl_add_u64 v[16:17], v[16:17], 1, s[6:7]
	global_store_short_d16_hi v[16:17], v23, off
	v_add_f32_e32 v28, v28, v29
	v_fmamk_f32 v28, v28, 0x3c000000, v254
	s_nop 0
	s_nop 0
	s_nop 0
	s_nop 1
	s_nop 1
	s_nop 0
	v_rsq_f32_e32 v38, v28
	s_nop 0
	v_mul_f32_e32 v29, v36, v38
	v_mul_f32_e32 v36, v37, v38
	v_mul_f32_e32 v29, v7, v29
	v_mul_f32_e32 v36, v9, v36
	v_add_u32_e32 v28, 0xa000, v2
	v_cvt_pk_bf16_f32 v36, v29, v36
	v_mov_b32_e32 v29, v3
	v_lshl_add_u64 v[28:29], v[28:29], 1, s[6:7]
	global_store_short v[28:29], v36, off
	v_add_u32_e32 v28, 0xa020, v2
	v_mov_b32_e32 v29, v3
	v_lshl_add_u64 v[28:29], v[28:29], 1, s[6:7]
	global_store_short_d16_hi v[28:29], v36, off
	v_mul_f32_e32 v28, v39, v38
	v_mul_f32_e32 v29, v35, v38
	v_mul_f32_e32 v28, v6, v28
	v_mul_f32_e32 v29, v8, v29
	v_cvt_pk_bf16_f32 v35, v28, v29
	v_add_u32_e32 v28, 0xa040, v2
	v_mov_b32_e32 v29, v3
	v_lshl_add_u64 v[28:29], v[28:29], 1, s[6:7]
	global_store_short v[28:29], v35, off
	v_add_u32_e32 v28, 0xa060, v2
	v_mov_b32_e32 v29, v3
	v_lshl_add_u64 v[28:29], v[28:29], 1, s[6:7]
	global_store_short_d16_hi v[28:29], v35, off
	v_add_f32_e32 v40, v40, v41
	v_fmamk_f32 v40, v40, 0x3c000000, v254
	s_nop 0
	s_nop 0
	s_nop 0
	s_nop 1
	s_nop 1
	s_nop 0
	v_rsq_f32_e32 v50, v40
	s_nop 0
	v_mul_f32_e32 v41, v48, v50
	v_mul_f32_e32 v48, v49, v50
	v_mul_f32_e32 v41, v7, v41
	v_mul_f32_e32 v48, v9, v48
	v_add_u32_e32 v40, 0xb000, v2
	v_cvt_pk_bf16_f32 v48, v41, v48
	v_mov_b32_e32 v41, v3
	v_lshl_add_u64 v[40:41], v[40:41], 1, s[6:7]
	global_store_short v[40:41], v48, off
	v_add_u32_e32 v40, 0xb020, v2
	v_mov_b32_e32 v41, v3
	v_lshl_add_u64 v[40:41], v[40:41], 1, s[6:7]
	global_store_short_d16_hi v[40:41], v48, off
	v_mul_f32_e32 v40, v51, v50
	v_mul_f32_e32 v41, v47, v50
	v_mul_f32_e32 v40, v6, v40
	v_mul_f32_e32 v41, v8, v41
	v_cvt_pk_bf16_f32 v47, v40, v41
	v_add_u32_e32 v40, 0xb040, v2
	v_mov_b32_e32 v41, v3
	v_lshl_add_u64 v[40:41], v[40:41], 1, s[6:7]
	global_store_short v[40:41], v47, off
	v_add_u32_e32 v40, 0xb060, v2
	v_mov_b32_e32 v41, v3
	v_lshl_add_u64 v[40:41], v[40:41], 1, s[6:7]
	global_store_short_d16_hi v[40:41], v47, off
	ds_read_b32 v11, v10 offset:64
	ds_read2st64_b32 v[4:5], v1 offset0:8 offset1:24
	ds_read_b32 v23, v10 offset:68
	ds_read2st64_b32 v[16:17], v1 offset0:9 offset1:25
	ds_read_b32 v35, v10 offset:72
	ds_read2st64_b32 v[28:29], v1 offset0:10 offset1:26
	ds_read_b32 v47, v10 offset:76
	ds_read2st64_b32 v[40:41], v1 offset0:11 offset1:27
	s_waitcnt lgkmcnt(0)
	v_fma_f32 v12, v76, v11, -v4
	v_fma_f32 v13, v92, v11, -v5
	ds_read2st64_b32 v[4:5], v1 offset0:40 offset1:56
	v_mul_f32_e32 v14, v13, v13
	v_fmac_f32_e32 v14, v12, v12
	v_fma_f32 v24, v77, v23, -v16
	v_fma_f32 v25, v93, v23, -v17
	ds_read2st64_b32 v[16:17], v1 offset0:41 offset1:57
	v_mul_f32_e32 v26, v25, v25
	v_fmac_f32_e32 v26, v24, v24
	v_fma_f32 v36, v78, v35, -v28
	v_fma_f32 v37, v94, v35, -v29
	ds_read2st64_b32 v[28:29], v1 offset0:42 offset1:58
	v_mul_f32_e32 v38, v37, v37
	v_fmac_f32_e32 v38, v36, v36
	v_fma_f32 v48, v79, v47, -v40
	v_fma_f32 v49, v95, v47, -v41
	ds_read2st64_b32 v[40:41], v1 offset0:43 offset1:59
	v_mul_f32_e32 v50, v49, v49
	v_fmac_f32_e32 v50, v48, v48
	s_waitcnt lgkmcnt(0)
	v_fma_f32 v15, v108, v11, -v4
	v_fmac_f32_e32 v14, v15, v15
	v_fma_f32 v11, v124, v11, -v5
	v_fmac_f32_e32 v14, v11, v11
	s_nop 1
	v_add_f32_dpp v4, v14, v14 quad_perm:[1,0,3,2] row_mask:0xf bank_mask:0xf
	s_nop 1
	v_add_f32_dpp v4, v4, v4 quad_perm:[2,3,0,1] row_mask:0xf bank_mask:0xf
	s_nop 1
	v_add_f32_dpp v4, v4, v4 row_half_mirror row_mask:0xf bank_mask:0xf
	s_nop 1
	v_add_f32_dpp v4, v4, v4 row_mirror row_mask:0xf bank_mask:0xf
	ds_swizzle_b32 v5, v4 offset:swizzle(SWAP,16)
	v_fma_f32 v27, v109, v23, -v16
	v_fmac_f32_e32 v26, v27, v27
	v_fma_f32 v23, v125, v23, -v17
	v_fmac_f32_e32 v26, v23, v23
	s_nop 1
	v_add_f32_dpp v16, v26, v26 quad_perm:[1,0,3,2] row_mask:0xf bank_mask:0xf
	s_nop 1
	v_add_f32_dpp v16, v16, v16 quad_perm:[2,3,0,1] row_mask:0xf bank_mask:0xf
	s_nop 1
	v_add_f32_dpp v16, v16, v16 row_half_mirror row_mask:0xf bank_mask:0xf
	s_nop 1
	v_add_f32_dpp v16, v16, v16 row_mirror row_mask:0xf bank_mask:0xf
	ds_swizzle_b32 v17, v16 offset:swizzle(SWAP,16)
	v_fma_f32 v39, v110, v35, -v28
	v_fmac_f32_e32 v38, v39, v39
	v_fma_f32 v35, v126, v35, -v29
	v_fmac_f32_e32 v38, v35, v35
	s_nop 1
	v_add_f32_dpp v28, v38, v38 quad_perm:[1,0,3,2] row_mask:0xf bank_mask:0xf
	s_nop 1
	v_add_f32_dpp v28, v28, v28 quad_perm:[2,3,0,1] row_mask:0xf bank_mask:0xf
	s_nop 1
	v_add_f32_dpp v28, v28, v28 row_half_mirror row_mask:0xf bank_mask:0xf
	s_nop 1
	v_add_f32_dpp v28, v28, v28 row_mirror row_mask:0xf bank_mask:0xf
	ds_swizzle_b32 v29, v28 offset:swizzle(SWAP,16)
	v_fma_f32 v51, v111, v47, -v40
	v_fmac_f32_e32 v50, v51, v51
	v_fma_f32 v47, v127, v47, -v41
	v_fmac_f32_e32 v50, v47, v47
	s_nop 1
	v_add_f32_dpp v40, v50, v50 quad_perm:[1,0,3,2] row_mask:0xf bank_mask:0xf
	s_nop 1
	v_add_f32_dpp v40, v40, v40 quad_perm:[2,3,0,1] row_mask:0xf bank_mask:0xf
	s_nop 1
	v_add_f32_dpp v40, v40, v40 row_half_mirror row_mask:0xf bank_mask:0xf
	s_nop 1
	v_add_f32_dpp v40, v40, v40 row_mirror row_mask:0xf bank_mask:0xf
	ds_swizzle_b32 v41, v40 offset:swizzle(SWAP,16)
	s_waitcnt lgkmcnt(0)
	v_add_f32_e32 v4, v4, v5
	v_fmamk_f32 v4, v4, 0x3c000000, v254
	s_nop 0
	s_nop 0
	s_nop 0
	s_nop 1
	s_nop 1
	s_nop 0
	v_rsq_f32_e32 v14, v4
	s_nop 0
	v_mul_f32_e32 v5, v12, v14
	v_mul_f32_e32 v12, v13, v14
	v_mul_f32_e32 v5, v7, v5
	v_mul_f32_e32 v12, v9, v12
	v_add_u32_e32 v4, 0x10000, v2
	v_cvt_pk_bf16_f32 v12, v5, v12
	v_mov_b32_e32 v5, v3
	v_lshl_add_u64 v[4:5], v[4:5], 1, s[6:7]
	global_store_short v[4:5], v12, off
	v_add_u32_e32 v4, 0x10020, v2
	v_mov_b32_e32 v5, v3
	v_lshl_add_u64 v[4:5], v[4:5], 1, s[6:7]
	global_store_short_d16_hi v[4:5], v12, off
	v_mul_f32_e32 v4, v15, v14
	v_mul_f32_e32 v5, v11, v14
	v_mul_f32_e32 v4, v6, v4
	v_mul_f32_e32 v5, v8, v5
	v_cvt_pk_bf16_f32 v11, v4, v5
	v_add_u32_e32 v4, 0x10040, v2
	v_mov_b32_e32 v5, v3
	v_lshl_add_u64 v[4:5], v[4:5], 1, s[6:7]
	global_store_short v[4:5], v11, off
	v_add_u32_e32 v4, 0x10060, v2
	v_mov_b32_e32 v5, v3
	v_lshl_add_u64 v[4:5], v[4:5], 1, s[6:7]
	global_store_short_d16_hi v[4:5], v11, off
	v_add_f32_e32 v16, v16, v17
	v_fmamk_f32 v16, v16, 0x3c000000, v254
	s_nop 0
	s_nop 0
	s_nop 0
	s_nop 1
	s_nop 1
	s_nop 0
	v_rsq_f32_e32 v26, v16
	s_nop 0
	v_mul_f32_e32 v17, v24, v26
	v_mul_f32_e32 v24, v25, v26
	v_mul_f32_e32 v17, v7, v17
	v_mul_f32_e32 v24, v9, v24
	v_add_u32_e32 v16, 0x11000, v2
	v_cvt_pk_bf16_f32 v24, v17, v24
	v_mov_b32_e32 v17, v3
	v_lshl_add_u64 v[16:17], v[16:17], 1, s[6:7]
	global_store_short v[16:17], v24, off
	v_add_u32_e32 v16, 0x11020, v2
	v_mov_b32_e32 v17, v3
	v_lshl_add_u64 v[16:17], v[16:17], 1, s[6:7]
	global_store_short_d16_hi v[16:17], v24, off
	v_mul_f32_e32 v16, v27, v26
	v_mul_f32_e32 v17, v23, v26
	v_mul_f32_e32 v16, v6, v16
	v_mul_f32_e32 v17, v8, v17
	v_cvt_pk_bf16_f32 v23, v16, v17
	v_add_u32_e32 v16, 0x11040, v2
	v_mov_b32_e32 v17, v3
	v_lshl_add_u64 v[16:17], v[16:17], 1, s[6:7]
	global_store_short v[16:17], v23, off
	v_add_u32_e32 v16, 0x11060, v2
	v_mov_b32_e32 v17, v3
	v_lshl_add_u64 v[16:17], v[16:17], 1, s[6:7]
	global_store_short_d16_hi v[16:17], v23, off
	v_add_f32_e32 v28, v28, v29
	v_fmamk_f32 v28, v28, 0x3c000000, v254
	s_nop 0
	s_nop 0
	s_nop 0
	s_nop 1
	s_nop 1
	s_nop 0
	v_rsq_f32_e32 v38, v28
	s_nop 0
	v_mul_f32_e32 v29, v36, v38
	v_mul_f32_e32 v36, v37, v38
	v_mul_f32_e32 v29, v7, v29
	v_mul_f32_e32 v36, v9, v36
	v_add_u32_e32 v28, 0x12000, v2
	v_cvt_pk_bf16_f32 v36, v29, v36
	v_mov_b32_e32 v29, v3
	v_lshl_add_u64 v[28:29], v[28:29], 1, s[6:7]
	global_store_short v[28:29], v36, off
	v_add_u32_e32 v28, 0x12020, v2
	v_mov_b32_e32 v29, v3
	v_lshl_add_u64 v[28:29], v[28:29], 1, s[6:7]
	global_store_short_d16_hi v[28:29], v36, off
	v_mul_f32_e32 v28, v39, v38
	v_mul_f32_e32 v29, v35, v38
	v_mul_f32_e32 v28, v6, v28
	v_mul_f32_e32 v29, v8, v29
	v_cvt_pk_bf16_f32 v35, v28, v29
	v_add_u32_e32 v28, 0x12040, v2
	v_mov_b32_e32 v29, v3
	v_lshl_add_u64 v[28:29], v[28:29], 1, s[6:7]
	global_store_short v[28:29], v35, off
	v_add_u32_e32 v28, 0x12060, v2
	v_mov_b32_e32 v29, v3
	v_lshl_add_u64 v[28:29], v[28:29], 1, s[6:7]
	global_store_short_d16_hi v[28:29], v35, off
	v_add_f32_e32 v40, v40, v41
	v_fmamk_f32 v40, v40, 0x3c000000, v254
	s_nop 0
	s_nop 0
	s_nop 0
	s_nop 1
	s_nop 1
	s_nop 0
	v_rsq_f32_e32 v50, v40
	s_nop 0
	v_mul_f32_e32 v41, v48, v50
	v_mul_f32_e32 v48, v49, v50
	v_mul_f32_e32 v41, v7, v41
	v_mul_f32_e32 v48, v9, v48
	v_add_u32_e32 v40, 0x13000, v2
	v_cvt_pk_bf16_f32 v48, v41, v48
	v_mov_b32_e32 v41, v3
	v_lshl_add_u64 v[40:41], v[40:41], 1, s[6:7]
	global_store_short v[40:41], v48, off
	v_add_u32_e32 v40, 0x13020, v2
	v_mov_b32_e32 v41, v3
	v_lshl_add_u64 v[40:41], v[40:41], 1, s[6:7]
	global_store_short_d16_hi v[40:41], v48, off
	v_mul_f32_e32 v40, v51, v50
	v_mul_f32_e32 v41, v47, v50
	v_mul_f32_e32 v40, v6, v40
	v_mul_f32_e32 v41, v8, v41
	v_cvt_pk_bf16_f32 v47, v40, v41
	v_add_u32_e32 v40, 0x13040, v2
	v_mov_b32_e32 v41, v3
	v_lshl_add_u64 v[40:41], v[40:41], 1, s[6:7]
	global_store_short v[40:41], v47, off
	v_add_u32_e32 v40, 0x13060, v2
	v_mov_b32_e32 v41, v3
	v_lshl_add_u64 v[40:41], v[40:41], 1, s[6:7]
	global_store_short_d16_hi v[40:41], v47, off
	ds_read_b32 v11, v10 offset:96
	ds_read2st64_b32 v[4:5], v1 offset0:12 offset1:28
	ds_read_b32 v23, v10 offset:100
	ds_read2st64_b32 v[16:17], v1 offset0:13 offset1:29
	ds_read_b32 v35, v10 offset:104
	ds_read2st64_b32 v[28:29], v1 offset0:14 offset1:30
	s_waitcnt lgkmcnt(0)
	v_fma_f32 v12, v80, v11, -v4
	v_fma_f32 v13, v96, v11, -v5
	ds_read2st64_b32 v[4:5], v1 offset0:44 offset1:60
	v_mul_f32_e32 v14, v13, v13
	v_fmac_f32_e32 v14, v12, v12
	v_fma_f32 v24, v81, v23, -v16
	v_fma_f32 v25, v97, v23, -v17
	ds_read2st64_b32 v[16:17], v1 offset0:45 offset1:61
	v_mul_f32_e32 v26, v25, v25
	v_fmac_f32_e32 v26, v24, v24
	v_fma_f32 v36, v82, v35, -v28
	v_fma_f32 v37, v98, v35, -v29
	ds_read2st64_b32 v[28:29], v1 offset0:46 offset1:62
	v_mul_f32_e32 v38, v37, v37
	v_fmac_f32_e32 v38, v36, v36
	s_waitcnt lgkmcnt(0)
	v_fma_f32 v15, v112, v11, -v4
	v_fmac_f32_e32 v14, v15, v15
	v_fma_f32 v11, v128, v11, -v5
	v_fmac_f32_e32 v14, v11, v11
	s_nop 1
	v_add_f32_dpp v4, v14, v14 quad_perm:[1,0,3,2] row_mask:0xf bank_mask:0xf
	s_nop 1
	v_add_f32_dpp v4, v4, v4 quad_perm:[2,3,0,1] row_mask:0xf bank_mask:0xf
	s_nop 1
	v_add_f32_dpp v4, v4, v4 row_half_mirror row_mask:0xf bank_mask:0xf
	s_nop 1
	v_add_f32_dpp v4, v4, v4 row_mirror row_mask:0xf bank_mask:0xf
	ds_swizzle_b32 v5, v4 offset:swizzle(SWAP,16)
	v_fma_f32 v27, v113, v23, -v16
	v_fmac_f32_e32 v26, v27, v27
	v_fma_f32 v23, v129, v23, -v17
	v_fmac_f32_e32 v26, v23, v23
	s_nop 1
	v_add_f32_dpp v16, v26, v26 quad_perm:[1,0,3,2] row_mask:0xf bank_mask:0xf
	s_nop 1
	v_add_f32_dpp v16, v16, v16 quad_perm:[2,3,0,1] row_mask:0xf bank_mask:0xf
	s_nop 1
	v_add_f32_dpp v16, v16, v16 row_half_mirror row_mask:0xf bank_mask:0xf
	s_nop 1
	v_add_f32_dpp v16, v16, v16 row_mirror row_mask:0xf bank_mask:0xf
	ds_swizzle_b32 v17, v16 offset:swizzle(SWAP,16)
	v_fma_f32 v39, v114, v35, -v28
	v_fmac_f32_e32 v38, v39, v39
	v_fma_f32 v35, v130, v35, -v29
	v_fmac_f32_e32 v38, v35, v35
	s_nop 1
	v_add_f32_dpp v28, v38, v38 quad_perm:[1,0,3,2] row_mask:0xf bank_mask:0xf
	s_nop 1
	v_add_f32_dpp v28, v28, v28 quad_perm:[2,3,0,1] row_mask:0xf bank_mask:0xf
	s_nop 1
	v_add_f32_dpp v28, v28, v28 row_half_mirror row_mask:0xf bank_mask:0xf
	s_nop 1
	v_add_f32_dpp v28, v28, v28 row_mirror row_mask:0xf bank_mask:0xf
	ds_swizzle_b32 v29, v28 offset:swizzle(SWAP,16)
	s_waitcnt lgkmcnt(0)
	v_add_f32_e32 v4, v4, v5
	v_fmamk_f32 v4, v4, 0x3c000000, v254
	s_nop 0
	s_nop 0
	s_nop 0
	s_nop 1
	s_nop 1
	s_nop 0
	v_rsq_f32_e32 v14, v4
	s_nop 0
	v_mul_f32_e32 v5, v12, v14
	v_mul_f32_e32 v12, v13, v14
	v_mul_f32_e32 v5, v7, v5
	v_mul_f32_e32 v12, v9, v12
	v_add_u32_e32 v4, 0x18000, v2
	v_cvt_pk_bf16_f32 v12, v5, v12
	v_mov_b32_e32 v5, v3
	v_lshl_add_u64 v[4:5], v[4:5], 1, s[6:7]
	global_store_short v[4:5], v12, off
	v_add_u32_e32 v4, 0x18020, v2
	v_mov_b32_e32 v5, v3
	v_lshl_add_u64 v[4:5], v[4:5], 1, s[6:7]
	global_store_short_d16_hi v[4:5], v12, off
	v_mul_f32_e32 v4, v15, v14
	v_mul_f32_e32 v5, v11, v14
	v_mul_f32_e32 v4, v6, v4
	v_mul_f32_e32 v5, v8, v5
	v_cvt_pk_bf16_f32 v11, v4, v5
	v_add_u32_e32 v4, 0x18040, v2
	v_mov_b32_e32 v5, v3
	v_lshl_add_u64 v[4:5], v[4:5], 1, s[6:7]
	global_store_short v[4:5], v11, off
	v_add_u32_e32 v4, 0x18060, v2
	v_mov_b32_e32 v5, v3
	v_lshl_add_u64 v[4:5], v[4:5], 1, s[6:7]
	global_store_short_d16_hi v[4:5], v11, off
	v_add_f32_e32 v16, v16, v17
	v_fmamk_f32 v16, v16, 0x3c000000, v254
	s_nop 0
	s_nop 0
	s_nop 0
	s_nop 1
	s_nop 1
	s_nop 0
	v_rsq_f32_e32 v26, v16
	s_nop 0
	v_mul_f32_e32 v17, v24, v26
	v_mul_f32_e32 v24, v25, v26
	v_mul_f32_e32 v17, v7, v17
	v_mul_f32_e32 v24, v9, v24
	v_add_u32_e32 v16, 0x19000, v2
	v_cvt_pk_bf16_f32 v24, v17, v24
	v_mov_b32_e32 v17, v3
	v_lshl_add_u64 v[16:17], v[16:17], 1, s[6:7]
	global_store_short v[16:17], v24, off
	v_add_u32_e32 v16, 0x19020, v2
	v_mov_b32_e32 v17, v3
	v_lshl_add_u64 v[16:17], v[16:17], 1, s[6:7]
	global_store_short_d16_hi v[16:17], v24, off
	v_mul_f32_e32 v16, v27, v26
	v_mul_f32_e32 v17, v23, v26
	v_mul_f32_e32 v16, v6, v16
	v_mul_f32_e32 v17, v8, v17
	v_cvt_pk_bf16_f32 v23, v16, v17
	v_add_u32_e32 v16, 0x19040, v2
	v_mov_b32_e32 v17, v3
	v_lshl_add_u64 v[16:17], v[16:17], 1, s[6:7]
	global_store_short v[16:17], v23, off
	v_add_u32_e32 v16, 0x19060, v2
	v_mov_b32_e32 v17, v3
	v_lshl_add_u64 v[16:17], v[16:17], 1, s[6:7]
	global_store_short_d16_hi v[16:17], v23, off
	v_add_f32_e32 v28, v28, v29
	v_fmamk_f32 v28, v28, 0x3c000000, v254
	s_nop 0
	s_nop 0
	s_nop 0
	s_nop 1
	s_nop 1
	s_nop 0
	v_rsq_f32_e32 v38, v28
	s_nop 0
	v_mul_f32_e32 v29, v36, v38
	v_mul_f32_e32 v36, v37, v38
	v_mul_f32_e32 v29, v7, v29
	v_mul_f32_e32 v36, v9, v36
	v_add_u32_e32 v28, 0x1a000, v2
	v_cvt_pk_bf16_f32 v36, v29, v36
	v_mov_b32_e32 v29, v3
	v_lshl_add_u64 v[28:29], v[28:29], 1, s[6:7]
	global_store_short v[28:29], v36, off
	v_add_u32_e32 v28, 0x1a020, v2
	v_mov_b32_e32 v29, v3
	v_lshl_add_u64 v[28:29], v[28:29], 1, s[6:7]
	global_store_short_d16_hi v[28:29], v36, off
	v_mul_f32_e32 v28, v39, v38
	v_mul_f32_e32 v29, v35, v38
	v_mul_f32_e32 v28, v6, v28
	v_mul_f32_e32 v29, v8, v29
	v_cvt_pk_bf16_f32 v35, v28, v29
	v_add_u32_e32 v28, 0x1a040, v2
	v_mov_b32_e32 v29, v3
	v_lshl_add_u64 v[28:29], v[28:29], 1, s[6:7]
	global_store_short v[28:29], v35, off
	v_add_u32_e32 v28, 0x1a060, v2
	v_mov_b32_e32 v29, v3
	v_lshl_add_u64 v[28:29], v[28:29], 1, s[6:7]
	global_store_short_d16_hi v[28:29], v35, off
	ds_read_b32 v10, v10 offset:108
	ds_read2st64_b32 v[4:5], v1 offset0:15 offset1:31
	s_waitcnt lgkmcnt(0)
	v_fma_f32 v11, v83, v10, -v4
	v_fma_f32 v12, v99, v10, -v5
	ds_read2st64_b32 v[4:5], v1 offset0:47 offset1:63
	v_mul_f32_e32 v13, v12, v12
	v_fmac_f32_e32 v13, v11, v11
	s_waitcnt lgkmcnt(0)
	v_fma_f32 v1, v115, v10, -v4
	v_fmac_f32_e32 v13, v1, v1
	v_fma_f32 v10, v131, v10, -v5
	v_fmac_f32_e32 v13, v10, v10
	s_nop 1
	v_add_f32_dpp v4, v13, v13 quad_perm:[1,0,3,2] row_mask:0xf bank_mask:0xf
	s_nop 1
	v_add_f32_dpp v4, v4, v4 quad_perm:[2,3,0,1] row_mask:0xf bank_mask:0xf
	s_nop 1
	v_add_f32_dpp v4, v4, v4 row_half_mirror row_mask:0xf bank_mask:0xf
	s_nop 1
	v_add_f32_dpp v4, v4, v4 row_mirror row_mask:0xf bank_mask:0xf
	ds_swizzle_b32 v5, v4 offset:swizzle(SWAP,16)
	s_waitcnt lgkmcnt(0)
	v_add_f32_e32 v4, v4, v5
	v_fmamk_f32 v4, v4, 0x3c000000, v254
	s_nop 0
	s_nop 0
	s_nop 0
	s_nop 1
	s_nop 1
	s_nop 0
	v_rsq_f32_e32 v13, v4
	s_nop 0
	v_mul_f32_e32 v5, v11, v13
	v_mul_f32_e32 v5, v7, v5
	v_mul_f32_e32 v7, v12, v13
	v_mul_f32_e32 v7, v9, v7
	v_add_u32_e32 v4, 0x1b000, v2
	v_cvt_pk_bf16_f32 v7, v5, v7
	v_mov_b32_e32 v5, v3
	v_lshl_add_u64 v[4:5], v[4:5], 1, s[6:7]
	global_store_short v[4:5], v7, off
	v_add_u32_e32 v4, 0x1b020, v2
	v_mov_b32_e32 v5, v3
	v_lshl_add_u64 v[4:5], v[4:5], 1, s[6:7]
	global_store_short_d16_hi v[4:5], v7, off
	v_mul_f32_e32 v1, v1, v13
	v_mul_f32_e32 v4, v10, v13
	v_mul_f32_e32 v1, v6, v1
	v_mul_f32_e32 v4, v8, v4
	v_cvt_pk_bf16_f32 v1, v1, v4
	v_add_u32_e32 v4, 0x1b040, v2
	v_mov_b32_e32 v5, v3
	v_lshl_add_u64 v[4:5], v[4:5], 1, s[6:7]
	v_add_u32_e32 v2, 0x1b060, v2
	global_store_short v[4:5], v1, off
	v_lshl_add_u64 v[4:5], v[2:3], 1, s[6:7]
	global_store_short_d16_hi v[4:5], v1, off

.LBB0_1374:
	s_or_b64 exec, exec, s[4:5]
	s_waitcnt lgkmcnt(0)
	v_lshlrev_b32_e32 v4, 2, v158
	global_load_dword v248, v4, s[0:1]
	global_load_dword v249, v4, s[0:1] offset:128
	global_load_dword v250, v4, s[0:1] offset:256
	global_load_dword v251, v4, s[0:1] offset:384
	v_add_u32_e32 v9, s29, v148
	s_lshl_b64 s[4:5], s[24:25], 13
	s_add_u32 s6, s86, s4
	s_addc_u32 s7, s87, s5
	s_waitcnt vmcnt(0)
	v_mul_f32_e32 v6, v164, v248
	v_mul_f32_e32 v8, v164, v249
	v_mul_f32_e32 v2, v164, v250
	v_mul_f32_e32 v7, v164, v251
	v_lshl_or_b32 v4, v159, 14, v158
	ds_read_b32 v5, v9
	ds_read2st64_b32 v[10:11], v1 offset1:16
	s_waitcnt lgkmcnt(0)
	v_fma_f32 v12, v68, v5, -v10
	v_fma_f32 v13, v84, v5, -v11
	ds_read2st64_b32 v[10:11], v1 offset0:32 offset1:48
	v_mul_f32_e32 v14, v13, v13
	v_fmac_f32_e32 v14, v12, v12
	s_waitcnt lgkmcnt(0)
	v_fma_f32 v15, v100, v5, -v10
	v_fmac_f32_e32 v14, v15, v15
	v_fma_f32 v16, v116, v5, -v11
	v_fmac_f32_e32 v14, v16, v16
	s_nop 1
	v_add_f32_dpp v5, v14, v14 quad_perm:[1,0,3,2] row_mask:0xf bank_mask:0xf
	s_nop 1
	v_add_f32_dpp v5, v5, v5 quad_perm:[2,3,0,1] row_mask:0xf bank_mask:0xf
	s_nop 1
	v_add_f32_dpp v5, v5, v5 row_half_mirror row_mask:0xf bank_mask:0xf
	s_nop 1
	v_add_f32_dpp v5, v5, v5 row_mirror row_mask:0xf bank_mask:0xf
	ds_swizzle_b32 v10, v5 offset:swizzle(SWAP,16)
	s_waitcnt lgkmcnt(0)
	v_add_f32_e32 v5, v5, v10
	v_fmamk_f32 v5, v5, 0x3c000000, v254
	s_nop 0
	s_nop 0
	s_nop 0
	s_nop 1
	s_nop 1
	s_nop 0
	v_rsq_f32_e32 v14, v5
	s_nop 0
	v_mul_f32_e32 v5, v12, v14
	v_mul_f32_e32 v5, v6, v5
	v_mul_f32_e32 v10, v13, v14
	v_mul_f32_e32 v10, v8, v10
	v_cvt_pk_bf16_f32 v12, v5, v10
	v_mov_b32_e32 v5, v3
	v_lshl_add_u64 v[10:11], v[4:5], 1, s[6:7]
	global_store_short v[10:11], v12, off offset:768
	v_add_u32_e32 v10, 32, v4
	v_mov_b32_e32 v11, v3
	v_lshl_add_u64 v[10:11], v[10:11], 1, s[6:7]
	global_store_short_d16_hi v[10:11], v12, off offset:768
	v_mul_f32_e32 v5, v15, v14
	v_mul_f32_e32 v10, v16, v14
	v_mul_f32_e32 v5, v2, v5
	v_mul_f32_e32 v10, v7, v10
	v_cvt_pk_bf16_f32 v5, v5, v10
	v_add_u32_e32 v10, 64, v4
	v_mov_b32_e32 v11, v3
	v_lshl_add_u64 v[10:11], v[10:11], 1, s[6:7]
	global_store_short v[10:11], v5, off offset:768
	v_add_u32_e32 v10, 0x60, v4
	v_mov_b32_e32 v11, v3
	v_lshl_add_u64 v[10:11], v[10:11], 1, s[6:7]
	global_store_short_d16_hi v[10:11], v5, off offset:768
	ds_read_b32 v5, v9 offset:4
	ds_read2st64_b32 v[10:11], v1 offset0:1 offset1:17
	ds_read_b32 v35, v9 offset:8
	ds_read2st64_b32 v[40:41], v1 offset0:2 offset1:18
	ds_read_b32 v47, v9 offset:12
	ds_read2st64_b32 v[52:53], v1 offset0:3 offset1:19
	ds_read_b32 v149, v9 offset:32
	ds_read2st64_b32 v[154:155], v1 offset0:4 offset1:20
	s_waitcnt lgkmcnt(0)
	v_fma_f32 v12, v69, v5, -v10
	v_fma_f32 v13, v85, v5, -v11
	ds_read2st64_b32 v[10:11], v1 offset0:33 offset1:49
	v_mul_f32_e32 v14, v13, v13
	v_fmac_f32_e32 v14, v12, v12
	v_fma_f32 v42, v70, v35, -v40
	v_fma_f32 v43, v86, v35, -v41
	ds_read2st64_b32 v[40:41], v1 offset0:34 offset1:50
	v_mul_f32_e32 v44, v43, v43
	v_fmac_f32_e32 v44, v42, v42
	v_fma_f32 v54, v71, v47, -v52
	v_fma_f32 v55, v87, v47, -v53
	ds_read2st64_b32 v[52:53], v1 offset0:35 offset1:51
	v_mul_f32_e32 v56, v55, v55
	v_fmac_f32_e32 v56, v54, v54
	v_fma_f32 v156, v72, v149, -v154
	v_fma_f32 v157, v88, v149, -v155
	ds_read2st64_b32 v[154:155], v1 offset0:36 offset1:52
	v_mul_f32_e32 v158, v157, v157
	v_fmac_f32_e32 v158, v156, v156
	s_waitcnt lgkmcnt(0)
	v_fma_f32 v15, v101, v5, -v10
	v_fmac_f32_e32 v14, v15, v15
	v_fma_f32 v5, v117, v5, -v11
	v_fmac_f32_e32 v14, v5, v5
	s_nop 1
	v_add_f32_dpp v10, v14, v14 quad_perm:[1,0,3,2] row_mask:0xf bank_mask:0xf
	s_nop 1
	v_add_f32_dpp v10, v10, v10 quad_perm:[2,3,0,1] row_mask:0xf bank_mask:0xf
	s_nop 1
	v_add_f32_dpp v10, v10, v10 row_half_mirror row_mask:0xf bank_mask:0xf
	s_nop 1
	v_add_f32_dpp v10, v10, v10 row_mirror row_mask:0xf bank_mask:0xf
	ds_swizzle_b32 v11, v10 offset:swizzle(SWAP,16)
	v_fma_f32 v45, v102, v35, -v40
	v_fmac_f32_e32 v44, v45, v45
	v_fma_f32 v35, v118, v35, -v41
	v_fmac_f32_e32 v44, v35, v35
	s_nop 1
	v_add_f32_dpp v40, v44, v44 quad_perm:[1,0,3,2] row_mask:0xf bank_mask:0xf
	s_nop 1
	v_add_f32_dpp v40, v40, v40 quad_perm:[2,3,0,1] row_mask:0xf bank_mask:0xf
	s_nop 1
	v_add_f32_dpp v40, v40, v40 row_half_mirror row_mask:0xf bank_mask:0xf
	s_nop 1
	v_add_f32_dpp v40, v40, v40 row_mirror row_mask:0xf bank_mask:0xf
	ds_swizzle_b32 v41, v40 offset:swizzle(SWAP,16)
	v_fma_f32 v57, v103, v47, -v52
	v_fmac_f32_e32 v56, v57, v57
	v_fma_f32 v47, v119, v47, -v53
	v_fmac_f32_e32 v56, v47, v47
	s_nop 1
	v_add_f32_dpp v52, v56, v56 quad_perm:[1,0,3,2] row_mask:0xf bank_mask:0xf
	s_nop 1
	v_add_f32_dpp v52, v52, v52 quad_perm:[2,3,0,1] row_mask:0xf bank_mask:0xf
	s_nop 1
	v_add_f32_dpp v52, v52, v52 row_half_mirror row_mask:0xf bank_mask:0xf
	s_nop 1
	v_add_f32_dpp v52, v52, v52 row_mirror row_mask:0xf bank_mask:0xf
	ds_swizzle_b32 v53, v52 offset:swizzle(SWAP,16)
	v_fma_f32 v159, v104, v149, -v154
	v_fmac_f32_e32 v158, v159, v159
	v_fma_f32 v149, v120, v149, -v155
	v_fmac_f32_e32 v158, v149, v149
	s_nop 1
	v_add_f32_dpp v154, v158, v158 quad_perm:[1,0,3,2] row_mask:0xf bank_mask:0xf
	s_nop 1
	v_add_f32_dpp v154, v154, v154 quad_perm:[2,3,0,1] row_mask:0xf bank_mask:0xf
	s_nop 1
	v_add_f32_dpp v154, v154, v154 row_half_mirror row_mask:0xf bank_mask:0xf
	s_nop 1
	v_add_f32_dpp v154, v154, v154 row_mirror row_mask:0xf bank_mask:0xf
	ds_swizzle_b32 v155, v154 offset:swizzle(SWAP,16)
	s_waitcnt lgkmcnt(0)
	v_add_f32_e32 v10, v10, v11
	v_fmamk_f32 v10, v10, 0x3c000000, v254
	s_nop 0
	s_nop 0
	s_nop 0
	s_nop 1
	s_nop 1
	s_nop 0
	v_rsq_f32_e32 v14, v10
	s_nop 0
	v_mul_f32_e32 v11, v12, v14
	v_mul_f32_e32 v12, v13, v14
	v_mul_f32_e32 v11, v6, v11
	v_mul_f32_e32 v12, v8, v12
	v_add_u32_e32 v10, 0x1000, v4
	v_cvt_pk_bf16_f32 v12, v11, v12
	v_mov_b32_e32 v11, v3
	v_lshl_add_u64 v[10:11], v[10:11], 1, s[6:7]
	global_store_short v[10:11], v12, off offset:768
	v_add_u32_e32 v10, 0x1020, v4
	v_mov_b32_e32 v11, v3
	v_lshl_add_u64 v[10:11], v[10:11], 1, s[6:7]
	global_store_short_d16_hi v[10:11], v12, off offset:768
	v_mul_f32_e32 v10, v15, v14
	v_mul_f32_e32 v5, v5, v14
	v_mul_f32_e32 v10, v2, v10
	v_mul_f32_e32 v5, v7, v5
	v_cvt_pk_bf16_f32 v5, v10, v5
	v_add_u32_e32 v10, 0x1040, v4
	v_mov_b32_e32 v11, v3
	v_lshl_add_u64 v[10:11], v[10:11], 1, s[6:7]
	global_store_short v[10:11], v5, off offset:768
	v_add_u32_e32 v10, 0x1060, v4
	v_mov_b32_e32 v11, v3
	v_lshl_add_u64 v[10:11], v[10:11], 1, s[6:7]
	global_store_short_d16_hi v[10:11], v5, off offset:768
	v_add_f32_e32 v40, v40, v41
	v_fmamk_f32 v40, v40, 0x3c000000, v254
	s_nop 0
	s_nop 0
	s_nop 0
	s_nop 1
	s_nop 1
	s_nop 0
	v_rsq_f32_e32 v44, v40
	s_nop 0
	v_mul_f32_e32 v41, v42, v44
	v_mul_f32_e32 v42, v43, v44
	v_mul_f32_e32 v41, v6, v41
	v_mul_f32_e32 v42, v8, v42
	v_add_u32_e32 v40, 0x2000, v4
	v_cvt_pk_bf16_f32 v42, v41, v42
	v_mov_b32_e32 v41, v3
	v_lshl_add_u64 v[40:41], v[40:41], 1, s[6:7]
	global_store_short v[40:41], v42, off offset:768
	v_add_u32_e32 v40, 0x2020, v4
	v_mov_b32_e32 v41, v3
	v_lshl_add_u64 v[40:41], v[40:41], 1, s[6:7]
	global_store_short_d16_hi v[40:41], v42, off offset:768
	v_mul_f32_e32 v40, v45, v44
	v_mul_f32_e32 v35, v35, v44
	v_mul_f32_e32 v40, v2, v40
	v_mul_f32_e32 v35, v7, v35
	v_cvt_pk_bf16_f32 v35, v40, v35
	v_add_u32_e32 v40, 0x2040, v4
	v_mov_b32_e32 v41, v3
	v_lshl_add_u64 v[40:41], v[40:41], 1, s[6:7]
	global_store_short v[40:41], v35, off offset:768
	v_add_u32_e32 v40, 0x2060, v4
	v_mov_b32_e32 v41, v3
	v_lshl_add_u64 v[40:41], v[40:41], 1, s[6:7]
	global_store_short_d16_hi v[40:41], v35, off offset:768
	v_add_f32_e32 v52, v52, v53
	v_fmamk_f32 v52, v52, 0x3c000000, v254
	s_nop 0
	s_nop 0
	s_nop 0
	s_nop 1
	s_nop 1
	s_nop 0
	v_rsq_f32_e32 v56, v52
	s_nop 0
	v_mul_f32_e32 v53, v54, v56
	v_mul_f32_e32 v54, v55, v56
	v_mul_f32_e32 v53, v6, v53
	v_mul_f32_e32 v54, v8, v54
	v_add_u32_e32 v52, 0x3000, v4
	v_cvt_pk_bf16_f32 v54, v53, v54
	v_mov_b32_e32 v53, v3
	v_lshl_add_u64 v[52:53], v[52:53], 1, s[6:7]
	global_store_short v[52:53], v54, off offset:768
	v_add_u32_e32 v52, 0x3020, v4
	v_mov_b32_e32 v53, v3
	v_lshl_add_u64 v[52:53], v[52:53], 1, s[6:7]
	global_store_short_d16_hi v[52:53], v54, off offset:768
	v_mul_f32_e32 v52, v57, v56
	v_mul_f32_e32 v47, v47, v56
	v_mul_f32_e32 v52, v2, v52
	v_mul_f32_e32 v47, v7, v47
	v_cvt_pk_bf16_f32 v47, v52, v47
	v_add_u32_e32 v52, 0x3040, v4
	v_mov_b32_e32 v53, v3
	v_lshl_add_u64 v[52:53], v[52:53], 1, s[6:7]
	global_store_short v[52:53], v47, off offset:768
	v_add_u32_e32 v52, 0x3060, v4
	v_mov_b32_e32 v53, v3
	v_lshl_add_u64 v[52:53], v[52:53], 1, s[6:7]
	global_store_short_d16_hi v[52:53], v47, off offset:768
	v_add_f32_e32 v154, v154, v155
	v_fmamk_f32 v154, v154, 0x3c000000, v254
	s_nop 0
	s_nop 0
	s_nop 0
	s_nop 1
	s_nop 1
	s_nop 0
	v_rsq_f32_e32 v158, v154
	s_nop 0
	v_mul_f32_e32 v155, v156, v158
	v_mul_f32_e32 v156, v157, v158
	v_mul_f32_e32 v155, v6, v155
	v_mul_f32_e32 v156, v8, v156
	v_add_u32_e32 v154, 0x8000, v4
	v_cvt_pk_bf16_f32 v156, v155, v156
	v_mov_b32_e32 v155, v3
	v_lshl_add_u64 v[154:155], v[154:155], 1, s[6:7]
	global_store_short v[154:155], v156, off offset:768
	v_add_u32_e32 v154, 0x8020, v4
	v_mov_b32_e32 v155, v3
	v_lshl_add_u64 v[154:155], v[154:155], 1, s[6:7]
	global_store_short_d16_hi v[154:155], v156, off offset:768
	v_mul_f32_e32 v154, v159, v158
	v_mul_f32_e32 v149, v149, v158
	v_mul_f32_e32 v154, v2, v154
	v_mul_f32_e32 v149, v7, v149
	v_cvt_pk_bf16_f32 v149, v154, v149
	v_add_u32_e32 v154, 0x8040, v4
	v_mov_b32_e32 v155, v3
	v_lshl_add_u64 v[154:155], v[154:155], 1, s[6:7]
	global_store_short v[154:155], v149, off offset:768
	v_add_u32_e32 v154, 0x8060, v4
	v_mov_b32_e32 v155, v3
	v_lshl_add_u64 v[154:155], v[154:155], 1, s[6:7]
	global_store_short_d16_hi v[154:155], v149, off offset:768
	ds_read_b32 v5, v9 offset:36
	ds_read2st64_b32 v[10:11], v1 offset0:5 offset1:21
	ds_read_b32 v35, v9 offset:40
	ds_read2st64_b32 v[40:41], v1 offset0:6 offset1:22
	ds_read_b32 v47, v9 offset:44
	ds_read2st64_b32 v[52:53], v1 offset0:7 offset1:23
	ds_read_b32 v149, v9 offset:64
	ds_read2st64_b32 v[154:155], v1 offset0:8 offset1:24
	s_waitcnt lgkmcnt(0)
	v_fma_f32 v12, v73, v5, -v10
	v_fma_f32 v13, v89, v5, -v11
	ds_read2st64_b32 v[10:11], v1 offset0:37 offset1:53
	v_mul_f32_e32 v14, v13, v13
	v_fmac_f32_e32 v14, v12, v12
	v_fma_f32 v42, v74, v35, -v40
	v_fma_f32 v43, v90, v35, -v41
	ds_read2st64_b32 v[40:41], v1 offset0:38 offset1:54
	v_mul_f32_e32 v44, v43, v43
	v_fmac_f32_e32 v44, v42, v42
	v_fma_f32 v54, v75, v47, -v52
	v_fma_f32 v55, v91, v47, -v53
	ds_read2st64_b32 v[52:53], v1 offset0:39 offset1:55
	v_mul_f32_e32 v56, v55, v55
	v_fmac_f32_e32 v56, v54, v54
	v_fma_f32 v156, v76, v149, -v154
	v_fma_f32 v157, v92, v149, -v155
	ds_read2st64_b32 v[154:155], v1 offset0:40 offset1:56
	v_mul_f32_e32 v158, v157, v157
	v_fmac_f32_e32 v158, v156, v156
	s_waitcnt lgkmcnt(0)
	v_fma_f32 v15, v105, v5, -v10
	v_fmac_f32_e32 v14, v15, v15
	v_fma_f32 v5, v121, v5, -v11
	v_fmac_f32_e32 v14, v5, v5
	s_nop 1
	v_add_f32_dpp v10, v14, v14 quad_perm:[1,0,3,2] row_mask:0xf bank_mask:0xf
	s_nop 1
	v_add_f32_dpp v10, v10, v10 quad_perm:[2,3,0,1] row_mask:0xf bank_mask:0xf
	s_nop 1
	v_add_f32_dpp v10, v10, v10 row_half_mirror row_mask:0xf bank_mask:0xf
	s_nop 1
	v_add_f32_dpp v10, v10, v10 row_mirror row_mask:0xf bank_mask:0xf
	ds_swizzle_b32 v11, v10 offset:swizzle(SWAP,16)
	v_fma_f32 v45, v106, v35, -v40
	v_fmac_f32_e32 v44, v45, v45
	v_fma_f32 v35, v122, v35, -v41
	v_fmac_f32_e32 v44, v35, v35
	s_nop 1
	v_add_f32_dpp v40, v44, v44 quad_perm:[1,0,3,2] row_mask:0xf bank_mask:0xf
	s_nop 1
	v_add_f32_dpp v40, v40, v40 quad_perm:[2,3,0,1] row_mask:0xf bank_mask:0xf
	s_nop 1
	v_add_f32_dpp v40, v40, v40 row_half_mirror row_mask:0xf bank_mask:0xf
	s_nop 1
	v_add_f32_dpp v40, v40, v40 row_mirror row_mask:0xf bank_mask:0xf
	ds_swizzle_b32 v41, v40 offset:swizzle(SWAP,16)
	v_fma_f32 v57, v107, v47, -v52
	v_fmac_f32_e32 v56, v57, v57
	v_fma_f32 v47, v123, v47, -v53
	v_fmac_f32_e32 v56, v47, v47
	s_nop 1
	v_add_f32_dpp v52, v56, v56 quad_perm:[1,0,3,2] row_mask:0xf bank_mask:0xf
	s_nop 1
	v_add_f32_dpp v52, v52, v52 quad_perm:[2,3,0,1] row_mask:0xf bank_mask:0xf
	s_nop 1
	v_add_f32_dpp v52, v52, v52 row_half_mirror row_mask:0xf bank_mask:0xf
	s_nop 1
	v_add_f32_dpp v52, v52, v52 row_mirror row_mask:0xf bank_mask:0xf
	ds_swizzle_b32 v53, v52 offset:swizzle(SWAP,16)
	v_fma_f32 v159, v108, v149, -v154
	v_fmac_f32_e32 v158, v159, v159
	v_fma_f32 v149, v124, v149, -v155
	v_fmac_f32_e32 v158, v149, v149
	s_nop 1
	v_add_f32_dpp v154, v158, v158 quad_perm:[1,0,3,2] row_mask:0xf bank_mask:0xf
	s_nop 1
	v_add_f32_dpp v154, v154, v154 quad_perm:[2,3,0,1] row_mask:0xf bank_mask:0xf
	s_nop 1
	v_add_f32_dpp v154, v154, v154 row_half_mirror row_mask:0xf bank_mask:0xf
	s_nop 1
	v_add_f32_dpp v154, v154, v154 row_mirror row_mask:0xf bank_mask:0xf
	ds_swizzle_b32 v155, v154 offset:swizzle(SWAP,16)
	s_waitcnt lgkmcnt(0)
	v_add_f32_e32 v10, v10, v11
	v_fmamk_f32 v10, v10, 0x3c000000, v254
	s_nop 0
	s_nop 0
	s_nop 0
	s_nop 1
	s_nop 1
	s_nop 0
	v_rsq_f32_e32 v14, v10
	s_nop 0
	v_mul_f32_e32 v11, v12, v14
	v_mul_f32_e32 v12, v13, v14
	v_mul_f32_e32 v11, v6, v11
	v_mul_f32_e32 v12, v8, v12
	v_add_u32_e32 v10, 0x9000, v4
	v_cvt_pk_bf16_f32 v12, v11, v12
	v_mov_b32_e32 v11, v3
	v_lshl_add_u64 v[10:11], v[10:11], 1, s[6:7]
	global_store_short v[10:11], v12, off offset:768
	v_add_u32_e32 v10, 0x9020, v4
	v_mov_b32_e32 v11, v3
	v_lshl_add_u64 v[10:11], v[10:11], 1, s[6:7]
	global_store_short_d16_hi v[10:11], v12, off offset:768
	v_mul_f32_e32 v10, v15, v14
	v_mul_f32_e32 v5, v5, v14
	v_mul_f32_e32 v10, v2, v10
	v_mul_f32_e32 v5, v7, v5
	v_cvt_pk_bf16_f32 v5, v10, v5
	v_add_u32_e32 v10, 0x9040, v4
	v_mov_b32_e32 v11, v3
	v_lshl_add_u64 v[10:11], v[10:11], 1, s[6:7]
	global_store_short v[10:11], v5, off offset:768
	v_add_u32_e32 v10, 0x9060, v4
	v_mov_b32_e32 v11, v3
	v_lshl_add_u64 v[10:11], v[10:11], 1, s[6:7]
	global_store_short_d16_hi v[10:11], v5, off offset:768
	v_add_f32_e32 v40, v40, v41
	v_fmamk_f32 v40, v40, 0x3c000000, v254
	s_nop 0
	s_nop 0
	s_nop 0
	s_nop 1
	s_nop 1
	s_nop 0
	v_rsq_f32_e32 v44, v40
	s_nop 0
	v_mul_f32_e32 v41, v42, v44
	v_mul_f32_e32 v42, v43, v44
	v_mul_f32_e32 v41, v6, v41
	v_mul_f32_e32 v42, v8, v42
	v_add_u32_e32 v40, 0xa000, v4
	v_cvt_pk_bf16_f32 v42, v41, v42
	v_mov_b32_e32 v41, v3
	v_lshl_add_u64 v[40:41], v[40:41], 1, s[6:7]
	global_store_short v[40:41], v42, off offset:768
	v_add_u32_e32 v40, 0xa020, v4
	v_mov_b32_e32 v41, v3
	v_lshl_add_u64 v[40:41], v[40:41], 1, s[6:7]
	global_store_short_d16_hi v[40:41], v42, off offset:768
	v_mul_f32_e32 v40, v45, v44
	v_mul_f32_e32 v35, v35, v44
	v_mul_f32_e32 v40, v2, v40
	v_mul_f32_e32 v35, v7, v35
	v_cvt_pk_bf16_f32 v35, v40, v35
	v_add_u32_e32 v40, 0xa040, v4
	v_mov_b32_e32 v41, v3
	v_lshl_add_u64 v[40:41], v[40:41], 1, s[6:7]
	global_store_short v[40:41], v35, off offset:768
	v_add_u32_e32 v40, 0xa060, v4
	v_mov_b32_e32 v41, v3
	v_lshl_add_u64 v[40:41], v[40:41], 1, s[6:7]
	global_store_short_d16_hi v[40:41], v35, off offset:768
	v_add_f32_e32 v52, v52, v53
	v_fmamk_f32 v52, v52, 0x3c000000, v254
	s_nop 0
	s_nop 0
	s_nop 0
	s_nop 1
	s_nop 1
	s_nop 0
	v_rsq_f32_e32 v56, v52
	s_nop 0
	v_mul_f32_e32 v53, v54, v56
	v_mul_f32_e32 v54, v55, v56
	v_mul_f32_e32 v53, v6, v53
	v_mul_f32_e32 v54, v8, v54
	v_add_u32_e32 v52, 0xb000, v4
	v_cvt_pk_bf16_f32 v54, v53, v54
	v_mov_b32_e32 v53, v3
	v_lshl_add_u64 v[52:53], v[52:53], 1, s[6:7]
	global_store_short v[52:53], v54, off offset:768
	v_add_u32_e32 v52, 0xb020, v4
	v_mov_b32_e32 v53, v3
	v_lshl_add_u64 v[52:53], v[52:53], 1, s[6:7]
	global_store_short_d16_hi v[52:53], v54, off offset:768
	v_mul_f32_e32 v52, v57, v56
	v_mul_f32_e32 v47, v47, v56
	v_mul_f32_e32 v52, v2, v52
	v_mul_f32_e32 v47, v7, v47
	v_cvt_pk_bf16_f32 v47, v52, v47
	v_add_u32_e32 v52, 0xb040, v4
	v_mov_b32_e32 v53, v3
	v_lshl_add_u64 v[52:53], v[52:53], 1, s[6:7]
	global_store_short v[52:53], v47, off offset:768
	v_add_u32_e32 v52, 0xb060, v4
	v_mov_b32_e32 v53, v3
	v_lshl_add_u64 v[52:53], v[52:53], 1, s[6:7]
	global_store_short_d16_hi v[52:53], v47, off offset:768
	v_add_f32_e32 v154, v154, v155
	v_fmamk_f32 v154, v154, 0x3c000000, v254
	s_nop 0
	s_nop 0
	s_nop 0
	s_nop 1
	s_nop 1
	s_nop 0
	v_rsq_f32_e32 v158, v154
	s_nop 0
	v_mul_f32_e32 v155, v156, v158
	v_mul_f32_e32 v156, v157, v158
	v_mul_f32_e32 v155, v6, v155
	v_mul_f32_e32 v156, v8, v156
	v_add_u32_e32 v154, 0x10000, v4
	v_cvt_pk_bf16_f32 v156, v155, v156
	v_mov_b32_e32 v155, v3
	v_lshl_add_u64 v[154:155], v[154:155], 1, s[6:7]
	global_store_short v[154:155], v156, off offset:768
	v_add_u32_e32 v154, 0x10020, v4
	v_mov_b32_e32 v155, v3
	v_lshl_add_u64 v[154:155], v[154:155], 1, s[6:7]
	global_store_short_d16_hi v[154:155], v156, off offset:768
	v_mul_f32_e32 v154, v159, v158
	v_mul_f32_e32 v149, v149, v158
	v_mul_f32_e32 v154, v2, v154
	v_mul_f32_e32 v149, v7, v149
	v_cvt_pk_bf16_f32 v149, v154, v149
	v_add_u32_e32 v154, 0x10040, v4
	v_mov_b32_e32 v155, v3
	v_lshl_add_u64 v[154:155], v[154:155], 1, s[6:7]
	global_store_short v[154:155], v149, off offset:768
	v_add_u32_e32 v154, 0x10060, v4
	v_mov_b32_e32 v155, v3
	v_lshl_add_u64 v[154:155], v[154:155], 1, s[6:7]
	global_store_short_d16_hi v[154:155], v149, off offset:768
	ds_read_b32 v5, v9 offset:68
	ds_read2st64_b32 v[10:11], v1 offset0:9 offset1:25
	ds_read_b32 v35, v9 offset:72
	ds_read2st64_b32 v[40:41], v1 offset0:10 offset1:26
	ds_read_b32 v47, v9 offset:76
	ds_read2st64_b32 v[52:53], v1 offset0:11 offset1:27
	ds_read_b32 v149, v9 offset:96
	ds_read2st64_b32 v[154:155], v1 offset0:12 offset1:28
	s_waitcnt lgkmcnt(0)
	v_fma_f32 v12, v77, v5, -v10
	v_fma_f32 v13, v93, v5, -v11
	ds_read2st64_b32 v[10:11], v1 offset0:41 offset1:57
	v_mul_f32_e32 v14, v13, v13
	v_fmac_f32_e32 v14, v12, v12
	v_fma_f32 v42, v78, v35, -v40
	v_fma_f32 v43, v94, v35, -v41
	ds_read2st64_b32 v[40:41], v1 offset0:42 offset1:58
	v_mul_f32_e32 v44, v43, v43
	v_fmac_f32_e32 v44, v42, v42
	v_fma_f32 v54, v79, v47, -v52
	v_fma_f32 v55, v95, v47, -v53
	ds_read2st64_b32 v[52:53], v1 offset0:43 offset1:59
	v_mul_f32_e32 v56, v55, v55
	v_fmac_f32_e32 v56, v54, v54
	v_fma_f32 v156, v80, v149, -v154
	v_fma_f32 v157, v96, v149, -v155
	ds_read2st64_b32 v[154:155], v1 offset0:44 offset1:60
	v_mul_f32_e32 v158, v157, v157
	v_fmac_f32_e32 v158, v156, v156
	s_waitcnt lgkmcnt(0)
	v_fma_f32 v15, v109, v5, -v10
	v_fmac_f32_e32 v14, v15, v15
	v_fma_f32 v5, v125, v5, -v11
	v_fmac_f32_e32 v14, v5, v5
	s_nop 1
	v_add_f32_dpp v10, v14, v14 quad_perm:[1,0,3,2] row_mask:0xf bank_mask:0xf
	s_nop 1
	v_add_f32_dpp v10, v10, v10 quad_perm:[2,3,0,1] row_mask:0xf bank_mask:0xf
	s_nop 1
	v_add_f32_dpp v10, v10, v10 row_half_mirror row_mask:0xf bank_mask:0xf
	s_nop 1
	v_add_f32_dpp v10, v10, v10 row_mirror row_mask:0xf bank_mask:0xf
	ds_swizzle_b32 v11, v10 offset:swizzle(SWAP,16)
	v_fma_f32 v45, v110, v35, -v40
	v_fmac_f32_e32 v44, v45, v45
	v_fma_f32 v35, v126, v35, -v41
	v_fmac_f32_e32 v44, v35, v35
	s_nop 1
	v_add_f32_dpp v40, v44, v44 quad_perm:[1,0,3,2] row_mask:0xf bank_mask:0xf
	s_nop 1
	v_add_f32_dpp v40, v40, v40 quad_perm:[2,3,0,1] row_mask:0xf bank_mask:0xf
	s_nop 1
	v_add_f32_dpp v40, v40, v40 row_half_mirror row_mask:0xf bank_mask:0xf
	s_nop 1
	v_add_f32_dpp v40, v40, v40 row_mirror row_mask:0xf bank_mask:0xf
	ds_swizzle_b32 v41, v40 offset:swizzle(SWAP,16)
	v_fma_f32 v57, v111, v47, -v52
	v_fmac_f32_e32 v56, v57, v57
	v_fma_f32 v47, v127, v47, -v53
	v_fmac_f32_e32 v56, v47, v47
	s_nop 1
	v_add_f32_dpp v52, v56, v56 quad_perm:[1,0,3,2] row_mask:0xf bank_mask:0xf
	s_nop 1
	v_add_f32_dpp v52, v52, v52 quad_perm:[2,3,0,1] row_mask:0xf bank_mask:0xf
	s_nop 1
	v_add_f32_dpp v52, v52, v52 row_half_mirror row_mask:0xf bank_mask:0xf
	s_nop 1
	v_add_f32_dpp v52, v52, v52 row_mirror row_mask:0xf bank_mask:0xf
	ds_swizzle_b32 v53, v52 offset:swizzle(SWAP,16)
	v_fma_f32 v159, v112, v149, -v154
	v_fmac_f32_e32 v158, v159, v159
	v_fma_f32 v149, v128, v149, -v155
	v_fmac_f32_e32 v158, v149, v149
	s_nop 1
	v_add_f32_dpp v154, v158, v158 quad_perm:[1,0,3,2] row_mask:0xf bank_mask:0xf
	s_nop 1
	v_add_f32_dpp v154, v154, v154 quad_perm:[2,3,0,1] row_mask:0xf bank_mask:0xf
	s_nop 1
	v_add_f32_dpp v154, v154, v154 row_half_mirror row_mask:0xf bank_mask:0xf
	s_nop 1
	v_add_f32_dpp v154, v154, v154 row_mirror row_mask:0xf bank_mask:0xf
	ds_swizzle_b32 v155, v154 offset:swizzle(SWAP,16)
	s_waitcnt lgkmcnt(0)
	v_add_f32_e32 v10, v10, v11
	v_fmamk_f32 v10, v10, 0x3c000000, v254
	s_nop 0
	s_nop 0
	s_nop 0
	s_nop 1
	s_nop 1
	s_nop 0
	v_rsq_f32_e32 v14, v10
	s_nop 0
	v_mul_f32_e32 v11, v12, v14
	v_mul_f32_e32 v12, v13, v14
	v_mul_f32_e32 v11, v6, v11
	v_mul_f32_e32 v12, v8, v12
	v_add_u32_e32 v10, 0x11000, v4
	v_cvt_pk_bf16_f32 v12, v11, v12
	v_mov_b32_e32 v11, v3
	v_lshl_add_u64 v[10:11], v[10:11], 1, s[6:7]
	global_store_short v[10:11], v12, off offset:768
	v_add_u32_e32 v10, 0x11020, v4
	v_mov_b32_e32 v11, v3
	v_lshl_add_u64 v[10:11], v[10:11], 1, s[6:7]
	global_store_short_d16_hi v[10:11], v12, off offset:768
	v_mul_f32_e32 v10, v15, v14
	v_mul_f32_e32 v5, v5, v14
	v_mul_f32_e32 v10, v2, v10
	v_mul_f32_e32 v5, v7, v5
	v_cvt_pk_bf16_f32 v5, v10, v5
	v_add_u32_e32 v10, 0x11040, v4
	v_mov_b32_e32 v11, v3
	v_lshl_add_u64 v[10:11], v[10:11], 1, s[6:7]
	global_store_short v[10:11], v5, off offset:768
	v_add_u32_e32 v10, 0x11060, v4
	v_mov_b32_e32 v11, v3
	v_lshl_add_u64 v[10:11], v[10:11], 1, s[6:7]
	global_store_short_d16_hi v[10:11], v5, off offset:768
	v_add_f32_e32 v40, v40, v41
	v_fmamk_f32 v40, v40, 0x3c000000, v254
	s_nop 0
	s_nop 0
	s_nop 0
	s_nop 1
	s_nop 1
	s_nop 0
	v_rsq_f32_e32 v44, v40
	s_nop 0
	v_mul_f32_e32 v41, v42, v44
	v_mul_f32_e32 v42, v43, v44
	v_mul_f32_e32 v41, v6, v41
	v_mul_f32_e32 v42, v8, v42
	v_add_u32_e32 v40, 0x12000, v4
	v_cvt_pk_bf16_f32 v42, v41, v42
	v_mov_b32_e32 v41, v3
	v_lshl_add_u64 v[40:41], v[40:41], 1, s[6:7]
	global_store_short v[40:41], v42, off offset:768
	v_add_u32_e32 v40, 0x12020, v4
	v_mov_b32_e32 v41, v3
	v_lshl_add_u64 v[40:41], v[40:41], 1, s[6:7]
	global_store_short_d16_hi v[40:41], v42, off offset:768
	v_mul_f32_e32 v40, v45, v44
	v_mul_f32_e32 v35, v35, v44
	v_mul_f32_e32 v40, v2, v40
	v_mul_f32_e32 v35, v7, v35
	v_cvt_pk_bf16_f32 v35, v40, v35
	v_add_u32_e32 v40, 0x12040, v4
	v_mov_b32_e32 v41, v3
	v_lshl_add_u64 v[40:41], v[40:41], 1, s[6:7]
	global_store_short v[40:41], v35, off offset:768
	v_add_u32_e32 v40, 0x12060, v4
	v_mov_b32_e32 v41, v3
	v_lshl_add_u64 v[40:41], v[40:41], 1, s[6:7]
	global_store_short_d16_hi v[40:41], v35, off offset:768
	v_add_f32_e32 v52, v52, v53
	v_fmamk_f32 v52, v52, 0x3c000000, v254
	s_nop 0
	s_nop 0
	s_nop 0
	s_nop 1
	s_nop 1
	s_nop 0
	v_rsq_f32_e32 v56, v52
	s_nop 0
	v_mul_f32_e32 v53, v54, v56
	v_mul_f32_e32 v54, v55, v56
	v_mul_f32_e32 v53, v6, v53
	v_mul_f32_e32 v54, v8, v54
	v_add_u32_e32 v52, 0x13000, v4
	v_cvt_pk_bf16_f32 v54, v53, v54
	v_mov_b32_e32 v53, v3
	v_lshl_add_u64 v[52:53], v[52:53], 1, s[6:7]
	global_store_short v[52:53], v54, off offset:768
	v_add_u32_e32 v52, 0x13020, v4
	v_mov_b32_e32 v53, v3
	v_lshl_add_u64 v[52:53], v[52:53], 1, s[6:7]
	global_store_short_d16_hi v[52:53], v54, off offset:768
	v_mul_f32_e32 v52, v57, v56
	v_mul_f32_e32 v47, v47, v56
	v_mul_f32_e32 v52, v2, v52
	v_mul_f32_e32 v47, v7, v47
	v_cvt_pk_bf16_f32 v47, v52, v47
	v_add_u32_e32 v52, 0x13040, v4
	v_mov_b32_e32 v53, v3
	v_lshl_add_u64 v[52:53], v[52:53], 1, s[6:7]
	global_store_short v[52:53], v47, off offset:768
	v_add_u32_e32 v52, 0x13060, v4
	v_mov_b32_e32 v53, v3
	v_lshl_add_u64 v[52:53], v[52:53], 1, s[6:7]
	global_store_short_d16_hi v[52:53], v47, off offset:768
	v_add_f32_e32 v154, v154, v155
	v_fmamk_f32 v154, v154, 0x3c000000, v254
	s_nop 0
	s_nop 0
	s_nop 0
	s_nop 1
	s_nop 1
	s_nop 0
	v_rsq_f32_e32 v158, v154
	s_nop 0
	v_mul_f32_e32 v155, v156, v158
	v_mul_f32_e32 v156, v157, v158
	v_mul_f32_e32 v155, v6, v155
	v_mul_f32_e32 v156, v8, v156
	v_add_u32_e32 v154, 0x18000, v4
	v_cvt_pk_bf16_f32 v156, v155, v156
	v_mov_b32_e32 v155, v3
	v_lshl_add_u64 v[154:155], v[154:155], 1, s[6:7]
	global_store_short v[154:155], v156, off offset:768
	v_add_u32_e32 v154, 0x18020, v4
	v_mov_b32_e32 v155, v3
	v_lshl_add_u64 v[154:155], v[154:155], 1, s[6:7]
	global_store_short_d16_hi v[154:155], v156, off offset:768
	v_mul_f32_e32 v154, v159, v158
	v_mul_f32_e32 v149, v149, v158
	v_mul_f32_e32 v154, v2, v154
	v_mul_f32_e32 v149, v7, v149
	v_cvt_pk_bf16_f32 v149, v154, v149
	v_add_u32_e32 v154, 0x18040, v4
	v_mov_b32_e32 v155, v3
	v_lshl_add_u64 v[154:155], v[154:155], 1, s[6:7]
	global_store_short v[154:155], v149, off offset:768
	v_add_u32_e32 v154, 0x18060, v4
	v_mov_b32_e32 v155, v3
	v_lshl_add_u64 v[154:155], v[154:155], 1, s[6:7]
	global_store_short_d16_hi v[154:155], v149, off offset:768
	ds_read_b32 v5, v9 offset:100
	ds_read2st64_b32 v[10:11], v1 offset0:13 offset1:29
	s_waitcnt lgkmcnt(0)
	v_fma_f32 v12, v81, v5, -v10
	v_fma_f32 v13, v97, v5, -v11
	ds_read2st64_b32 v[10:11], v1 offset0:45 offset1:61
	v_mul_f32_e32 v14, v13, v13
	v_fmac_f32_e32 v14, v12, v12
	s_waitcnt lgkmcnt(0)
	v_fma_f32 v15, v113, v5, -v10
	v_fmac_f32_e32 v14, v15, v15
	v_fma_f32 v5, v129, v5, -v11
	v_fmac_f32_e32 v14, v5, v5
	s_nop 1
	v_add_f32_dpp v10, v14, v14 quad_perm:[1,0,3,2] row_mask:0xf bank_mask:0xf
	s_nop 1
	v_add_f32_dpp v10, v10, v10 quad_perm:[2,3,0,1] row_mask:0xf bank_mask:0xf
	s_nop 1
	v_add_f32_dpp v10, v10, v10 row_half_mirror row_mask:0xf bank_mask:0xf
	s_nop 1
	v_add_f32_dpp v10, v10, v10 row_mirror row_mask:0xf bank_mask:0xf
	ds_swizzle_b32 v11, v10 offset:swizzle(SWAP,16)
	s_waitcnt lgkmcnt(0)
	v_add_f32_e32 v10, v10, v11
	v_fmamk_f32 v10, v10, 0x3c000000, v254
	s_nop 0
	s_nop 0
	s_nop 0
	s_nop 1
	s_nop 1
	s_nop 0
	v_rsq_f32_e32 v14, v10
	s_nop 0
	v_mul_f32_e32 v11, v12, v14
	v_mul_f32_e32 v12, v13, v14
	v_mul_f32_e32 v11, v6, v11
	v_mul_f32_e32 v12, v8, v12
	v_add_u32_e32 v10, 0x19000, v4
	v_cvt_pk_bf16_f32 v12, v11, v12
	v_mov_b32_e32 v11, v3
	v_lshl_add_u64 v[10:11], v[10:11], 1, s[6:7]
	global_store_short v[10:11], v12, off offset:768
	v_add_u32_e32 v10, 0x19020, v4
	v_mov_b32_e32 v11, v3
	v_lshl_add_u64 v[10:11], v[10:11], 1, s[6:7]
	global_store_short_d16_hi v[10:11], v12, off offset:768
	v_mul_f32_e32 v10, v15, v14
	v_mul_f32_e32 v5, v5, v14
	v_mul_f32_e32 v10, v2, v10
	v_mul_f32_e32 v5, v7, v5
	v_cvt_pk_bf16_f32 v5, v10, v5
	v_add_u32_e32 v10, 0x19040, v4
	v_mov_b32_e32 v11, v3
	v_lshl_add_u64 v[10:11], v[10:11], 1, s[6:7]
	global_store_short v[10:11], v5, off offset:768
	v_add_u32_e32 v10, 0x19060, v4
	v_mov_b32_e32 v11, v3
	v_lshl_add_u64 v[10:11], v[10:11], 1, s[6:7]
	global_store_short_d16_hi v[10:11], v5, off offset:768
	ds_read_b32 v5, v9 offset:104
	ds_read2st64_b32 v[10:11], v1 offset0:14 offset1:30
	s_waitcnt lgkmcnt(0)
	v_fma_f32 v12, v82, v5, -v10
	v_fma_f32 v13, v98, v5, -v11
	ds_read2st64_b32 v[10:11], v1 offset0:46 offset1:62
	v_mul_f32_e32 v14, v13, v13
	v_fmac_f32_e32 v14, v12, v12
	s_waitcnt lgkmcnt(0)
	v_fma_f32 v15, v114, v5, -v10
	v_fmac_f32_e32 v14, v15, v15
	v_fma_f32 v5, v130, v5, -v11
	v_fmac_f32_e32 v14, v5, v5
	s_nop 1
	v_add_f32_dpp v10, v14, v14 quad_perm:[1,0,3,2] row_mask:0xf bank_mask:0xf
	s_nop 1
	v_add_f32_dpp v10, v10, v10 quad_perm:[2,3,0,1] row_mask:0xf bank_mask:0xf
	s_nop 1
	v_add_f32_dpp v10, v10, v10 row_half_mirror row_mask:0xf bank_mask:0xf
	s_nop 1
	v_add_f32_dpp v10, v10, v10 row_mirror row_mask:0xf bank_mask:0xf
	ds_swizzle_b32 v11, v10 offset:swizzle(SWAP,16)
	s_waitcnt lgkmcnt(0)
	v_add_f32_e32 v10, v10, v11
	v_fmamk_f32 v10, v10, 0x3c000000, v254
	v_cmp_gt_f32_e32 vcc, s90, v10
	v_mul_f32_e32 v11, 0x4f800000, v10
	s_nop 0
	v_cndmask_b32_e32 v10, v10, v11, vcc
	v_sqrt_f32_e32 v11, v10
	s_nop 0
	v_add_u32_e32 v14, -1, v11
	v_fma_f32 v16, -v14, v11, v10
	v_cmp_ge_f32_e64 s[4:5], 0, v16
	v_add_u32_e32 v16, 1, v11
	s_nop 0
	v_cndmask_b32_e64 v14, v11, v14, s[4:5]
	v_fma_f32 v11, -v16, v11, v10
	v_cmp_lt_f32_e64 s[4:5], 0, v11
	s_nop 1
	v_cndmask_b32_e64 v11, v14, v16, s[4:5]
	v_mul_f32_e32 v14, 0x37800000, v11
	v_cndmask_b32_e32 v11, v11, v14, vcc
	v_cmp_class_f32_e32 vcc, v10, v209
	s_nop 1
	v_cndmask_b32_e32 v10, v11, v10, vcc
	v_div_scale_f32 v11, s[4:5], v10, v10, 1.0
	v_rcp_f32_e32 v14, v11
	s_nop 0
	v_fma_f32 v16, -v11, v14, 1.0
	v_fmac_f32_e32 v14, v16, v14
	v_div_scale_f32 v16, vcc, 1.0, v10, 1.0
	v_mul_f32_e32 v17, v16, v14
	v_fma_f32 v18, -v11, v17, v16
	v_fmac_f32_e32 v17, v18, v14
	v_fma_f32 v11, -v11, v17, v16
	v_div_fmas_f32 v11, v11, v14, v17
	v_div_fixup_f32 v14, v11, v10, 1.0
	v_mul_f32_e32 v11, v12, v14
	v_mul_f32_e32 v12, v13, v14
	v_mul_f32_e32 v11, v6, v11
	v_mul_f32_e32 v12, v8, v12
	v_add_u32_e32 v10, 0x1a000, v4
	v_cvt_pk_bf16_f32 v12, v11, v12
	v_mov_b32_e32 v11, v3
	v_lshl_add_u64 v[10:11], v[10:11], 1, s[6:7]
	global_store_short v[10:11], v12, off offset:768
	v_add_u32_e32 v10, 0x1a020, v4
	v_mov_b32_e32 v11, v3
	v_lshl_add_u64 v[10:11], v[10:11], 1, s[6:7]
	global_store_short_d16_hi v[10:11], v12, off offset:768
	v_mul_f32_e32 v10, v15, v14
	v_mul_f32_e32 v5, v5, v14
	v_mul_f32_e32 v10, v2, v10
	v_mul_f32_e32 v5, v7, v5
	v_cvt_pk_bf16_f32 v5, v10, v5
	v_add_u32_e32 v10, 0x1a040, v4
	v_mov_b32_e32 v11, v3
	v_lshl_add_u64 v[10:11], v[10:11], 1, s[6:7]
	global_store_short v[10:11], v5, off offset:768
	v_add_u32_e32 v10, 0x1a060, v4
	v_mov_b32_e32 v11, v3
	v_lshl_add_u64 v[10:11], v[10:11], 1, s[6:7]
	global_store_short_d16_hi v[10:11], v5, off offset:768
	ds_read_b32 v5, v9 offset:108
	ds_read2st64_b32 v[10:11], v1 offset0:15 offset1:31
	s_waitcnt lgkmcnt(0)
	v_fma_f32 v9, v83, v5, -v10
	v_fma_f32 v12, v99, v5, -v11
	ds_read2st64_b32 v[10:11], v1 offset0:47 offset1:63
	v_mul_f32_e32 v13, v12, v12
	v_fmac_f32_e32 v13, v9, v9
	s_waitcnt lgkmcnt(0)
	v_fma_f32 v1, v115, v5, -v10
	v_fmac_f32_e32 v13, v1, v1
	v_fma_f32 v5, v131, v5, -v11
	v_fmac_f32_e32 v13, v5, v5
	s_nop 1
	v_add_f32_dpp v10, v13, v13 quad_perm:[1,0,3,2] row_mask:0xf bank_mask:0xf
	s_nop 1
	v_add_f32_dpp v10, v10, v10 quad_perm:[2,3,0,1] row_mask:0xf bank_mask:0xf
	s_nop 1
	v_add_f32_dpp v10, v10, v10 row_half_mirror row_mask:0xf bank_mask:0xf
	s_nop 1
	v_add_f32_dpp v10, v10, v10 row_mirror row_mask:0xf bank_mask:0xf
	ds_swizzle_b32 v11, v10 offset:swizzle(SWAP,16)
	s_waitcnt lgkmcnt(0)
	v_add_f32_e32 v10, v10, v11
	v_fmamk_f32 v10, v10, 0x3c000000, v254
	v_cmp_gt_f32_e32 vcc, s90, v10
	v_mul_f32_e32 v11, 0x4f800000, v10
	s_nop 0
	v_cndmask_b32_e32 v10, v10, v11, vcc
	v_sqrt_f32_e32 v11, v10
	s_nop 0
	v_add_u32_e32 v13, -1, v11
	v_fma_f32 v14, -v13, v11, v10
	v_cmp_ge_f32_e64 s[4:5], 0, v14
	v_add_u32_e32 v14, 1, v11
	s_nop 0
	v_cndmask_b32_e64 v13, v11, v13, s[4:5]
	v_fma_f32 v11, -v14, v11, v10
	v_cmp_lt_f32_e64 s[4:5], 0, v11
	s_nop 1
	v_cndmask_b32_e64 v11, v13, v14, s[4:5]
	v_mul_f32_e32 v13, 0x37800000, v11
	v_cndmask_b32_e32 v11, v11, v13, vcc
	v_cmp_class_f32_e32 vcc, v10, v209
	s_nop 1
	v_cndmask_b32_e32 v10, v11, v10, vcc
	v_div_scale_f32 v11, s[4:5], v10, v10, 1.0
	v_rcp_f32_e32 v13, v11
	s_nop 0
	v_fma_f32 v14, -v11, v13, 1.0
	v_fmac_f32_e32 v13, v14, v13
	v_div_scale_f32 v14, vcc, 1.0, v10, 1.0
	v_mul_f32_e32 v15, v14, v13
	v_fma_f32 v16, -v11, v15, v14
	v_fmac_f32_e32 v15, v16, v13
	v_fma_f32 v11, -v11, v15, v14
	v_div_fmas_f32 v11, v11, v13, v15
	v_div_fixup_f32 v13, v11, v10, 1.0
	v_mul_f32_e32 v9, v9, v13
	v_mul_f32_e32 v6, v6, v9
	v_mul_f32_e32 v9, v12, v13
	v_add_u32_e32 v10, 0x1b000, v4
	v_mul_f32_e32 v8, v8, v9
	v_mov_b32_e32 v11, v3
	v_cvt_pk_bf16_f32 v6, v6, v8
	v_lshl_add_u64 v[8:9], v[10:11], 1, s[6:7]
	global_store_short v[8:9], v6, off offset:768
	v_add_u32_e32 v8, 0x1b020, v4
	v_mov_b32_e32 v9, v3
	v_mul_f32_e32 v1, v1, v13
	v_lshl_add_u64 v[8:9], v[8:9], 1, s[6:7]
	v_mul_f32_e32 v1, v2, v1
	v_mul_f32_e32 v2, v5, v13
	global_store_short_d16_hi v[8:9], v6, off offset:768
	v_mul_f32_e32 v2, v7, v2
	v_add_u32_e32 v6, 0x1b040, v4
	v_mov_b32_e32 v7, v3
	v_add_u32_e32 v4, 0x1b060, v4
	v_mov_b32_e32 v5, v3
	v_lshl_add_u64 v[6:7], v[6:7], 1, s[6:7]
	v_lshl_add_u64 v[4:5], v[4:5], 1, s[6:7]
	v_cvt_pk_bf16_f32 v1, v1, v2
	global_store_short v[6:7], v1, off offset:768
	global_store_short_d16_hi v[4:5], v1, off offset:768

.LBB0_1426:
	s_or_b64 exec, exec, s[4:5]
	s_waitcnt lgkmcnt(0)
	v_lshlrev_b32_e32 v68, 2, v1
	global_load_dword v248, v68, s[0:1]
	global_load_dword v249, v68, s[0:1] offset:128
	global_load_dword v250, v68, s[0:1] offset:256
	global_load_dword v251, v68, s[0:1] offset:384
	s_or_b32 s24, s24, s35
	s_lshl_b64 s[4:5], s[24:25], 13
	s_add_u32 s6, s86, s4
	s_addc_u32 s7, s87, s5
	s_lshl_b64 s[4:5], s[46:47], 1
	s_add_u32 s6, s6, s4
	s_addc_u32 s7, s7, s5
	s_waitcnt vmcnt(0)
	v_mul_f32_e32 v72, v164, v248
	v_mul_f32_e32 v74, v164, v249
	v_mul_f32_e32 v71, v164, v250
	v_mul_f32_e32 v73, v164, v251
	v_lshl_or_b32 v68, v2, 14, v1
	v_lshl_add_u32 v1, v2, 4, s34
	ds_read_b32 v2, v1
	ds_read2st64_b32 v[76:77], v70 offset1:16
	s_waitcnt lgkmcnt(0)
	v_fma_f32 v52, v52, v2, -v76
	v_fma_f32 v36, v36, v2, -v77
	ds_read2st64_b32 v[76:77], v70 offset0:32 offset1:48
	v_mul_f32_e32 v69, v36, v36
	v_fmac_f32_e32 v69, v52, v52
	s_waitcnt lgkmcnt(0)
	v_fma_f32 v20, v20, v2, -v76
	v_fmac_f32_e32 v69, v20, v20
	v_fma_f32 v2, v4, v2, -v77
	v_fmac_f32_e32 v69, v2, v2
	s_nop 1
	v_add_f32_dpp v4, v69, v69 quad_perm:[1,0,3,2] row_mask:0xf bank_mask:0xf
	s_nop 1
	v_add_f32_dpp v4, v4, v4 quad_perm:[2,3,0,1] row_mask:0xf bank_mask:0xf
	s_nop 1
	v_add_f32_dpp v4, v4, v4 row_half_mirror row_mask:0xf bank_mask:0xf
	s_nop 1
	v_add_f32_dpp v4, v4, v4 row_mirror row_mask:0xf bank_mask:0xf
	ds_swizzle_b32 v69, v4 offset:swizzle(SWAP,16)
	s_waitcnt lgkmcnt(0)
	v_add_f32_e32 v4, v4, v69
	v_fmamk_f32 v4, v4, 0x3c000000, v254
	v_cmp_gt_f32_e32 vcc, s90, v4
	v_mul_f32_e32 v69, 0x4f800000, v4
	s_nop 0
	v_cndmask_b32_e32 v4, v4, v69, vcc
	v_sqrt_f32_e32 v69, v4
	s_nop 0
	v_add_u32_e32 v75, -1, v69
	v_fma_f32 v76, -v75, v69, v4
	v_cmp_ge_f32_e64 s[4:5], 0, v76
	v_add_u32_e32 v76, 1, v69
	s_nop 0
	v_cndmask_b32_e64 v75, v69, v75, s[4:5]
	v_fma_f32 v69, -v76, v69, v4
	v_cmp_lt_f32_e64 s[4:5], 0, v69
	s_nop 1
	v_cndmask_b32_e64 v69, v75, v76, s[4:5]
	v_mul_f32_e32 v75, 0x37800000, v69
	v_cndmask_b32_e32 v69, v69, v75, vcc
	v_cmp_class_f32_e32 vcc, v4, v209
	s_nop 1
	v_cndmask_b32_e32 v4, v69, v4, vcc
	v_div_scale_f32 v69, s[4:5], v4, v4, 1.0
	v_rcp_f32_e32 v75, v69
	s_nop 0
	v_fma_f32 v76, -v69, v75, 1.0
	v_fmac_f32_e32 v75, v76, v75
	v_div_scale_f32 v76, vcc, 1.0, v4, 1.0
	v_mul_f32_e32 v77, v76, v75
	v_fma_f32 v78, -v69, v77, v76
	v_fmac_f32_e32 v77, v78, v75
	v_fma_f32 v69, -v69, v77, v76
	v_div_fmas_f32 v69, v69, v75, v77
	v_div_fixup_f32 v4, v69, v4, 1.0
	v_mul_f32_e32 v36, v36, v4
	v_mov_b32_e32 v69, v3
	v_mul_f32_e32 v52, v52, v4
	v_mul_f32_e32 v36, v74, v36
	v_lshl_add_u64 v[76:77], v[68:69], 1, s[6:7]
	v_mul_f32_e32 v52, v72, v52
	v_cvt_pk_bf16_f32 v36, v52, v36
	global_store_short v[76:77], v36, off
	v_add_u32_e32 v76, 32, v68
	v_mov_b32_e32 v77, v3
	v_lshl_add_u64 v[76:77], v[76:77], 1, s[6:7]
	global_store_short_d16_hi v[76:77], v36, off
	v_mul_f32_e32 v2, v2, v4
	v_add_u32_e32 v76, 64, v68
	v_mov_b32_e32 v77, v3
	v_mul_f32_e32 v20, v20, v4
	v_mul_f32_e32 v2, v73, v2
	v_lshl_add_u64 v[76:77], v[76:77], 1, s[6:7]
	v_mul_f32_e32 v20, v71, v20
	v_cvt_pk_bf16_f32 v2, v20, v2
	global_store_short v[76:77], v2, off
	v_add_u32_e32 v76, 0x60, v68
	v_mov_b32_e32 v77, v3
	v_lshl_add_u64 v[76:77], v[76:77], 1, s[6:7]
	global_store_short_d16_hi v[76:77], v2, off
	ds_read_b32 v2, v1 offset:4
	ds_read2st64_b32 v[76:77], v70 offset0:1 offset1:17
	s_waitcnt lgkmcnt(0)
	v_fma_f32 v52, v37, v2, -v77
	ds_read2st64_b32 v[36:37], v70 offset0:33 offset1:49
	v_fma_f32 v20, v53, v2, -v76
	v_mul_f32_e32 v4, v52, v52
	v_fmac_f32_e32 v4, v20, v20
	s_waitcnt lgkmcnt(0)
	v_fma_f32 v21, v21, v2, -v36
	v_fmac_f32_e32 v4, v21, v21
	v_fma_f32 v2, v5, v2, -v37
	v_fmac_f32_e32 v4, v2, v2
	ds_swizzle_b32 v5, v4 offset:swizzle(SWAP,1)
	s_waitcnt lgkmcnt(0)
	v_add_f32_e32 v4, v4, v5
	ds_swizzle_b32 v5, v4 offset:swizzle(SWAP,2)
	s_waitcnt lgkmcnt(0)
	v_add_f32_e32 v4, v4, v5
	ds_swizzle_b32 v5, v4 offset:swizzle(SWAP,4)
	s_waitcnt lgkmcnt(0)
	v_add_f32_e32 v4, v4, v5
	ds_swizzle_b32 v5, v4 offset:swizzle(SWAP,8)
	s_waitcnt lgkmcnt(0)
	v_add_f32_e32 v4, v4, v5
	ds_swizzle_b32 v5, v4 offset:swizzle(SWAP,16)
	s_waitcnt lgkmcnt(0)
	v_add_f32_e32 v4, v4, v5
	v_fmamk_f32 v4, v4, 0x3c000000, v254
	v_cmp_gt_f32_e32 vcc, s90, v4
	v_mul_f32_e32 v5, 0x4f800000, v4
	s_nop 0
	v_cndmask_b32_e32 v4, v4, v5, vcc
	v_sqrt_f32_e32 v5, v4
	s_nop 0
	v_add_u32_e32 v36, -1, v5
	v_fma_f32 v37, -v36, v5, v4
	v_cmp_ge_f32_e64 s[4:5], 0, v37
	v_add_u32_e32 v37, 1, v5
	s_nop 0
	v_cndmask_b32_e64 v36, v5, v36, s[4:5]
	v_fma_f32 v5, -v37, v5, v4
	v_cmp_lt_f32_e64 s[4:5], 0, v5
	s_nop 1
	v_cndmask_b32_e64 v5, v36, v37, s[4:5]
	v_mul_f32_e32 v36, 0x37800000, v5
	v_cndmask_b32_e32 v5, v5, v36, vcc
	v_cmp_class_f32_e32 vcc, v4, v209
	s_nop 1
	v_cndmask_b32_e32 v4, v5, v4, vcc
	v_div_scale_f32 v5, s[4:5], v4, v4, 1.0
	v_rcp_f32_e32 v36, v5
	s_nop 0
	v_fma_f32 v37, -v5, v36, 1.0
	v_fmac_f32_e32 v36, v37, v36
	v_div_scale_f32 v37, vcc, 1.0, v4, 1.0
	v_mul_f32_e32 v53, v37, v36
	v_fma_f32 v69, -v5, v53, v37
	v_fmac_f32_e32 v53, v69, v36
	v_fma_f32 v5, -v5, v53, v37
	v_div_fmas_f32 v5, v5, v36, v53
	v_div_fixup_f32 v36, v5, v4, 1.0
	v_mul_f32_e32 v5, v20, v36
	v_mul_f32_e32 v20, v52, v36
	v_mul_f32_e32 v5, v72, v5
	v_mul_f32_e32 v20, v74, v20
	v_add_u32_e32 v4, 0x1000, v68
	v_cvt_pk_bf16_f32 v20, v5, v20
	v_mov_b32_e32 v5, v3
	v_lshl_add_u64 v[4:5], v[4:5], 1, s[6:7]
	global_store_short v[4:5], v20, off
	v_add_u32_e32 v4, 0x1020, v68
	v_mov_b32_e32 v5, v3
	v_lshl_add_u64 v[4:5], v[4:5], 1, s[6:7]
	global_store_short_d16_hi v[4:5], v20, off
	v_mul_f32_e32 v4, v21, v36
	v_mul_f32_e32 v2, v2, v36
	v_mul_f32_e32 v4, v71, v4
	v_mul_f32_e32 v2, v73, v2
	v_cvt_pk_bf16_f32 v2, v4, v2
	v_add_u32_e32 v4, 0x1040, v68
	v_mov_b32_e32 v5, v3
	v_lshl_add_u64 v[4:5], v[4:5], 1, s[6:7]
	global_store_short v[4:5], v2, off
	v_add_u32_e32 v4, 0x1060, v68
	v_mov_b32_e32 v5, v3
	v_lshl_add_u64 v[4:5], v[4:5], 1, s[6:7]
	global_store_short_d16_hi v[4:5], v2, off
	ds_read_b32 v2, v1 offset:8
	ds_read2st64_b32 v[4:5], v70 offset0:2 offset1:18
	s_waitcnt lgkmcnt(0)
	v_fma_f32 v20, v54, v2, -v4
	v_fma_f32 v21, v38, v2, -v5
	ds_read2st64_b32 v[4:5], v70 offset0:34 offset1:50
	v_mul_f32_e32 v36, v21, v21
	v_fmac_f32_e32 v36, v20, v20
	s_waitcnt lgkmcnt(0)
	v_fma_f32 v22, v22, v2, -v4
	v_fmac_f32_e32 v36, v22, v22
	v_fma_f32 v2, v6, v2, -v5
	v_fmac_f32_e32 v36, v2, v2
	s_nop 1
	v_add_f32_dpp v4, v36, v36 quad_perm:[1,0,3,2] row_mask:0xf bank_mask:0xf
	s_nop 1
	v_add_f32_dpp v4, v4, v4 quad_perm:[2,3,0,1] row_mask:0xf bank_mask:0xf
	s_nop 1
	v_add_f32_dpp v4, v4, v4 row_half_mirror row_mask:0xf bank_mask:0xf
	s_nop 1
	v_add_f32_dpp v4, v4, v4 row_mirror row_mask:0xf bank_mask:0xf
	ds_swizzle_b32 v5, v4 offset:swizzle(SWAP,16)
	s_waitcnt lgkmcnt(0)
	v_add_f32_e32 v4, v4, v5
	v_fmamk_f32 v4, v4, 0x3c000000, v254
	s_nop 0
	s_nop 0
	s_nop 0
	s_nop 1
	s_nop 1
	s_nop 0
	v_rsq_f32_e32 v6, v4
	s_nop 0
	v_mul_f32_e32 v5, v20, v6
	v_mul_f32_e32 v20, v21, v6
	v_mul_f32_e32 v5, v72, v5
	v_mul_f32_e32 v20, v74, v20
	v_add_u32_e32 v4, 0x2000, v68
	v_cvt_pk_bf16_f32 v20, v5, v20
	v_mov_b32_e32 v5, v3
	v_lshl_add_u64 v[4:5], v[4:5], 1, s[6:7]
	global_store_short v[4:5], v20, off
	v_add_u32_e32 v4, 0x2020, v68
	v_mov_b32_e32 v5, v3
	v_lshl_add_u64 v[4:5], v[4:5], 1, s[6:7]
	global_store_short_d16_hi v[4:5], v20, off
	v_mul_f32_e32 v4, v22, v6
	v_mul_f32_e32 v2, v2, v6
	v_mul_f32_e32 v4, v71, v4
	v_mul_f32_e32 v2, v73, v2
	v_cvt_pk_bf16_f32 v2, v4, v2
	v_add_u32_e32 v4, 0x2040, v68
	v_mov_b32_e32 v5, v3
	v_lshl_add_u64 v[4:5], v[4:5], 1, s[6:7]
	global_store_short v[4:5], v2, off
	v_add_u32_e32 v4, 0x2060, v68
	v_mov_b32_e32 v5, v3
	v_lshl_add_u64 v[4:5], v[4:5], 1, s[6:7]
	global_store_short_d16_hi v[4:5], v2, off
	ds_read_b32 v2, v1 offset:12
	ds_read2st64_b32 v[4:5], v70 offset0:3 offset1:19
	s_waitcnt lgkmcnt(0)
	v_fma_f32 v6, v55, v2, -v4
	v_fma_f32 v20, v39, v2, -v5
	ds_read2st64_b32 v[4:5], v70 offset0:35 offset1:51
	v_mul_f32_e32 v21, v20, v20
	v_fmac_f32_e32 v21, v6, v6
	s_waitcnt lgkmcnt(0)
	v_fma_f32 v22, v23, v2, -v4
	v_fmac_f32_e32 v21, v22, v22
	v_fma_f32 v2, v7, v2, -v5
	v_fmac_f32_e32 v21, v2, v2
	s_nop 1
	v_add_f32_dpp v4, v21, v21 quad_perm:[1,0,3,2] row_mask:0xf bank_mask:0xf
	s_nop 1
	v_add_f32_dpp v4, v4, v4 quad_perm:[2,3,0,1] row_mask:0xf bank_mask:0xf
	s_nop 1
	v_add_f32_dpp v4, v4, v4 row_half_mirror row_mask:0xf bank_mask:0xf
	s_nop 1
	v_add_f32_dpp v4, v4, v4 row_mirror row_mask:0xf bank_mask:0xf
	ds_swizzle_b32 v5, v4 offset:swizzle(SWAP,16)
	s_waitcnt lgkmcnt(0)
	v_add_f32_e32 v4, v4, v5
	v_fmamk_f32 v4, v4, 0x3c000000, v254
	s_nop 0
	s_nop 0
	s_nop 0
	s_nop 1
	s_nop 1
	s_nop 0
	v_rsq_f32_e32 v7, v4
	s_nop 0
	v_mul_f32_e32 v5, v6, v7
	v_mul_f32_e32 v6, v20, v7
	v_mul_f32_e32 v5, v72, v5
	v_mul_f32_e32 v6, v74, v6
	v_add_u32_e32 v4, 0x3000, v68
	v_cvt_pk_bf16_f32 v6, v5, v6
	v_mov_b32_e32 v5, v3
	v_lshl_add_u64 v[4:5], v[4:5], 1, s[6:7]
	global_store_short v[4:5], v6, off
	v_add_u32_e32 v4, 0x3020, v68
	v_mov_b32_e32 v5, v3
	v_lshl_add_u64 v[4:5], v[4:5], 1, s[6:7]
	global_store_short_d16_hi v[4:5], v6, off
	v_mul_f32_e32 v4, v22, v7
	v_mul_f32_e32 v2, v2, v7
	v_mul_f32_e32 v4, v71, v4
	v_mul_f32_e32 v2, v73, v2
	v_cvt_pk_bf16_f32 v2, v4, v2
	v_add_u32_e32 v4, 0x3040, v68
	v_mov_b32_e32 v5, v3
	v_lshl_add_u64 v[4:5], v[4:5], 1, s[6:7]
	global_store_short v[4:5], v2, off
	v_add_u32_e32 v4, 0x3060, v68
	v_mov_b32_e32 v5, v3
	v_lshl_add_u64 v[4:5], v[4:5], 1, s[6:7]
	global_store_short_d16_hi v[4:5], v2, off
	ds_read_b32 v2, v1 offset:32
	ds_read2st64_b32 v[4:5], v70 offset0:4 offset1:20
	s_waitcnt lgkmcnt(0)
	v_fma_f32 v6, v56, v2, -v4
	v_fma_f32 v7, v40, v2, -v5
	ds_read2st64_b32 v[4:5], v70 offset0:36 offset1:52
	v_mul_f32_e32 v20, v7, v7
	v_fmac_f32_e32 v20, v6, v6
	s_waitcnt lgkmcnt(0)
	v_fma_f32 v21, v24, v2, -v4
	v_fmac_f32_e32 v20, v21, v21
	v_fma_f32 v2, v8, v2, -v5
	v_fmac_f32_e32 v20, v2, v2
	s_nop 1
	v_add_f32_dpp v4, v20, v20 quad_perm:[1,0,3,2] row_mask:0xf bank_mask:0xf
	s_nop 1
	v_add_f32_dpp v4, v4, v4 quad_perm:[2,3,0,1] row_mask:0xf bank_mask:0xf
	s_nop 1
	v_add_f32_dpp v4, v4, v4 row_half_mirror row_mask:0xf bank_mask:0xf
	s_nop 1
	v_add_f32_dpp v4, v4, v4 row_mirror row_mask:0xf bank_mask:0xf
	ds_swizzle_b32 v5, v4 offset:swizzle(SWAP,16)
	s_waitcnt lgkmcnt(0)
	v_add_f32_e32 v4, v4, v5
	v_fmamk_f32 v4, v4, 0x3c000000, v254
	s_nop 0
	s_nop 0
	s_nop 0
	s_nop 1
	s_nop 1
	s_nop 0
	v_rsq_f32_e32 v8, v4
	s_nop 0
	v_mul_f32_e32 v5, v6, v8
	v_mul_f32_e32 v6, v7, v8
	v_mul_f32_e32 v5, v72, v5
	v_mul_f32_e32 v6, v74, v6
	v_add_u32_e32 v4, 0x8000, v68
	v_cvt_pk_bf16_f32 v6, v5, v6
	v_mov_b32_e32 v5, v3
	v_lshl_add_u64 v[4:5], v[4:5], 1, s[6:7]
	global_store_short v[4:5], v6, off
	v_add_u32_e32 v4, 0x8020, v68
	v_mov_b32_e32 v5, v3
	v_lshl_add_u64 v[4:5], v[4:5], 1, s[6:7]
	global_store_short_d16_hi v[4:5], v6, off
	v_mul_f32_e32 v4, v21, v8
	v_mul_f32_e32 v2, v2, v8
	v_mul_f32_e32 v4, v71, v4
	v_mul_f32_e32 v2, v73, v2
	v_cvt_pk_bf16_f32 v2, v4, v2
	v_add_u32_e32 v4, 0x8040, v68
	v_mov_b32_e32 v5, v3
	v_lshl_add_u64 v[4:5], v[4:5], 1, s[6:7]
	global_store_short v[4:5], v2, off
	v_add_u32_e32 v4, 0x8060, v68
	v_mov_b32_e32 v5, v3
	v_lshl_add_u64 v[4:5], v[4:5], 1, s[6:7]
	global_store_short_d16_hi v[4:5], v2, off
	ds_read_b32 v2, v1 offset:36
	ds_read2st64_b32 v[4:5], v70 offset0:5 offset1:21
	s_waitcnt lgkmcnt(0)
	v_fma_f32 v6, v57, v2, -v4
	v_fma_f32 v7, v41, v2, -v5
	ds_read2st64_b32 v[4:5], v70 offset0:37 offset1:53
	v_mul_f32_e32 v8, v7, v7
	v_fmac_f32_e32 v8, v6, v6
	s_waitcnt lgkmcnt(0)
	v_fma_f32 v20, v25, v2, -v4
	v_fmac_f32_e32 v8, v20, v20
	v_fma_f32 v2, v9, v2, -v5
	v_fmac_f32_e32 v8, v2, v2
	s_nop 1
	v_add_f32_dpp v4, v8, v8 quad_perm:[1,0,3,2] row_mask:0xf bank_mask:0xf
	s_nop 1
	v_add_f32_dpp v4, v4, v4 quad_perm:[2,3,0,1] row_mask:0xf bank_mask:0xf
	s_nop 1
	v_add_f32_dpp v4, v4, v4 row_half_mirror row_mask:0xf bank_mask:0xf
	s_nop 1
	v_add_f32_dpp v4, v4, v4 row_mirror row_mask:0xf bank_mask:0xf
	ds_swizzle_b32 v5, v4 offset:swizzle(SWAP,16)
	s_waitcnt lgkmcnt(0)
	v_add_f32_e32 v4, v4, v5
	v_fmamk_f32 v4, v4, 0x3c000000, v254
	s_nop 0
	s_nop 0
	s_nop 0
	s_nop 1
	s_nop 1
	s_nop 0
	v_rsq_f32_e32 v8, v4
	s_nop 0
	v_mul_f32_e32 v5, v6, v8
	v_mul_f32_e32 v6, v7, v8
	v_mul_f32_e32 v5, v72, v5
	v_mul_f32_e32 v6, v74, v6
	v_add_u32_e32 v4, 0x9000, v68
	v_cvt_pk_bf16_f32 v6, v5, v6
	v_mov_b32_e32 v5, v3
	v_lshl_add_u64 v[4:5], v[4:5], 1, s[6:7]
	global_store_short v[4:5], v6, off
	v_add_u32_e32 v4, 0x9020, v68
	v_mov_b32_e32 v5, v3
	v_lshl_add_u64 v[4:5], v[4:5], 1, s[6:7]
	global_store_short_d16_hi v[4:5], v6, off
	v_mul_f32_e32 v4, v20, v8
	v_mul_f32_e32 v2, v2, v8
	v_mul_f32_e32 v4, v71, v4
	v_mul_f32_e32 v2, v73, v2
	v_cvt_pk_bf16_f32 v2, v4, v2
	v_add_u32_e32 v4, 0x9040, v68
	v_mov_b32_e32 v5, v3
	v_lshl_add_u64 v[4:5], v[4:5], 1, s[6:7]
	global_store_short v[4:5], v2, off
	v_add_u32_e32 v4, 0x9060, v68
	v_mov_b32_e32 v5, v3
	v_lshl_add_u64 v[4:5], v[4:5], 1, s[6:7]
	global_store_short_d16_hi v[4:5], v2, off
	ds_read_b32 v2, v1 offset:40
	ds_read2st64_b32 v[4:5], v70 offset0:6 offset1:22
	ds_read_b32 v84, v1 offset:44
	ds_read2st64_b32 v[86:87], v70 offset0:7 offset1:23
	ds_read_b32 v92, v1 offset:64
	ds_read2st64_b32 v[94:95], v70 offset0:8 offset1:24
	ds_read_b32 v148, v1 offset:68
	ds_read2st64_b32 v[150:151], v70 offset0:9 offset1:25
	s_waitcnt lgkmcnt(0)
	v_fma_f32 v6, v58, v2, -v4
	v_fma_f32 v7, v42, v2, -v5
	ds_read2st64_b32 v[4:5], v70 offset0:38 offset1:54
	v_mul_f32_e32 v8, v7, v7
	v_fmac_f32_e32 v8, v6, v6
	v_fma_f32 v88, v59, v84, -v86
	v_fma_f32 v89, v43, v84, -v87
	ds_read2st64_b32 v[86:87], v70 offset0:39 offset1:55
	v_mul_f32_e32 v90, v89, v89
	v_fmac_f32_e32 v90, v88, v88
	v_fma_f32 v96, v60, v92, -v94
	v_fma_f32 v97, v44, v92, -v95
	ds_read2st64_b32 v[94:95], v70 offset0:40 offset1:56
	v_mul_f32_e32 v98, v97, v97
	v_fmac_f32_e32 v98, v96, v96
	v_fma_f32 v152, v61, v148, -v150
	v_fma_f32 v153, v45, v148, -v151
	ds_read2st64_b32 v[150:151], v70 offset0:41 offset1:57
	v_mul_f32_e32 v154, v153, v153
	v_fmac_f32_e32 v154, v152, v152
	s_waitcnt lgkmcnt(0)
	v_fma_f32 v9, v26, v2, -v4
	v_fmac_f32_e32 v8, v9, v9
	v_fma_f32 v2, v10, v2, -v5
	v_fmac_f32_e32 v8, v2, v2
	s_nop 1
	v_add_f32_dpp v4, v8, v8 quad_perm:[1,0,3,2] row_mask:0xf bank_mask:0xf
	s_nop 1
	v_add_f32_dpp v4, v4, v4 quad_perm:[2,3,0,1] row_mask:0xf bank_mask:0xf
	s_nop 1
	v_add_f32_dpp v4, v4, v4 row_half_mirror row_mask:0xf bank_mask:0xf
	s_nop 1
	v_add_f32_dpp v4, v4, v4 row_mirror row_mask:0xf bank_mask:0xf
	ds_swizzle_b32 v5, v4 offset:swizzle(SWAP,16)
	v_fma_f32 v91, v27, v84, -v86
	v_fmac_f32_e32 v90, v91, v91
	v_fma_f32 v84, v11, v84, -v87
	v_fmac_f32_e32 v90, v84, v84
	s_nop 1
	v_add_f32_dpp v86, v90, v90 quad_perm:[1,0,3,2] row_mask:0xf bank_mask:0xf
	s_nop 1
	v_add_f32_dpp v86, v86, v86 quad_perm:[2,3,0,1] row_mask:0xf bank_mask:0xf
	s_nop 1
	v_add_f32_dpp v86, v86, v86 row_half_mirror row_mask:0xf bank_mask:0xf
	s_nop 1
	v_add_f32_dpp v86, v86, v86 row_mirror row_mask:0xf bank_mask:0xf
	ds_swizzle_b32 v87, v86 offset:swizzle(SWAP,16)
	v_fma_f32 v99, v28, v92, -v94
	v_fmac_f32_e32 v98, v99, v99
	v_fma_f32 v92, v12, v92, -v95
	v_fmac_f32_e32 v98, v92, v92
	s_nop 1
	v_add_f32_dpp v94, v98, v98 quad_perm:[1,0,3,2] row_mask:0xf bank_mask:0xf
	s_nop 1
	v_add_f32_dpp v94, v94, v94 quad_perm:[2,3,0,1] row_mask:0xf bank_mask:0xf
	s_nop 1
	v_add_f32_dpp v94, v94, v94 row_half_mirror row_mask:0xf bank_mask:0xf
	s_nop 1
	v_add_f32_dpp v94, v94, v94 row_mirror row_mask:0xf bank_mask:0xf
	ds_swizzle_b32 v95, v94 offset:swizzle(SWAP,16)
	v_fma_f32 v155, v29, v148, -v150
	v_fmac_f32_e32 v154, v155, v155
	v_fma_f32 v148, v13, v148, -v151
	v_fmac_f32_e32 v154, v148, v148
	s_nop 1
	v_add_f32_dpp v150, v154, v154 quad_perm:[1,0,3,2] row_mask:0xf bank_mask:0xf
	s_nop 1
	v_add_f32_dpp v150, v150, v150 quad_perm:[2,3,0,1] row_mask:0xf bank_mask:0xf
	s_nop 1
	v_add_f32_dpp v150, v150, v150 row_half_mirror row_mask:0xf bank_mask:0xf
	s_nop 1
	v_add_f32_dpp v150, v150, v150 row_mirror row_mask:0xf bank_mask:0xf
	ds_swizzle_b32 v151, v150 offset:swizzle(SWAP,16)
	s_waitcnt lgkmcnt(0)
	v_add_f32_e32 v4, v4, v5
	v_fmamk_f32 v4, v4, 0x3c000000, v254
	s_nop 0
	s_nop 0
	s_nop 0
	s_nop 1
	s_nop 1
	s_nop 0
	v_rsq_f32_e32 v8, v4
	s_nop 0
	v_mul_f32_e32 v5, v6, v8
	v_mul_f32_e32 v6, v7, v8
	v_mul_f32_e32 v5, v72, v5
	v_mul_f32_e32 v6, v74, v6
	v_add_u32_e32 v4, 0xa000, v68
	v_cvt_pk_bf16_f32 v6, v5, v6
	v_mov_b32_e32 v5, v3
	v_lshl_add_u64 v[4:5], v[4:5], 1, s[6:7]
	global_store_short v[4:5], v6, off
	v_add_u32_e32 v4, 0xa020, v68
	v_mov_b32_e32 v5, v3
	v_lshl_add_u64 v[4:5], v[4:5], 1, s[6:7]
	global_store_short_d16_hi v[4:5], v6, off
	v_mul_f32_e32 v4, v9, v8
	v_mul_f32_e32 v2, v2, v8
	v_mul_f32_e32 v4, v71, v4
	v_mul_f32_e32 v2, v73, v2
	v_cvt_pk_bf16_f32 v2, v4, v2
	v_add_u32_e32 v4, 0xa040, v68
	v_mov_b32_e32 v5, v3
	v_lshl_add_u64 v[4:5], v[4:5], 1, s[6:7]
	global_store_short v[4:5], v2, off
	v_add_u32_e32 v4, 0xa060, v68
	v_mov_b32_e32 v5, v3
	v_lshl_add_u64 v[4:5], v[4:5], 1, s[6:7]
	global_store_short_d16_hi v[4:5], v2, off
	v_add_f32_e32 v86, v86, v87
	v_fmamk_f32 v86, v86, 0x3c000000, v254
	s_nop 0
	s_nop 0
	s_nop 0
	s_nop 1
	s_nop 1
	s_nop 0
	v_rsq_f32_e32 v90, v86
	s_nop 0
	v_mul_f32_e32 v87, v88, v90
	v_mul_f32_e32 v88, v89, v90
	v_mul_f32_e32 v87, v72, v87
	v_mul_f32_e32 v88, v74, v88
	v_add_u32_e32 v86, 0xb000, v68
	v_cvt_pk_bf16_f32 v88, v87, v88
	v_mov_b32_e32 v87, v3
	v_lshl_add_u64 v[86:87], v[86:87], 1, s[6:7]
	global_store_short v[86:87], v88, off
	v_add_u32_e32 v86, 0xb020, v68
	v_mov_b32_e32 v87, v3
	v_lshl_add_u64 v[86:87], v[86:87], 1, s[6:7]
	global_store_short_d16_hi v[86:87], v88, off
	v_mul_f32_e32 v86, v91, v90
	v_mul_f32_e32 v84, v84, v90
	v_mul_f32_e32 v86, v71, v86
	v_mul_f32_e32 v84, v73, v84
	v_cvt_pk_bf16_f32 v84, v86, v84
	v_add_u32_e32 v86, 0xb040, v68
	v_mov_b32_e32 v87, v3
	v_lshl_add_u64 v[86:87], v[86:87], 1, s[6:7]
	global_store_short v[86:87], v84, off
	v_add_u32_e32 v86, 0xb060, v68
	v_mov_b32_e32 v87, v3
	v_lshl_add_u64 v[86:87], v[86:87], 1, s[6:7]
	global_store_short_d16_hi v[86:87], v84, off
	v_add_f32_e32 v94, v94, v95
	v_fmamk_f32 v94, v94, 0x3c000000, v254
	s_nop 0
	s_nop 0
	s_nop 0
	s_nop 1
	s_nop 1
	s_nop 0
	v_rsq_f32_e32 v98, v94
	s_nop 0
	v_mul_f32_e32 v95, v96, v98
	v_mul_f32_e32 v96, v97, v98
	v_mul_f32_e32 v95, v72, v95
	v_mul_f32_e32 v96, v74, v96
	v_add_u32_e32 v94, 0x10000, v68
	v_cvt_pk_bf16_f32 v96, v95, v96
	v_mov_b32_e32 v95, v3
	v_lshl_add_u64 v[94:95], v[94:95], 1, s[6:7]
	global_store_short v[94:95], v96, off
	v_add_u32_e32 v94, 0x10020, v68
	v_mov_b32_e32 v95, v3
	v_lshl_add_u64 v[94:95], v[94:95], 1, s[6:7]
	global_store_short_d16_hi v[94:95], v96, off
	v_mul_f32_e32 v94, v99, v98
	v_mul_f32_e32 v92, v92, v98
	v_mul_f32_e32 v94, v71, v94
	v_mul_f32_e32 v92, v73, v92
	v_cvt_pk_bf16_f32 v92, v94, v92
	v_add_u32_e32 v94, 0x10040, v68
	v_mov_b32_e32 v95, v3
	v_lshl_add_u64 v[94:95], v[94:95], 1, s[6:7]
	global_store_short v[94:95], v92, off
	v_add_u32_e32 v94, 0x10060, v68
	v_mov_b32_e32 v95, v3
	v_lshl_add_u64 v[94:95], v[94:95], 1, s[6:7]
	global_store_short_d16_hi v[94:95], v92, off
	v_add_f32_e32 v150, v150, v151
	v_fmamk_f32 v150, v150, 0x3c000000, v254
	s_nop 0
	s_nop 0
	s_nop 0
	s_nop 1
	s_nop 1
	s_nop 0
	v_rsq_f32_e32 v154, v150
	s_nop 0
	v_mul_f32_e32 v151, v152, v154
	v_mul_f32_e32 v152, v153, v154
	v_mul_f32_e32 v151, v72, v151
	v_mul_f32_e32 v152, v74, v152
	v_add_u32_e32 v150, 0x11000, v68
	v_cvt_pk_bf16_f32 v152, v151, v152
	v_mov_b32_e32 v151, v3
	v_lshl_add_u64 v[150:151], v[150:151], 1, s[6:7]
	global_store_short v[150:151], v152, off
	v_add_u32_e32 v150, 0x11020, v68
	v_mov_b32_e32 v151, v3
	v_lshl_add_u64 v[150:151], v[150:151], 1, s[6:7]
	global_store_short_d16_hi v[150:151], v152, off
	v_mul_f32_e32 v150, v155, v154
	v_mul_f32_e32 v148, v148, v154
	v_mul_f32_e32 v150, v71, v150
	v_mul_f32_e32 v148, v73, v148
	v_cvt_pk_bf16_f32 v148, v150, v148
	v_add_u32_e32 v150, 0x11040, v68
	v_mov_b32_e32 v151, v3
	v_lshl_add_u64 v[150:151], v[150:151], 1, s[6:7]
	global_store_short v[150:151], v148, off
	v_add_u32_e32 v150, 0x11060, v68
	v_mov_b32_e32 v151, v3
	v_lshl_add_u64 v[150:151], v[150:151], 1, s[6:7]
	global_store_short_d16_hi v[150:151], v148, off
	ds_read_b32 v2, v1 offset:72
	ds_read2st64_b32 v[4:5], v70 offset0:10 offset1:26
	ds_read_b32 v84, v1 offset:76
	ds_read2st64_b32 v[86:87], v70 offset0:11 offset1:27
	ds_read_b32 v92, v1 offset:96
	ds_read2st64_b32 v[94:95], v70 offset0:12 offset1:28
	ds_read_b32 v148, v1 offset:100
	ds_read2st64_b32 v[150:151], v70 offset0:13 offset1:29
	s_waitcnt lgkmcnt(0)
	v_fma_f32 v6, v62, v2, -v4
	v_fma_f32 v7, v46, v2, -v5
	ds_read2st64_b32 v[4:5], v70 offset0:42 offset1:58
	v_mul_f32_e32 v8, v7, v7
	v_fmac_f32_e32 v8, v6, v6
	v_fma_f32 v88, v63, v84, -v86
	v_fma_f32 v89, v47, v84, -v87
	ds_read2st64_b32 v[86:87], v70 offset0:43 offset1:59
	v_mul_f32_e32 v90, v89, v89
	v_fmac_f32_e32 v90, v88, v88
	v_fma_f32 v96, v64, v92, -v94
	v_fma_f32 v97, v48, v92, -v95
	ds_read2st64_b32 v[94:95], v70 offset0:44 offset1:60
	v_mul_f32_e32 v98, v97, v97
	v_fmac_f32_e32 v98, v96, v96
	v_fma_f32 v152, v65, v148, -v150
	v_fma_f32 v153, v49, v148, -v151
	ds_read2st64_b32 v[150:151], v70 offset0:45 offset1:61
	v_mul_f32_e32 v154, v153, v153
	v_fmac_f32_e32 v154, v152, v152
	s_waitcnt lgkmcnt(0)
	v_fma_f32 v9, v30, v2, -v4
	v_fmac_f32_e32 v8, v9, v9
	v_fma_f32 v2, v14, v2, -v5
	v_fmac_f32_e32 v8, v2, v2
	s_nop 1
	v_add_f32_dpp v4, v8, v8 quad_perm:[1,0,3,2] row_mask:0xf bank_mask:0xf
	s_nop 1
	v_add_f32_dpp v4, v4, v4 quad_perm:[2,3,0,1] row_mask:0xf bank_mask:0xf
	s_nop 1
	v_add_f32_dpp v4, v4, v4 row_half_mirror row_mask:0xf bank_mask:0xf
	s_nop 1
	v_add_f32_dpp v4, v4, v4 row_mirror row_mask:0xf bank_mask:0xf
	ds_swizzle_b32 v5, v4 offset:swizzle(SWAP,16)
	v_fma_f32 v91, v31, v84, -v86
	v_fmac_f32_e32 v90, v91, v91
	v_fma_f32 v84, v15, v84, -v87
	v_fmac_f32_e32 v90, v84, v84
	s_nop 1
	v_add_f32_dpp v86, v90, v90 quad_perm:[1,0,3,2] row_mask:0xf bank_mask:0xf
	s_nop 1
	v_add_f32_dpp v86, v86, v86 quad_perm:[2,3,0,1] row_mask:0xf bank_mask:0xf
	s_nop 1
	v_add_f32_dpp v86, v86, v86 row_half_mirror row_mask:0xf bank_mask:0xf
	s_nop 1
	v_add_f32_dpp v86, v86, v86 row_mirror row_mask:0xf bank_mask:0xf
	ds_swizzle_b32 v87, v86 offset:swizzle(SWAP,16)
	v_fma_f32 v99, v32, v92, -v94
	v_fmac_f32_e32 v98, v99, v99
	v_fma_f32 v92, v16, v92, -v95
	v_fmac_f32_e32 v98, v92, v92
	s_nop 1
	v_add_f32_dpp v94, v98, v98 quad_perm:[1,0,3,2] row_mask:0xf bank_mask:0xf
	s_nop 1
	v_add_f32_dpp v94, v94, v94 quad_perm:[2,3,0,1] row_mask:0xf bank_mask:0xf
	s_nop 1
	v_add_f32_dpp v94, v94, v94 row_half_mirror row_mask:0xf bank_mask:0xf
	s_nop 1
	v_add_f32_dpp v94, v94, v94 row_mirror row_mask:0xf bank_mask:0xf
	ds_swizzle_b32 v95, v94 offset:swizzle(SWAP,16)
	v_fma_f32 v155, v33, v148, -v150
	v_fmac_f32_e32 v154, v155, v155
	v_fma_f32 v148, v17, v148, -v151
	v_fmac_f32_e32 v154, v148, v148
	s_nop 1
	v_add_f32_dpp v150, v154, v154 quad_perm:[1,0,3,2] row_mask:0xf bank_mask:0xf
	s_nop 1
	v_add_f32_dpp v150, v150, v150 quad_perm:[2,3,0,1] row_mask:0xf bank_mask:0xf
	s_nop 1
	v_add_f32_dpp v150, v150, v150 row_half_mirror row_mask:0xf bank_mask:0xf
	s_nop 1
	v_add_f32_dpp v150, v150, v150 row_mirror row_mask:0xf bank_mask:0xf
	ds_swizzle_b32 v151, v150 offset:swizzle(SWAP,16)
	s_waitcnt lgkmcnt(0)
	v_add_f32_e32 v4, v4, v5
	v_fmamk_f32 v4, v4, 0x3c000000, v254
	s_nop 0
	s_nop 0
	s_nop 0
	s_nop 1
	s_nop 1
	s_nop 0
	v_rsq_f32_e32 v8, v4
	s_nop 0
	v_mul_f32_e32 v5, v6, v8
	v_mul_f32_e32 v6, v7, v8
	v_mul_f32_e32 v5, v72, v5
	v_mul_f32_e32 v6, v74, v6
	v_add_u32_e32 v4, 0x12000, v68
	v_cvt_pk_bf16_f32 v6, v5, v6
	v_mov_b32_e32 v5, v3
	v_lshl_add_u64 v[4:5], v[4:5], 1, s[6:7]
	global_store_short v[4:5], v6, off
	v_add_u32_e32 v4, 0x12020, v68
	v_mov_b32_e32 v5, v3
	v_lshl_add_u64 v[4:5], v[4:5], 1, s[6:7]
	global_store_short_d16_hi v[4:5], v6, off
	v_mul_f32_e32 v4, v9, v8
	v_mul_f32_e32 v2, v2, v8
	v_mul_f32_e32 v4, v71, v4
	v_mul_f32_e32 v2, v73, v2
	v_cvt_pk_bf16_f32 v2, v4, v2
	v_add_u32_e32 v4, 0x12040, v68
	v_mov_b32_e32 v5, v3
	v_lshl_add_u64 v[4:5], v[4:5], 1, s[6:7]
	global_store_short v[4:5], v2, off
	v_add_u32_e32 v4, 0x12060, v68
	v_mov_b32_e32 v5, v3
	v_lshl_add_u64 v[4:5], v[4:5], 1, s[6:7]
	global_store_short_d16_hi v[4:5], v2, off
	v_add_f32_e32 v86, v86, v87
	v_fmamk_f32 v86, v86, 0x3c000000, v254
	s_nop 0
	s_nop 0
	s_nop 0
	s_nop 1
	s_nop 1
	s_nop 0
	v_rsq_f32_e32 v90, v86
	s_nop 0
	v_mul_f32_e32 v87, v88, v90
	v_mul_f32_e32 v88, v89, v90
	v_mul_f32_e32 v87, v72, v87
	v_mul_f32_e32 v88, v74, v88
	v_add_u32_e32 v86, 0x13000, v68
	v_cvt_pk_bf16_f32 v88, v87, v88
	v_mov_b32_e32 v87, v3
	v_lshl_add_u64 v[86:87], v[86:87], 1, s[6:7]
	global_store_short v[86:87], v88, off
	v_add_u32_e32 v86, 0x13020, v68
	v_mov_b32_e32 v87, v3
	v_lshl_add_u64 v[86:87], v[86:87], 1, s[6:7]
	global_store_short_d16_hi v[86:87], v88, off
	v_mul_f32_e32 v86, v91, v90
	v_mul_f32_e32 v84, v84, v90
	v_mul_f32_e32 v86, v71, v86
	v_mul_f32_e32 v84, v73, v84
	v_cvt_pk_bf16_f32 v84, v86, v84
	v_add_u32_e32 v86, 0x13040, v68
	v_mov_b32_e32 v87, v3
	v_lshl_add_u64 v[86:87], v[86:87], 1, s[6:7]
	global_store_short v[86:87], v84, off
	v_add_u32_e32 v86, 0x13060, v68
	v_mov_b32_e32 v87, v3
	v_lshl_add_u64 v[86:87], v[86:87], 1, s[6:7]
	global_store_short_d16_hi v[86:87], v84, off
	v_add_f32_e32 v94, v94, v95
	v_fmamk_f32 v94, v94, 0x3c000000, v254
	s_nop 0
	s_nop 0
	s_nop 0
	s_nop 1
	s_nop 1
	s_nop 0
	v_rsq_f32_e32 v98, v94
	s_nop 0
	v_mul_f32_e32 v95, v96, v98
	v_mul_f32_e32 v96, v97, v98
	v_mul_f32_e32 v95, v72, v95
	v_mul_f32_e32 v96, v74, v96
	v_add_u32_e32 v94, 0x18000, v68
	v_cvt_pk_bf16_f32 v96, v95, v96
	v_mov_b32_e32 v95, v3
	v_lshl_add_u64 v[94:95], v[94:95], 1, s[6:7]
	global_store_short v[94:95], v96, off
	v_add_u32_e32 v94, 0x18020, v68
	v_mov_b32_e32 v95, v3
	v_lshl_add_u64 v[94:95], v[94:95], 1, s[6:7]
	global_store_short_d16_hi v[94:95], v96, off
	v_mul_f32_e32 v94, v99, v98
	v_mul_f32_e32 v92, v92, v98
	v_mul_f32_e32 v94, v71, v94
	v_mul_f32_e32 v92, v73, v92
	v_cvt_pk_bf16_f32 v92, v94, v92
	v_add_u32_e32 v94, 0x18040, v68
	v_mov_b32_e32 v95, v3
	v_lshl_add_u64 v[94:95], v[94:95], 1, s[6:7]
	global_store_short v[94:95], v92, off
	v_add_u32_e32 v94, 0x18060, v68
	v_mov_b32_e32 v95, v3
	v_lshl_add_u64 v[94:95], v[94:95], 1, s[6:7]
	global_store_short_d16_hi v[94:95], v92, off
	v_add_f32_e32 v150, v150, v151
	v_fmamk_f32 v150, v150, 0x3c000000, v254
	s_nop 0
	s_nop 0
	s_nop 0
	s_nop 1
	s_nop 1
	s_nop 0
	v_rsq_f32_e32 v154, v150
	s_nop 0
	v_mul_f32_e32 v151, v152, v154
	v_mul_f32_e32 v152, v153, v154
	v_mul_f32_e32 v151, v72, v151
	v_mul_f32_e32 v152, v74, v152
	v_add_u32_e32 v150, 0x19000, v68
	v_cvt_pk_bf16_f32 v152, v151, v152
	v_mov_b32_e32 v151, v3
	v_lshl_add_u64 v[150:151], v[150:151], 1, s[6:7]
	global_store_short v[150:151], v152, off
	v_add_u32_e32 v150, 0x19020, v68
	v_mov_b32_e32 v151, v3
	v_lshl_add_u64 v[150:151], v[150:151], 1, s[6:7]
	global_store_short_d16_hi v[150:151], v152, off
	v_mul_f32_e32 v150, v155, v154
	v_mul_f32_e32 v148, v148, v154
	v_mul_f32_e32 v150, v71, v150
	v_mul_f32_e32 v148, v73, v148
	v_cvt_pk_bf16_f32 v148, v150, v148
	v_add_u32_e32 v150, 0x19040, v68
	v_mov_b32_e32 v151, v3
	v_lshl_add_u64 v[150:151], v[150:151], 1, s[6:7]
	global_store_short v[150:151], v148, off
	v_add_u32_e32 v150, 0x19060, v68
	v_mov_b32_e32 v151, v3
	v_lshl_add_u64 v[150:151], v[150:151], 1, s[6:7]
	global_store_short_d16_hi v[150:151], v148, off
	ds_read_b32 v2, v1 offset:104
	ds_read2st64_b32 v[4:5], v70 offset0:14 offset1:30
	s_waitcnt lgkmcnt(0)
	v_fma_f32 v6, v66, v2, -v4
	v_fma_f32 v7, v50, v2, -v5
	ds_read2st64_b32 v[4:5], v70 offset0:46 offset1:62
	v_mul_f32_e32 v8, v7, v7
	v_fmac_f32_e32 v8, v6, v6
	s_waitcnt lgkmcnt(0)
	v_fma_f32 v9, v34, v2, -v4
	v_fmac_f32_e32 v8, v9, v9
	v_fma_f32 v2, v18, v2, -v5
	v_fmac_f32_e32 v8, v2, v2
	s_nop 1
	v_add_f32_dpp v4, v8, v8 quad_perm:[1,0,3,2] row_mask:0xf bank_mask:0xf
	s_nop 1
	v_add_f32_dpp v4, v4, v4 quad_perm:[2,3,0,1] row_mask:0xf bank_mask:0xf
	s_nop 1
	v_add_f32_dpp v4, v4, v4 row_half_mirror row_mask:0xf bank_mask:0xf
	s_nop 1
	v_add_f32_dpp v4, v4, v4 row_mirror row_mask:0xf bank_mask:0xf
	ds_swizzle_b32 v5, v4 offset:swizzle(SWAP,16)
	s_waitcnt lgkmcnt(0)
	v_add_f32_e32 v4, v4, v5
	v_fmamk_f32 v4, v4, 0x3c000000, v254
	v_cmp_gt_f32_e32 vcc, s90, v4
	v_mul_f32_e32 v5, 0x4f800000, v4
	s_nop 0
	v_cndmask_b32_e32 v4, v4, v5, vcc
	v_sqrt_f32_e32 v5, v4
	s_nop 0
	v_add_u32_e32 v8, -1, v5
	v_fma_f32 v10, -v8, v5, v4
	v_cmp_ge_f32_e64 s[4:5], 0, v10
	v_add_u32_e32 v10, 1, v5
	s_nop 0
	v_cndmask_b32_e64 v8, v5, v8, s[4:5]
	v_fma_f32 v5, -v10, v5, v4
	v_cmp_lt_f32_e64 s[4:5], 0, v5
	s_nop 1
	v_cndmask_b32_e64 v5, v8, v10, s[4:5]
	v_mul_f32_e32 v8, 0x37800000, v5
	v_cndmask_b32_e32 v5, v5, v8, vcc
	v_cmp_class_f32_e32 vcc, v4, v209
	s_nop 1
	v_cndmask_b32_e32 v4, v5, v4, vcc
	v_div_scale_f32 v5, s[4:5], v4, v4, 1.0
	v_rcp_f32_e32 v8, v5
	s_nop 0
	v_fma_f32 v10, -v5, v8, 1.0
	v_fmac_f32_e32 v8, v10, v8
	v_div_scale_f32 v10, vcc, 1.0, v4, 1.0
	v_mul_f32_e32 v11, v10, v8
	v_fma_f32 v12, -v5, v11, v10
	v_fmac_f32_e32 v11, v12, v8
	v_fma_f32 v5, -v5, v11, v10
	v_div_fmas_f32 v5, v5, v8, v11
	v_div_fixup_f32 v8, v5, v4, 1.0
	v_mul_f32_e32 v5, v6, v8
	v_mul_f32_e32 v6, v7, v8
	v_mul_f32_e32 v5, v72, v5
	v_mul_f32_e32 v6, v74, v6
	v_add_u32_e32 v4, 0x1a000, v68
	v_cvt_pk_bf16_f32 v6, v5, v6
	v_mov_b32_e32 v5, v3
	v_lshl_add_u64 v[4:5], v[4:5], 1, s[6:7]
	global_store_short v[4:5], v6, off
	v_add_u32_e32 v4, 0x1a020, v68
	v_mov_b32_e32 v5, v3
	v_lshl_add_u64 v[4:5], v[4:5], 1, s[6:7]
	global_store_short_d16_hi v[4:5], v6, off
	v_mul_f32_e32 v4, v9, v8
	v_mul_f32_e32 v2, v2, v8
	v_mul_f32_e32 v4, v71, v4
	v_mul_f32_e32 v2, v73, v2
	v_cvt_pk_bf16_f32 v2, v4, v2
	v_add_u32_e32 v4, 0x1a040, v68
	v_mov_b32_e32 v5, v3
	v_lshl_add_u64 v[4:5], v[4:5], 1, s[6:7]
	global_store_short v[4:5], v2, off
	v_add_u32_e32 v4, 0x1a060, v68
	v_mov_b32_e32 v5, v3
	v_lshl_add_u64 v[4:5], v[4:5], 1, s[6:7]
	global_store_short_d16_hi v[4:5], v2, off
	ds_read_b32 v1, v1 offset:108
	ds_read2st64_b32 v[4:5], v70 offset0:15 offset1:31
	s_waitcnt lgkmcnt(0)
	v_fma_f32 v2, v67, v1, -v4
	v_fma_f32 v6, v51, v1, -v5
	ds_read2st64_b32 v[4:5], v70 offset0:47 offset1:63
	v_mul_f32_e32 v7, v6, v6
	v_fmac_f32_e32 v7, v2, v2
	s_waitcnt lgkmcnt(0)
	v_fma_f32 v8, v35, v1, -v4
	v_fmac_f32_e32 v7, v8, v8
	v_fma_f32 v1, v19, v1, -v5
	v_fmac_f32_e32 v7, v1, v1
	s_nop 1
	v_add_f32_dpp v4, v7, v7 quad_perm:[1,0,3,2] row_mask:0xf bank_mask:0xf
	s_nop 1
	v_add_f32_dpp v4, v4, v4 quad_perm:[2,3,0,1] row_mask:0xf bank_mask:0xf
	s_nop 1
	v_add_f32_dpp v4, v4, v4 row_half_mirror row_mask:0xf bank_mask:0xf
	s_nop 1
	v_add_f32_dpp v4, v4, v4 row_mirror row_mask:0xf bank_mask:0xf
	ds_swizzle_b32 v5, v4 offset:swizzle(SWAP,16)
	s_waitcnt lgkmcnt(0)
	v_add_f32_e32 v4, v4, v5
	v_fmamk_f32 v4, v4, 0x3c000000, v254
	v_cmp_gt_f32_e32 vcc, s90, v4
	v_mul_f32_e32 v5, 0x4f800000, v4
	s_nop 0
	v_cndmask_b32_e32 v4, v4, v5, vcc
	v_sqrt_f32_e32 v5, v4
	s_nop 0
	v_add_u32_e32 v7, -1, v5
	v_fma_f32 v9, -v7, v5, v4
	v_cmp_ge_f32_e64 s[4:5], 0, v9
	v_add_u32_e32 v9, 1, v5
	s_nop 0
	v_cndmask_b32_e64 v7, v5, v7, s[4:5]
	v_fma_f32 v5, -v9, v5, v4
	v_cmp_lt_f32_e64 s[4:5], 0, v5
	s_nop 1
	v_cndmask_b32_e64 v5, v7, v9, s[4:5]
	v_mul_f32_e32 v7, 0x37800000, v5
	v_cndmask_b32_e32 v5, v5, v7, vcc
	v_cmp_class_f32_e32 vcc, v4, v209
	s_nop 1
	v_cndmask_b32_e32 v4, v5, v4, vcc
	v_div_scale_f32 v5, s[4:5], v4, v4, 1.0
	v_rcp_f32_e32 v7, v5
	s_nop 0
	v_fma_f32 v9, -v5, v7, 1.0
	v_fmac_f32_e32 v7, v9, v7
	v_div_scale_f32 v9, vcc, 1.0, v4, 1.0
	v_mul_f32_e32 v10, v9, v7
	v_fma_f32 v11, -v5, v10, v9
	v_fmac_f32_e32 v10, v11, v7
	v_fma_f32 v5, -v5, v10, v9
	v_div_fmas_f32 v5, v5, v7, v10
	v_div_fixup_f32 v7, v5, v4, 1.0
	v_mul_f32_e32 v2, v2, v7
	v_mul_f32_e32 v5, v6, v7
	v_mul_f32_e32 v2, v72, v2
	v_mul_f32_e32 v5, v74, v5
	v_add_u32_e32 v4, 0x1b000, v68
	v_cvt_pk_bf16_f32 v2, v2, v5
	v_mov_b32_e32 v5, v3
	v_lshl_add_u64 v[4:5], v[4:5], 1, s[6:7]
	global_store_short v[4:5], v2, off
	v_add_u32_e32 v4, 0x1b020, v68
	v_mov_b32_e32 v5, v3
	v_lshl_add_u64 v[4:5], v[4:5], 1, s[6:7]
	global_store_short_d16_hi v[4:5], v2, off
	v_mul_f32_e32 v1, v1, v7
	v_add_u32_e32 v4, 0x1b040, v68
	v_mov_b32_e32 v5, v3
	v_mul_f32_e32 v2, v8, v7
	v_mul_f32_e32 v1, v73, v1
	v_lshl_add_u64 v[4:5], v[4:5], 1, s[6:7]
	v_mul_f32_e32 v2, v71, v2
	v_cvt_pk_bf16_f32 v1, v2, v1
	global_store_short v[4:5], v1, off
	v_add_u32_e32 v4, 0x1b060, v68
	v_mov_b32_e32 v5, v3
	v_lshl_add_u64 v[4:5], v[4:5], 1, s[6:7]
	global_store_short_d16_hi v[4:5], v1, off

.LBB0_1657:
	s_or_b64 exec, exec, s[4:5]
	s_waitcnt lgkmcnt(0)
	v_lshlrev_b32_e32 v2, 2, v158
	global_load_dword v248, v2, s[0:1]
	global_load_dword v249, v2, s[0:1] offset:128
	global_load_dword v250, v2, s[0:1] offset:256
	global_load_dword v251, v2, s[0:1] offset:384
	v_add_u32_e32 v8, s46, v148
	s_lshl_b64 s[4:5], s[26:27], 13
	s_add_u32 s6, s86, s4
	s_addc_u32 s7, s87, s5
	s_waitcnt vmcnt(0)
	v_mul_f32_e32 v5, v164, v248
	v_mul_f32_e32 v7, v164, v249
	v_mul_f32_e32 v4, v164, v250
	v_mul_f32_e32 v6, v164, v251
	v_lshl_or_b32 v2, v159, 14, v158
	ds_read_b32 v9, v8
	ds_read2st64_b32 v[10:11], v1 offset1:16
	ds_read_b32 v21, v8 offset:4
	ds_read2st64_b32 v[22:23], v1 offset0:1 offset1:17
	ds_read_b32 v29, v8 offset:8
	ds_read2st64_b32 v[30:31], v1 offset0:2 offset1:18
	ds_read_b32 v37, v8 offset:12
	ds_read2st64_b32 v[38:39], v1 offset0:3 offset1:19
	s_waitcnt lgkmcnt(0)
	v_fma_f32 v12, v68, v9, -v10
	v_fma_f32 v13, v100, v9, -v11
	ds_read2st64_b32 v[10:11], v1 offset0:32 offset1:48
	v_mul_f32_e32 v14, v13, v13
	v_fmac_f32_e32 v14, v12, v12
	v_fma_f32 v24, v69, v21, -v22
	v_fma_f32 v25, v101, v21, -v23
	ds_read2st64_b32 v[22:23], v1 offset0:33 offset1:49
	v_mul_f32_e32 v26, v25, v25
	v_fmac_f32_e32 v26, v24, v24
	v_fma_f32 v32, v70, v29, -v30
	v_fma_f32 v33, v102, v29, -v31
	ds_read2st64_b32 v[30:31], v1 offset0:34 offset1:50
	v_mul_f32_e32 v34, v33, v33
	v_fmac_f32_e32 v34, v32, v32
	v_fma_f32 v40, v71, v37, -v38
	v_fma_f32 v41, v103, v37, -v39
	ds_read2st64_b32 v[38:39], v1 offset0:35 offset1:51
	v_mul_f32_e32 v42, v41, v41
	v_fmac_f32_e32 v42, v40, v40
	s_waitcnt lgkmcnt(0)
	v_fma_f32 v15, v116, v9, -v10
	v_fmac_f32_e32 v14, v15, v15
	v_fma_f32 v9, v132, v9, -v11
	v_fmac_f32_e32 v14, v9, v9
	s_nop 1
	v_add_f32_dpp v10, v14, v14 quad_perm:[1,0,3,2] row_mask:0xf bank_mask:0xf
	s_nop 1
	v_add_f32_dpp v10, v10, v10 quad_perm:[2,3,0,1] row_mask:0xf bank_mask:0xf
	s_nop 1
	v_add_f32_dpp v10, v10, v10 row_half_mirror row_mask:0xf bank_mask:0xf
	s_nop 1
	v_add_f32_dpp v10, v10, v10 row_mirror row_mask:0xf bank_mask:0xf
	ds_swizzle_b32 v11, v10 offset:swizzle(SWAP,16)
	v_fma_f32 v27, v117, v21, -v22
	v_fmac_f32_e32 v26, v27, v27
	v_fma_f32 v21, v133, v21, -v23
	v_fmac_f32_e32 v26, v21, v21
	s_nop 1
	v_add_f32_dpp v22, v26, v26 quad_perm:[1,0,3,2] row_mask:0xf bank_mask:0xf
	s_nop 1
	v_add_f32_dpp v22, v22, v22 quad_perm:[2,3,0,1] row_mask:0xf bank_mask:0xf
	s_nop 1
	v_add_f32_dpp v22, v22, v22 row_half_mirror row_mask:0xf bank_mask:0xf
	s_nop 1
	v_add_f32_dpp v22, v22, v22 row_mirror row_mask:0xf bank_mask:0xf
	ds_swizzle_b32 v23, v22 offset:swizzle(SWAP,16)
	v_fma_f32 v35, v118, v29, -v30
	v_fmac_f32_e32 v34, v35, v35
	v_fma_f32 v29, v134, v29, -v31
	v_fmac_f32_e32 v34, v29, v29
	s_nop 1
	v_add_f32_dpp v30, v34, v34 quad_perm:[1,0,3,2] row_mask:0xf bank_mask:0xf
	s_nop 1
	v_add_f32_dpp v30, v30, v30 quad_perm:[2,3,0,1] row_mask:0xf bank_mask:0xf
	s_nop 1
	v_add_f32_dpp v30, v30, v30 row_half_mirror row_mask:0xf bank_mask:0xf
	s_nop 1
	v_add_f32_dpp v30, v30, v30 row_mirror row_mask:0xf bank_mask:0xf
	ds_swizzle_b32 v31, v30 offset:swizzle(SWAP,16)
	v_fma_f32 v43, v119, v37, -v38
	v_fmac_f32_e32 v42, v43, v43
	v_fma_f32 v37, v135, v37, -v39
	v_fmac_f32_e32 v42, v37, v37
	s_nop 1
	v_add_f32_dpp v38, v42, v42 quad_perm:[1,0,3,2] row_mask:0xf bank_mask:0xf
	s_nop 1
	v_add_f32_dpp v38, v38, v38 quad_perm:[2,3,0,1] row_mask:0xf bank_mask:0xf
	s_nop 1
	v_add_f32_dpp v38, v38, v38 row_half_mirror row_mask:0xf bank_mask:0xf
	s_nop 1
	v_add_f32_dpp v38, v38, v38 row_mirror row_mask:0xf bank_mask:0xf
	ds_swizzle_b32 v39, v38 offset:swizzle(SWAP,16)
	s_waitcnt lgkmcnt(0)
	v_add_f32_e32 v10, v10, v11
	v_fmamk_f32 v10, v10, 0x3c000000, v254
	s_nop 0
	s_nop 0
	s_nop 0
	s_nop 1
	s_nop 1
	s_nop 0
	v_rsq_f32_e32 v14, v10
	s_nop 0
	v_mul_f32_e32 v10, v12, v14
	v_mul_f32_e32 v11, v13, v14
	v_mul_f32_e32 v10, v5, v10
	v_mul_f32_e32 v11, v7, v11
	v_cvt_pk_bf16_f32 v12, v10, v11
	v_lshl_add_u64 v[10:11], v[2:3], 1, s[6:7]
	global_store_short v[10:11], v12, off offset:768
	v_add_u32_e32 v10, 32, v2
	v_mov_b32_e32 v11, v3
	v_lshl_add_u64 v[10:11], v[10:11], 1, s[6:7]
	global_store_short_d16_hi v[10:11], v12, off offset:768
	v_mul_f32_e32 v10, v15, v14
	v_mul_f32_e32 v9, v9, v14
	v_mul_f32_e32 v10, v4, v10
	v_mul_f32_e32 v9, v6, v9
	v_cvt_pk_bf16_f32 v9, v10, v9
	v_add_u32_e32 v10, 64, v2
	v_mov_b32_e32 v11, v3
	v_lshl_add_u64 v[10:11], v[10:11], 1, s[6:7]
	global_store_short v[10:11], v9, off offset:768
	v_add_u32_e32 v10, 0x60, v2
	v_mov_b32_e32 v11, v3
	v_lshl_add_u64 v[10:11], v[10:11], 1, s[6:7]
	global_store_short_d16_hi v[10:11], v9, off offset:768
	v_add_f32_e32 v22, v22, v23
	v_fmamk_f32 v22, v22, 0x3c000000, v254
	s_nop 0
	s_nop 0
	s_nop 0
	s_nop 1
	s_nop 1
	s_nop 0
	v_rsq_f32_e32 v26, v22
	s_nop 0
	v_mul_f32_e32 v23, v24, v26
	v_mul_f32_e32 v24, v25, v26
	v_mul_f32_e32 v23, v5, v23
	v_mul_f32_e32 v24, v7, v24
	v_add_u32_e32 v22, 0x1000, v2
	v_cvt_pk_bf16_f32 v24, v23, v24
	v_mov_b32_e32 v23, v3
	v_lshl_add_u64 v[22:23], v[22:23], 1, s[6:7]
	global_store_short v[22:23], v24, off offset:768
	v_add_u32_e32 v22, 0x1020, v2
	v_mov_b32_e32 v23, v3
	v_lshl_add_u64 v[22:23], v[22:23], 1, s[6:7]
	global_store_short_d16_hi v[22:23], v24, off offset:768
	v_mul_f32_e32 v22, v27, v26
	v_mul_f32_e32 v21, v21, v26
	v_mul_f32_e32 v22, v4, v22
	v_mul_f32_e32 v21, v6, v21
	v_cvt_pk_bf16_f32 v21, v22, v21
	v_add_u32_e32 v22, 0x1040, v2
	v_mov_b32_e32 v23, v3
	v_lshl_add_u64 v[22:23], v[22:23], 1, s[6:7]
	global_store_short v[22:23], v21, off offset:768
	v_add_u32_e32 v22, 0x1060, v2
	v_mov_b32_e32 v23, v3
	v_lshl_add_u64 v[22:23], v[22:23], 1, s[6:7]
	global_store_short_d16_hi v[22:23], v21, off offset:768
	v_add_f32_e32 v30, v30, v31
	v_fmamk_f32 v30, v30, 0x3c000000, v254
	s_nop 0
	s_nop 0
	s_nop 0
	s_nop 1
	s_nop 1
	s_nop 0
	v_rsq_f32_e32 v34, v30
	s_nop 0
	v_mul_f32_e32 v31, v32, v34
	v_mul_f32_e32 v32, v33, v34
	v_mul_f32_e32 v31, v5, v31
	v_mul_f32_e32 v32, v7, v32
	v_add_u32_e32 v30, 0x2000, v2
	v_cvt_pk_bf16_f32 v32, v31, v32
	v_mov_b32_e32 v31, v3
	v_lshl_add_u64 v[30:31], v[30:31], 1, s[6:7]
	global_store_short v[30:31], v32, off offset:768
	v_add_u32_e32 v30, 0x2020, v2
	v_mov_b32_e32 v31, v3
	v_lshl_add_u64 v[30:31], v[30:31], 1, s[6:7]
	global_store_short_d16_hi v[30:31], v32, off offset:768
	v_mul_f32_e32 v30, v35, v34
	v_mul_f32_e32 v29, v29, v34
	v_mul_f32_e32 v30, v4, v30
	v_mul_f32_e32 v29, v6, v29
	v_cvt_pk_bf16_f32 v29, v30, v29
	v_add_u32_e32 v30, 0x2040, v2
	v_mov_b32_e32 v31, v3
	v_lshl_add_u64 v[30:31], v[30:31], 1, s[6:7]
	global_store_short v[30:31], v29, off offset:768
	v_add_u32_e32 v30, 0x2060, v2
	v_mov_b32_e32 v31, v3
	v_lshl_add_u64 v[30:31], v[30:31], 1, s[6:7]
	global_store_short_d16_hi v[30:31], v29, off offset:768
	v_add_f32_e32 v38, v38, v39
	v_fmamk_f32 v38, v38, 0x3c000000, v254
	s_nop 0
	s_nop 0
	s_nop 0
	s_nop 1
	s_nop 1
	s_nop 0
	v_rsq_f32_e32 v42, v38
	s_nop 0
	v_mul_f32_e32 v39, v40, v42
	v_mul_f32_e32 v40, v41, v42
	v_mul_f32_e32 v39, v5, v39
	v_mul_f32_e32 v40, v7, v40
	v_add_u32_e32 v38, 0x3000, v2
	v_cvt_pk_bf16_f32 v40, v39, v40
	v_mov_b32_e32 v39, v3
	v_lshl_add_u64 v[38:39], v[38:39], 1, s[6:7]
	global_store_short v[38:39], v40, off offset:768
	v_add_u32_e32 v38, 0x3020, v2
	v_mov_b32_e32 v39, v3
	v_lshl_add_u64 v[38:39], v[38:39], 1, s[6:7]
	global_store_short_d16_hi v[38:39], v40, off offset:768
	v_mul_f32_e32 v38, v43, v42
	v_mul_f32_e32 v37, v37, v42
	v_mul_f32_e32 v38, v4, v38
	v_mul_f32_e32 v37, v6, v37
	v_cvt_pk_bf16_f32 v37, v38, v37
	v_add_u32_e32 v38, 0x3040, v2
	v_mov_b32_e32 v39, v3
	v_lshl_add_u64 v[38:39], v[38:39], 1, s[6:7]
	global_store_short v[38:39], v37, off offset:768
	v_add_u32_e32 v38, 0x3060, v2
	v_mov_b32_e32 v39, v3
	v_lshl_add_u64 v[38:39], v[38:39], 1, s[6:7]
	global_store_short_d16_hi v[38:39], v37, off offset:768
	ds_read_b32 v9, v8 offset:32
	ds_read2st64_b32 v[10:11], v1 offset0:4 offset1:20
	ds_read_b32 v21, v8 offset:36
	ds_read2st64_b32 v[22:23], v1 offset0:5 offset1:21
	ds_read_b32 v29, v8 offset:40
	ds_read2st64_b32 v[30:31], v1 offset0:6 offset1:22
	ds_read_b32 v37, v8 offset:44
	ds_read2st64_b32 v[38:39], v1 offset0:7 offset1:23
	s_waitcnt lgkmcnt(0)
	v_fma_f32 v12, v72, v9, -v10
	v_fma_f32 v13, v104, v9, -v11
	ds_read2st64_b32 v[10:11], v1 offset0:36 offset1:52
	v_mul_f32_e32 v14, v13, v13
	v_fmac_f32_e32 v14, v12, v12
	v_fma_f32 v24, v73, v21, -v22
	v_fma_f32 v25, v105, v21, -v23
	ds_read2st64_b32 v[22:23], v1 offset0:37 offset1:53
	v_mul_f32_e32 v26, v25, v25
	v_fmac_f32_e32 v26, v24, v24
	v_fma_f32 v32, v74, v29, -v30
	v_fma_f32 v33, v106, v29, -v31
	ds_read2st64_b32 v[30:31], v1 offset0:38 offset1:54
	v_mul_f32_e32 v34, v33, v33
	v_fmac_f32_e32 v34, v32, v32
	v_fma_f32 v40, v75, v37, -v38
	v_fma_f32 v41, v107, v37, -v39
	ds_read2st64_b32 v[38:39], v1 offset0:39 offset1:55
	v_mul_f32_e32 v42, v41, v41
	v_fmac_f32_e32 v42, v40, v40
	s_waitcnt lgkmcnt(0)
	v_fma_f32 v15, v120, v9, -v10
	v_fmac_f32_e32 v14, v15, v15
	v_fma_f32 v9, v136, v9, -v11
	v_fmac_f32_e32 v14, v9, v9
	s_nop 1
	v_add_f32_dpp v10, v14, v14 quad_perm:[1,0,3,2] row_mask:0xf bank_mask:0xf
	s_nop 1
	v_add_f32_dpp v10, v10, v10 quad_perm:[2,3,0,1] row_mask:0xf bank_mask:0xf
	s_nop 1
	v_add_f32_dpp v10, v10, v10 row_half_mirror row_mask:0xf bank_mask:0xf
	s_nop 1
	v_add_f32_dpp v10, v10, v10 row_mirror row_mask:0xf bank_mask:0xf
	ds_swizzle_b32 v11, v10 offset:swizzle(SWAP,16)
	v_fma_f32 v27, v121, v21, -v22
	v_fmac_f32_e32 v26, v27, v27
	v_fma_f32 v21, v137, v21, -v23
	v_fmac_f32_e32 v26, v21, v21
	s_nop 1
	v_add_f32_dpp v22, v26, v26 quad_perm:[1,0,3,2] row_mask:0xf bank_mask:0xf
	s_nop 1
	v_add_f32_dpp v22, v22, v22 quad_perm:[2,3,0,1] row_mask:0xf bank_mask:0xf
	s_nop 1
	v_add_f32_dpp v22, v22, v22 row_half_mirror row_mask:0xf bank_mask:0xf
	s_nop 1
	v_add_f32_dpp v22, v22, v22 row_mirror row_mask:0xf bank_mask:0xf
	ds_swizzle_b32 v23, v22 offset:swizzle(SWAP,16)
	v_fma_f32 v35, v122, v29, -v30
	v_fmac_f32_e32 v34, v35, v35
	v_fma_f32 v29, v138, v29, -v31
	v_fmac_f32_e32 v34, v29, v29
	s_nop 1
	v_add_f32_dpp v30, v34, v34 quad_perm:[1,0,3,2] row_mask:0xf bank_mask:0xf
	s_nop 1
	v_add_f32_dpp v30, v30, v30 quad_perm:[2,3,0,1] row_mask:0xf bank_mask:0xf
	s_nop 1
	v_add_f32_dpp v30, v30, v30 row_half_mirror row_mask:0xf bank_mask:0xf
	s_nop 1
	v_add_f32_dpp v30, v30, v30 row_mirror row_mask:0xf bank_mask:0xf
	ds_swizzle_b32 v31, v30 offset:swizzle(SWAP,16)
	v_fma_f32 v43, v123, v37, -v38
	v_fmac_f32_e32 v42, v43, v43
	v_fma_f32 v37, v139, v37, -v39
	v_fmac_f32_e32 v42, v37, v37
	s_nop 1
	v_add_f32_dpp v38, v42, v42 quad_perm:[1,0,3,2] row_mask:0xf bank_mask:0xf
	s_nop 1
	v_add_f32_dpp v38, v38, v38 quad_perm:[2,3,0,1] row_mask:0xf bank_mask:0xf
	s_nop 1
	v_add_f32_dpp v38, v38, v38 row_half_mirror row_mask:0xf bank_mask:0xf
	s_nop 1
	v_add_f32_dpp v38, v38, v38 row_mirror row_mask:0xf bank_mask:0xf
	ds_swizzle_b32 v39, v38 offset:swizzle(SWAP,16)
	s_waitcnt lgkmcnt(0)
	v_add_f32_e32 v10, v10, v11
	v_fmamk_f32 v10, v10, 0x3c000000, v254
	s_nop 0
	s_nop 0
	s_nop 0
	s_nop 1
	s_nop 1
	s_nop 0
	v_rsq_f32_e32 v14, v10
	s_nop 0
	v_mul_f32_e32 v11, v12, v14
	v_mul_f32_e32 v12, v13, v14
	v_mul_f32_e32 v11, v5, v11
	v_mul_f32_e32 v12, v7, v12
	v_add_u32_e32 v10, 0x8000, v2
	v_cvt_pk_bf16_f32 v12, v11, v12
	v_mov_b32_e32 v11, v3
	v_lshl_add_u64 v[10:11], v[10:11], 1, s[6:7]
	global_store_short v[10:11], v12, off offset:768
	v_add_u32_e32 v10, 0x8020, v2
	v_mov_b32_e32 v11, v3
	v_lshl_add_u64 v[10:11], v[10:11], 1, s[6:7]
	global_store_short_d16_hi v[10:11], v12, off offset:768
	v_mul_f32_e32 v10, v15, v14
	v_mul_f32_e32 v9, v9, v14
	v_mul_f32_e32 v10, v4, v10
	v_mul_f32_e32 v9, v6, v9
	v_cvt_pk_bf16_f32 v9, v10, v9
	v_add_u32_e32 v10, 0x8040, v2
	v_mov_b32_e32 v11, v3
	v_lshl_add_u64 v[10:11], v[10:11], 1, s[6:7]
	global_store_short v[10:11], v9, off offset:768
	v_add_u32_e32 v10, 0x8060, v2
	v_mov_b32_e32 v11, v3
	v_lshl_add_u64 v[10:11], v[10:11], 1, s[6:7]
	global_store_short_d16_hi v[10:11], v9, off offset:768
	v_add_f32_e32 v22, v22, v23
	v_fmamk_f32 v22, v22, 0x3c000000, v254
	s_nop 0
	s_nop 0
	s_nop 0
	s_nop 1
	s_nop 1
	s_nop 0
	v_rsq_f32_e32 v26, v22
	s_nop 0
	v_mul_f32_e32 v23, v24, v26
	v_mul_f32_e32 v24, v25, v26
	v_mul_f32_e32 v23, v5, v23
	v_mul_f32_e32 v24, v7, v24
	v_add_u32_e32 v22, 0x9000, v2
	v_cvt_pk_bf16_f32 v24, v23, v24
	v_mov_b32_e32 v23, v3
	v_lshl_add_u64 v[22:23], v[22:23], 1, s[6:7]
	global_store_short v[22:23], v24, off offset:768
	v_add_u32_e32 v22, 0x9020, v2
	v_mov_b32_e32 v23, v3
	v_lshl_add_u64 v[22:23], v[22:23], 1, s[6:7]
	global_store_short_d16_hi v[22:23], v24, off offset:768
	v_mul_f32_e32 v22, v27, v26
	v_mul_f32_e32 v21, v21, v26
	v_mul_f32_e32 v22, v4, v22
	v_mul_f32_e32 v21, v6, v21
	v_cvt_pk_bf16_f32 v21, v22, v21
	v_add_u32_e32 v22, 0x9040, v2
	v_mov_b32_e32 v23, v3
	v_lshl_add_u64 v[22:23], v[22:23], 1, s[6:7]
	global_store_short v[22:23], v21, off offset:768
	v_add_u32_e32 v22, 0x9060, v2
	v_mov_b32_e32 v23, v3
	v_lshl_add_u64 v[22:23], v[22:23], 1, s[6:7]
	global_store_short_d16_hi v[22:23], v21, off offset:768
	v_add_f32_e32 v30, v30, v31
	v_fmamk_f32 v30, v30, 0x3c000000, v254
	s_nop 0
	s_nop 0
	s_nop 0
	s_nop 1
	s_nop 1
	s_nop 0
	v_rsq_f32_e32 v34, v30
	s_nop 0
	v_mul_f32_e32 v31, v32, v34
	v_mul_f32_e32 v32, v33, v34
	v_mul_f32_e32 v31, v5, v31
	v_mul_f32_e32 v32, v7, v32
	v_add_u32_e32 v30, 0xa000, v2
	v_cvt_pk_bf16_f32 v32, v31, v32
	v_mov_b32_e32 v31, v3
	v_lshl_add_u64 v[30:31], v[30:31], 1, s[6:7]
	global_store_short v[30:31], v32, off offset:768
	v_add_u32_e32 v30, 0xa020, v2
	v_mov_b32_e32 v31, v3
	v_lshl_add_u64 v[30:31], v[30:31], 1, s[6:7]
	global_store_short_d16_hi v[30:31], v32, off offset:768
	v_mul_f32_e32 v30, v35, v34
	v_mul_f32_e32 v29, v29, v34
	v_mul_f32_e32 v30, v4, v30
	v_mul_f32_e32 v29, v6, v29
	v_cvt_pk_bf16_f32 v29, v30, v29
	v_add_u32_e32 v30, 0xa040, v2
	v_mov_b32_e32 v31, v3
	v_lshl_add_u64 v[30:31], v[30:31], 1, s[6:7]
	global_store_short v[30:31], v29, off offset:768
	v_add_u32_e32 v30, 0xa060, v2
	v_mov_b32_e32 v31, v3
	v_lshl_add_u64 v[30:31], v[30:31], 1, s[6:7]
	global_store_short_d16_hi v[30:31], v29, off offset:768
	v_add_f32_e32 v38, v38, v39
	v_fmamk_f32 v38, v38, 0x3c000000, v254
	s_nop 0
	s_nop 0
	s_nop 0
	s_nop 1
	s_nop 1
	s_nop 0
	v_rsq_f32_e32 v42, v38
	s_nop 0
	v_mul_f32_e32 v39, v40, v42
	v_mul_f32_e32 v40, v41, v42
	v_mul_f32_e32 v39, v5, v39
	v_mul_f32_e32 v40, v7, v40
	v_add_u32_e32 v38, 0xb000, v2
	v_cvt_pk_bf16_f32 v40, v39, v40
	v_mov_b32_e32 v39, v3
	v_lshl_add_u64 v[38:39], v[38:39], 1, s[6:7]
	global_store_short v[38:39], v40, off offset:768
	v_add_u32_e32 v38, 0xb020, v2
	v_mov_b32_e32 v39, v3
	v_lshl_add_u64 v[38:39], v[38:39], 1, s[6:7]
	global_store_short_d16_hi v[38:39], v40, off offset:768
	v_mul_f32_e32 v38, v43, v42
	v_mul_f32_e32 v37, v37, v42
	v_mul_f32_e32 v38, v4, v38
	v_mul_f32_e32 v37, v6, v37
	v_cvt_pk_bf16_f32 v37, v38, v37
	v_add_u32_e32 v38, 0xb040, v2
	v_mov_b32_e32 v39, v3
	v_lshl_add_u64 v[38:39], v[38:39], 1, s[6:7]
	global_store_short v[38:39], v37, off offset:768
	v_add_u32_e32 v38, 0xb060, v2
	v_mov_b32_e32 v39, v3
	v_lshl_add_u64 v[38:39], v[38:39], 1, s[6:7]
	global_store_short_d16_hi v[38:39], v37, off offset:768
	ds_read_b32 v9, v8 offset:64
	ds_read2st64_b32 v[10:11], v1 offset0:8 offset1:24
	ds_read_b32 v21, v8 offset:68
	ds_read2st64_b32 v[22:23], v1 offset0:9 offset1:25
	ds_read_b32 v29, v8 offset:72
	ds_read2st64_b32 v[30:31], v1 offset0:10 offset1:26
	ds_read_b32 v37, v8 offset:76
	ds_read2st64_b32 v[38:39], v1 offset0:11 offset1:27
	s_waitcnt lgkmcnt(0)
	v_fma_f32 v12, v76, v9, -v10
	v_fma_f32 v13, v108, v9, -v11
	ds_read2st64_b32 v[10:11], v1 offset0:40 offset1:56
	v_mul_f32_e32 v14, v13, v13
	v_fmac_f32_e32 v14, v12, v12
	v_fma_f32 v24, v77, v21, -v22
	v_fma_f32 v25, v109, v21, -v23
	ds_read2st64_b32 v[22:23], v1 offset0:41 offset1:57
	v_mul_f32_e32 v26, v25, v25
	v_fmac_f32_e32 v26, v24, v24
	v_fma_f32 v32, v78, v29, -v30
	v_fma_f32 v33, v110, v29, -v31
	ds_read2st64_b32 v[30:31], v1 offset0:42 offset1:58
	v_mul_f32_e32 v34, v33, v33
	v_fmac_f32_e32 v34, v32, v32
	v_fma_f32 v40, v79, v37, -v38
	v_fma_f32 v41, v111, v37, -v39
	ds_read2st64_b32 v[38:39], v1 offset0:43 offset1:59
	v_mul_f32_e32 v42, v41, v41
	v_fmac_f32_e32 v42, v40, v40
	s_waitcnt lgkmcnt(0)
	v_fma_f32 v15, v124, v9, -v10
	v_fmac_f32_e32 v14, v15, v15
	v_fma_f32 v9, v140, v9, -v11
	v_fmac_f32_e32 v14, v9, v9
	s_nop 1
	v_add_f32_dpp v10, v14, v14 quad_perm:[1,0,3,2] row_mask:0xf bank_mask:0xf
	s_nop 1
	v_add_f32_dpp v10, v10, v10 quad_perm:[2,3,0,1] row_mask:0xf bank_mask:0xf
	s_nop 1
	v_add_f32_dpp v10, v10, v10 row_half_mirror row_mask:0xf bank_mask:0xf
	s_nop 1
	v_add_f32_dpp v10, v10, v10 row_mirror row_mask:0xf bank_mask:0xf
	ds_swizzle_b32 v11, v10 offset:swizzle(SWAP,16)
	v_fma_f32 v27, v125, v21, -v22
	v_fmac_f32_e32 v26, v27, v27
	v_fma_f32 v21, v141, v21, -v23
	v_fmac_f32_e32 v26, v21, v21
	s_nop 1
	v_add_f32_dpp v22, v26, v26 quad_perm:[1,0,3,2] row_mask:0xf bank_mask:0xf
	s_nop 1
	v_add_f32_dpp v22, v22, v22 quad_perm:[2,3,0,1] row_mask:0xf bank_mask:0xf
	s_nop 1
	v_add_f32_dpp v22, v22, v22 row_half_mirror row_mask:0xf bank_mask:0xf
	s_nop 1
	v_add_f32_dpp v22, v22, v22 row_mirror row_mask:0xf bank_mask:0xf
	ds_swizzle_b32 v23, v22 offset:swizzle(SWAP,16)
	v_fma_f32 v35, v126, v29, -v30
	v_fmac_f32_e32 v34, v35, v35
	v_fma_f32 v29, v142, v29, -v31
	v_fmac_f32_e32 v34, v29, v29
	s_nop 1
	v_add_f32_dpp v30, v34, v34 quad_perm:[1,0,3,2] row_mask:0xf bank_mask:0xf
	s_nop 1
	v_add_f32_dpp v30, v30, v30 quad_perm:[2,3,0,1] row_mask:0xf bank_mask:0xf
	s_nop 1
	v_add_f32_dpp v30, v30, v30 row_half_mirror row_mask:0xf bank_mask:0xf
	s_nop 1
	v_add_f32_dpp v30, v30, v30 row_mirror row_mask:0xf bank_mask:0xf
	ds_swizzle_b32 v31, v30 offset:swizzle(SWAP,16)
	v_fma_f32 v43, v127, v37, -v38
	v_fmac_f32_e32 v42, v43, v43
	v_fma_f32 v37, v143, v37, -v39
	v_fmac_f32_e32 v42, v37, v37
	s_nop 1
	v_add_f32_dpp v38, v42, v42 quad_perm:[1,0,3,2] row_mask:0xf bank_mask:0xf
	s_nop 1
	v_add_f32_dpp v38, v38, v38 quad_perm:[2,3,0,1] row_mask:0xf bank_mask:0xf
	s_nop 1
	v_add_f32_dpp v38, v38, v38 row_half_mirror row_mask:0xf bank_mask:0xf
	s_nop 1
	v_add_f32_dpp v38, v38, v38 row_mirror row_mask:0xf bank_mask:0xf
	ds_swizzle_b32 v39, v38 offset:swizzle(SWAP,16)
	s_waitcnt lgkmcnt(0)
	v_add_f32_e32 v10, v10, v11
	v_fmamk_f32 v10, v10, 0x3c000000, v254
	s_nop 0
	s_nop 0
	s_nop 0
	s_nop 1
	s_nop 1
	s_nop 0
	v_rsq_f32_e32 v14, v10
	s_nop 0
	v_mul_f32_e32 v11, v12, v14
	v_mul_f32_e32 v12, v13, v14
	v_mul_f32_e32 v11, v5, v11
	v_mul_f32_e32 v12, v7, v12
	v_add_u32_e32 v10, 0x10000, v2
	v_cvt_pk_bf16_f32 v12, v11, v12
	v_mov_b32_e32 v11, v3
	v_lshl_add_u64 v[10:11], v[10:11], 1, s[6:7]
	global_store_short v[10:11], v12, off offset:768
	v_add_u32_e32 v10, 0x10020, v2
	v_mov_b32_e32 v11, v3
	v_lshl_add_u64 v[10:11], v[10:11], 1, s[6:7]
	global_store_short_d16_hi v[10:11], v12, off offset:768
	v_mul_f32_e32 v10, v15, v14
	v_mul_f32_e32 v9, v9, v14
	v_mul_f32_e32 v10, v4, v10
	v_mul_f32_e32 v9, v6, v9
	v_cvt_pk_bf16_f32 v9, v10, v9
	v_add_u32_e32 v10, 0x10040, v2
	v_mov_b32_e32 v11, v3
	v_lshl_add_u64 v[10:11], v[10:11], 1, s[6:7]
	global_store_short v[10:11], v9, off offset:768
	v_add_u32_e32 v10, 0x10060, v2
	v_mov_b32_e32 v11, v3
	v_lshl_add_u64 v[10:11], v[10:11], 1, s[6:7]
	global_store_short_d16_hi v[10:11], v9, off offset:768
	v_add_f32_e32 v22, v22, v23
	v_fmamk_f32 v22, v22, 0x3c000000, v254
	s_nop 0
	s_nop 0
	s_nop 0
	s_nop 1
	s_nop 1
	s_nop 0
	v_rsq_f32_e32 v26, v22
	s_nop 0
	v_mul_f32_e32 v23, v24, v26
	v_mul_f32_e32 v24, v25, v26
	v_mul_f32_e32 v23, v5, v23
	v_mul_f32_e32 v24, v7, v24
	v_add_u32_e32 v22, 0x11000, v2
	v_cvt_pk_bf16_f32 v24, v23, v24
	v_mov_b32_e32 v23, v3
	v_lshl_add_u64 v[22:23], v[22:23], 1, s[6:7]
	global_store_short v[22:23], v24, off offset:768
	v_add_u32_e32 v22, 0x11020, v2
	v_mov_b32_e32 v23, v3
	v_lshl_add_u64 v[22:23], v[22:23], 1, s[6:7]
	global_store_short_d16_hi v[22:23], v24, off offset:768
	v_mul_f32_e32 v22, v27, v26
	v_mul_f32_e32 v21, v21, v26
	v_mul_f32_e32 v22, v4, v22
	v_mul_f32_e32 v21, v6, v21
	v_cvt_pk_bf16_f32 v21, v22, v21
	v_add_u32_e32 v22, 0x11040, v2
	v_mov_b32_e32 v23, v3
	v_lshl_add_u64 v[22:23], v[22:23], 1, s[6:7]
	global_store_short v[22:23], v21, off offset:768
	v_add_u32_e32 v22, 0x11060, v2
	v_mov_b32_e32 v23, v3
	v_lshl_add_u64 v[22:23], v[22:23], 1, s[6:7]
	global_store_short_d16_hi v[22:23], v21, off offset:768
	v_add_f32_e32 v30, v30, v31
	v_fmamk_f32 v30, v30, 0x3c000000, v254
	s_nop 0
	s_nop 0
	s_nop 0
	s_nop 1
	s_nop 1
	s_nop 0
	v_rsq_f32_e32 v34, v30
	s_nop 0
	v_mul_f32_e32 v31, v32, v34
	v_mul_f32_e32 v32, v33, v34
	v_mul_f32_e32 v31, v5, v31
	v_mul_f32_e32 v32, v7, v32
	v_add_u32_e32 v30, 0x12000, v2
	v_cvt_pk_bf16_f32 v32, v31, v32
	v_mov_b32_e32 v31, v3
	v_lshl_add_u64 v[30:31], v[30:31], 1, s[6:7]
	global_store_short v[30:31], v32, off offset:768
	v_add_u32_e32 v30, 0x12020, v2
	v_mov_b32_e32 v31, v3
	v_lshl_add_u64 v[30:31], v[30:31], 1, s[6:7]
	global_store_short_d16_hi v[30:31], v32, off offset:768
	v_mul_f32_e32 v30, v35, v34
	v_mul_f32_e32 v29, v29, v34
	v_mul_f32_e32 v30, v4, v30
	v_mul_f32_e32 v29, v6, v29
	v_cvt_pk_bf16_f32 v29, v30, v29
	v_add_u32_e32 v30, 0x12040, v2
	v_mov_b32_e32 v31, v3
	v_lshl_add_u64 v[30:31], v[30:31], 1, s[6:7]
	global_store_short v[30:31], v29, off offset:768
	v_add_u32_e32 v30, 0x12060, v2
	v_mov_b32_e32 v31, v3
	v_lshl_add_u64 v[30:31], v[30:31], 1, s[6:7]
	global_store_short_d16_hi v[30:31], v29, off offset:768
	v_add_f32_e32 v38, v38, v39
	v_fmamk_f32 v38, v38, 0x3c000000, v254
	s_nop 0
	s_nop 0
	s_nop 0
	s_nop 1
	s_nop 1
	s_nop 0
	v_rsq_f32_e32 v42, v38
	s_nop 0
	v_mul_f32_e32 v39, v40, v42
	v_mul_f32_e32 v40, v41, v42
	v_mul_f32_e32 v39, v5, v39
	v_mul_f32_e32 v40, v7, v40
	v_add_u32_e32 v38, 0x13000, v2
	v_cvt_pk_bf16_f32 v40, v39, v40
	v_mov_b32_e32 v39, v3
	v_lshl_add_u64 v[38:39], v[38:39], 1, s[6:7]
	global_store_short v[38:39], v40, off offset:768
	v_add_u32_e32 v38, 0x13020, v2
	v_mov_b32_e32 v39, v3
	v_lshl_add_u64 v[38:39], v[38:39], 1, s[6:7]
	global_store_short_d16_hi v[38:39], v40, off offset:768
	v_mul_f32_e32 v38, v43, v42
	v_mul_f32_e32 v37, v37, v42
	v_mul_f32_e32 v38, v4, v38
	v_mul_f32_e32 v37, v6, v37
	v_cvt_pk_bf16_f32 v37, v38, v37
	v_add_u32_e32 v38, 0x13040, v2
	v_mov_b32_e32 v39, v3
	v_lshl_add_u64 v[38:39], v[38:39], 1, s[6:7]
	global_store_short v[38:39], v37, off offset:768
	v_add_u32_e32 v38, 0x13060, v2
	v_mov_b32_e32 v39, v3
	v_lshl_add_u64 v[38:39], v[38:39], 1, s[6:7]
	global_store_short_d16_hi v[38:39], v37, off offset:768
	ds_read_b32 v9, v8 offset:96
	ds_read2st64_b32 v[10:11], v1 offset0:12 offset1:28
	ds_read_b32 v21, v8 offset:100
	ds_read2st64_b32 v[22:23], v1 offset0:13 offset1:29
	s_waitcnt lgkmcnt(0)
	v_fma_f32 v12, v80, v9, -v10
	v_fma_f32 v13, v112, v9, -v11
	ds_read2st64_b32 v[10:11], v1 offset0:44 offset1:60
	v_mul_f32_e32 v14, v13, v13
	v_fmac_f32_e32 v14, v12, v12
	v_fma_f32 v24, v81, v21, -v22
	v_fma_f32 v25, v113, v21, -v23
	ds_read2st64_b32 v[22:23], v1 offset0:45 offset1:61
	v_mul_f32_e32 v26, v25, v25
	v_fmac_f32_e32 v26, v24, v24
	s_waitcnt lgkmcnt(0)
	v_fma_f32 v15, v128, v9, -v10
	v_fmac_f32_e32 v14, v15, v15
	v_fma_f32 v9, v144, v9, -v11
	v_fmac_f32_e32 v14, v9, v9
	s_nop 1
	v_add_f32_dpp v10, v14, v14 quad_perm:[1,0,3,2] row_mask:0xf bank_mask:0xf
	s_nop 1
	v_add_f32_dpp v10, v10, v10 quad_perm:[2,3,0,1] row_mask:0xf bank_mask:0xf
	s_nop 1
	v_add_f32_dpp v10, v10, v10 row_half_mirror row_mask:0xf bank_mask:0xf
	s_nop 1
	v_add_f32_dpp v10, v10, v10 row_mirror row_mask:0xf bank_mask:0xf
	ds_swizzle_b32 v11, v10 offset:swizzle(SWAP,16)
	v_fma_f32 v27, v129, v21, -v22
	v_fmac_f32_e32 v26, v27, v27
	v_fma_f32 v21, v145, v21, -v23
	v_fmac_f32_e32 v26, v21, v21
	s_nop 1
	v_add_f32_dpp v22, v26, v26 quad_perm:[1,0,3,2] row_mask:0xf bank_mask:0xf
	s_nop 1
	v_add_f32_dpp v22, v22, v22 quad_perm:[2,3,0,1] row_mask:0xf bank_mask:0xf
	s_nop 1
	v_add_f32_dpp v22, v22, v22 row_half_mirror row_mask:0xf bank_mask:0xf
	s_nop 1
	v_add_f32_dpp v22, v22, v22 row_mirror row_mask:0xf bank_mask:0xf
	ds_swizzle_b32 v23, v22 offset:swizzle(SWAP,16)
	s_waitcnt lgkmcnt(0)
	v_add_f32_e32 v10, v10, v11
	v_fmamk_f32 v10, v10, 0x3c000000, v254
	s_nop 0
	s_nop 0
	s_nop 0
	s_nop 1
	s_nop 1
	s_nop 0
	v_rsq_f32_e32 v14, v10
	s_nop 0
	v_mul_f32_e32 v11, v12, v14
	v_mul_f32_e32 v12, v13, v14
	v_mul_f32_e32 v11, v5, v11
	v_mul_f32_e32 v12, v7, v12
	v_add_u32_e32 v10, 0x18000, v2
	v_cvt_pk_bf16_f32 v12, v11, v12
	v_mov_b32_e32 v11, v3
	v_lshl_add_u64 v[10:11], v[10:11], 1, s[6:7]
	global_store_short v[10:11], v12, off offset:768
	v_add_u32_e32 v10, 0x18020, v2
	v_mov_b32_e32 v11, v3
	v_lshl_add_u64 v[10:11], v[10:11], 1, s[6:7]
	global_store_short_d16_hi v[10:11], v12, off offset:768
	v_mul_f32_e32 v10, v15, v14
	v_mul_f32_e32 v9, v9, v14
	v_mul_f32_e32 v10, v4, v10
	v_mul_f32_e32 v9, v6, v9
	v_cvt_pk_bf16_f32 v9, v10, v9
	v_add_u32_e32 v10, 0x18040, v2
	v_mov_b32_e32 v11, v3
	v_lshl_add_u64 v[10:11], v[10:11], 1, s[6:7]
	global_store_short v[10:11], v9, off offset:768
	v_add_u32_e32 v10, 0x18060, v2
	v_mov_b32_e32 v11, v3
	v_lshl_add_u64 v[10:11], v[10:11], 1, s[6:7]
	global_store_short_d16_hi v[10:11], v9, off offset:768
	v_add_f32_e32 v22, v22, v23
	v_fmamk_f32 v22, v22, 0x3c000000, v254
	s_nop 0
	s_nop 0
	s_nop 0
	s_nop 1
	s_nop 1
	s_nop 0
	v_rsq_f32_e32 v26, v22
	s_nop 0
	v_mul_f32_e32 v23, v24, v26
	v_mul_f32_e32 v24, v25, v26
	v_mul_f32_e32 v23, v5, v23
	v_mul_f32_e32 v24, v7, v24
	v_add_u32_e32 v22, 0x19000, v2
	v_cvt_pk_bf16_f32 v24, v23, v24
	v_mov_b32_e32 v23, v3
	v_lshl_add_u64 v[22:23], v[22:23], 1, s[6:7]
	global_store_short v[22:23], v24, off offset:768
	v_add_u32_e32 v22, 0x19020, v2
	v_mov_b32_e32 v23, v3
	v_lshl_add_u64 v[22:23], v[22:23], 1, s[6:7]
	global_store_short_d16_hi v[22:23], v24, off offset:768
	v_mul_f32_e32 v22, v27, v26
	v_mul_f32_e32 v21, v21, v26
	v_mul_f32_e32 v22, v4, v22
	v_mul_f32_e32 v21, v6, v21
	v_cvt_pk_bf16_f32 v21, v22, v21
	v_add_u32_e32 v22, 0x19040, v2
	v_mov_b32_e32 v23, v3
	v_lshl_add_u64 v[22:23], v[22:23], 1, s[6:7]
	global_store_short v[22:23], v21, off offset:768
	v_add_u32_e32 v22, 0x19060, v2
	v_mov_b32_e32 v23, v3
	v_lshl_add_u64 v[22:23], v[22:23], 1, s[6:7]
	global_store_short_d16_hi v[22:23], v21, off offset:768
	ds_read_b32 v9, v8 offset:104
	ds_read2st64_b32 v[10:11], v1 offset0:14 offset1:30
	s_waitcnt lgkmcnt(0)
	v_fma_f32 v12, v82, v9, -v10
	v_fma_f32 v13, v114, v9, -v11
	ds_read2st64_b32 v[10:11], v1 offset0:46 offset1:62
	v_mul_f32_e32 v14, v13, v13
	v_fmac_f32_e32 v14, v12, v12
	s_waitcnt lgkmcnt(0)
	v_fma_f32 v15, v130, v9, -v10
	v_fmac_f32_e32 v14, v15, v15
	v_fma_f32 v9, v146, v9, -v11
	v_fmac_f32_e32 v14, v9, v9
	s_nop 1
	v_add_f32_dpp v10, v14, v14 quad_perm:[1,0,3,2] row_mask:0xf bank_mask:0xf
	s_nop 1
	v_add_f32_dpp v10, v10, v10 quad_perm:[2,3,0,1] row_mask:0xf bank_mask:0xf
	s_nop 1
	v_add_f32_dpp v10, v10, v10 row_half_mirror row_mask:0xf bank_mask:0xf
	s_nop 1
	v_add_f32_dpp v10, v10, v10 row_mirror row_mask:0xf bank_mask:0xf
	ds_swizzle_b32 v11, v10 offset:swizzle(SWAP,16)
	s_waitcnt lgkmcnt(0)
	v_add_f32_e32 v10, v10, v11
	v_fmamk_f32 v10, v10, 0x3c000000, v254
	v_cmp_gt_f32_e32 vcc, s90, v10
	v_mul_f32_e32 v11, 0x4f800000, v10
	s_nop 0
	v_cndmask_b32_e32 v10, v10, v11, vcc
	v_sqrt_f32_e32 v11, v10
	s_nop 0
	v_add_u32_e32 v14, -1, v11
	v_fma_f32 v16, -v14, v11, v10
	v_cmp_ge_f32_e64 s[4:5], 0, v16
	v_add_u32_e32 v16, 1, v11
	s_nop 0
	v_cndmask_b32_e64 v14, v11, v14, s[4:5]
	v_fma_f32 v11, -v16, v11, v10
	v_cmp_lt_f32_e64 s[4:5], 0, v11
	s_nop 1
	v_cndmask_b32_e64 v11, v14, v16, s[4:5]
	v_mul_f32_e32 v14, 0x37800000, v11
	v_cndmask_b32_e32 v11, v11, v14, vcc
	v_cmp_class_f32_e32 vcc, v10, v209
	s_nop 1
	v_cndmask_b32_e32 v10, v11, v10, vcc
	v_div_scale_f32 v11, s[4:5], v10, v10, 1.0
	v_rcp_f32_e32 v14, v11
	s_nop 0
	v_fma_f32 v16, -v11, v14, 1.0
	v_fmac_f32_e32 v14, v16, v14
	v_div_scale_f32 v16, vcc, 1.0, v10, 1.0
	v_mul_f32_e32 v17, v16, v14
	v_fma_f32 v18, -v11, v17, v16
	v_fmac_f32_e32 v17, v18, v14
	v_fma_f32 v11, -v11, v17, v16
	v_div_fmas_f32 v11, v11, v14, v17
	v_div_fixup_f32 v14, v11, v10, 1.0
	v_mul_f32_e32 v11, v12, v14
	v_mul_f32_e32 v12, v13, v14
	v_mul_f32_e32 v11, v5, v11
	v_mul_f32_e32 v12, v7, v12
	v_add_u32_e32 v10, 0x1a000, v2
	v_cvt_pk_bf16_f32 v12, v11, v12
	v_mov_b32_e32 v11, v3
	v_lshl_add_u64 v[10:11], v[10:11], 1, s[6:7]
	global_store_short v[10:11], v12, off offset:768
	v_add_u32_e32 v10, 0x1a020, v2
	v_mov_b32_e32 v11, v3
	v_lshl_add_u64 v[10:11], v[10:11], 1, s[6:7]
	global_store_short_d16_hi v[10:11], v12, off offset:768
	v_mul_f32_e32 v10, v15, v14
	v_mul_f32_e32 v9, v9, v14
	v_mul_f32_e32 v10, v4, v10
	v_mul_f32_e32 v9, v6, v9
	v_cvt_pk_bf16_f32 v9, v10, v9
	v_add_u32_e32 v10, 0x1a040, v2
	v_mov_b32_e32 v11, v3
	v_lshl_add_u64 v[10:11], v[10:11], 1, s[6:7]
	global_store_short v[10:11], v9, off offset:768
	v_add_u32_e32 v10, 0x1a060, v2
	v_mov_b32_e32 v11, v3
	v_lshl_add_u64 v[10:11], v[10:11], 1, s[6:7]
	global_store_short_d16_hi v[10:11], v9, off offset:768
	ds_read_b32 v10, v8 offset:108
	ds_read2st64_b32 v[8:9], v1 offset0:15 offset1:31
	s_waitcnt lgkmcnt(0)
	v_fma_f32 v11, v83, v10, -v8
	v_fma_f32 v12, v115, v10, -v9
	ds_read2st64_b32 v[8:9], v1 offset0:47 offset1:63
	v_mul_f32_e32 v13, v12, v12
	v_fmac_f32_e32 v13, v11, v11
	s_waitcnt lgkmcnt(0)
	v_fma_f32 v1, v131, v10, -v8
	v_fmac_f32_e32 v13, v1, v1
	v_fma_f32 v10, v147, v10, -v9
	v_fmac_f32_e32 v13, v10, v10
	s_nop 1
	v_add_f32_dpp v8, v13, v13 quad_perm:[1,0,3,2] row_mask:0xf bank_mask:0xf
	s_nop 1
	v_add_f32_dpp v8, v8, v8 quad_perm:[2,3,0,1] row_mask:0xf bank_mask:0xf
	s_nop 1
	v_add_f32_dpp v8, v8, v8 row_half_mirror row_mask:0xf bank_mask:0xf
	s_nop 1
	v_add_f32_dpp v8, v8, v8 row_mirror row_mask:0xf bank_mask:0xf
	ds_swizzle_b32 v9, v8 offset:swizzle(SWAP,16)
	s_waitcnt lgkmcnt(0)
	v_add_f32_e32 v8, v8, v9
	v_fmamk_f32 v8, v8, 0x3c000000, v254
	v_cmp_gt_f32_e32 vcc, s90, v8
	v_mul_f32_e32 v9, 0x4f800000, v8
	s_nop 0
	v_cndmask_b32_e32 v8, v8, v9, vcc
	v_sqrt_f32_e32 v9, v8
	s_nop 0
	v_add_u32_e32 v13, -1, v9
	v_fma_f32 v14, -v13, v9, v8
	v_cmp_ge_f32_e64 s[4:5], 0, v14
	v_add_u32_e32 v14, 1, v9
	s_nop 0
	v_cndmask_b32_e64 v13, v9, v13, s[4:5]
	v_fma_f32 v9, -v14, v9, v8
	v_cmp_lt_f32_e64 s[4:5], 0, v9
	s_nop 1
	v_cndmask_b32_e64 v9, v13, v14, s[4:5]
	v_mul_f32_e32 v13, 0x37800000, v9
	v_cndmask_b32_e32 v9, v9, v13, vcc
	v_cmp_class_f32_e32 vcc, v8, v209
	s_nop 1
	v_cndmask_b32_e32 v8, v9, v8, vcc
	v_div_scale_f32 v9, s[4:5], v8, v8, 1.0
	v_rcp_f32_e32 v13, v9
	s_nop 0
	v_fma_f32 v14, -v9, v13, 1.0
	v_fmac_f32_e32 v13, v14, v13
	v_div_scale_f32 v14, vcc, 1.0, v8, 1.0
	v_mul_f32_e32 v15, v14, v13
	v_fma_f32 v16, -v9, v15, v14
	v_fmac_f32_e32 v15, v16, v13
	v_fma_f32 v9, -v9, v15, v14
	v_div_fmas_f32 v9, v9, v13, v15
	v_div_fixup_f32 v13, v9, v8, 1.0
	v_mul_f32_e32 v9, v11, v13
	v_mul_f32_e32 v5, v5, v9
	v_mul_f32_e32 v9, v12, v13
	v_add_u32_e32 v8, 0x1b000, v2
	v_mul_f32_e32 v7, v7, v9
	v_mov_b32_e32 v9, v3
	v_lshl_add_u64 v[8:9], v[8:9], 1, s[6:7]
	v_mul_f32_e32 v1, v1, v13
	v_cvt_pk_bf16_f32 v5, v5, v7
	global_store_short v[8:9], v5, off offset:768
	v_add_u32_e32 v8, 0x1b020, v2
	v_mov_b32_e32 v9, v3
	v_mul_f32_e32 v1, v4, v1
	v_mul_f32_e32 v4, v10, v13
	v_lshl_add_u64 v[8:9], v[8:9], 1, s[6:7]
	v_mul_f32_e32 v4, v6, v4
	global_store_short_d16_hi v[8:9], v5, off offset:768
	v_cvt_pk_bf16_f32 v1, v1, v4
	v_add_u32_e32 v4, 0x1b040, v2
	v_mov_b32_e32 v5, v3
	v_lshl_add_u64 v[4:5], v[4:5], 1, s[6:7]
	global_store_short v[4:5], v1, off offset:768
	v_add_u32_e32 v4, 0x1b060, v2
	v_mov_b32_e32 v5, v3
	v_lshl_add_u64 v[4:5], v[4:5], 1, s[6:7]
	global_store_short_d16_hi v[4:5], v1, off offset:768
